# MLA loop tail trim: next-tile K fragment prefetch reads issued one slot earlier and the rescale compare moved into slot 18, so nothing but the wait and barrier follows the last MFMA
# speedup vs baseline: 1.0026x; 1.0005x over previous
; template <int VAR>
; __device__ __forceinline__ void attn_phase(LAS unsigned char* lds, const AttnP P, int vcu, int G, int wave_s) {
;     ...
;                 if (ND0 == 6) {
;                     KR1(0); KR1(1); KR1(2); KR1(3); SB();
;                     QK1(0, negm); EX2(pc0, 0, w0.x); KR1(4); SB();
;                     QK1(1, negm); EX2(pc0, 2, w0.y); KR1(5); SB();
;                     QK1(2, pn0); EX2(pc0, 4, w0.z); KR1(6); SB();
;                     QK1(3, pn1); EX2(pc0, 6, w0.w); KR1(7); SB();
;                     QK1(4, pn0); EX2(pc0, 8, w1.x); KR1(8); SB();
;                     QK1(5, pn1); EX2(pc0, 10, w1.y); KR1(9); SB();
;                     QK1(6, pn0); EX2(pc0, 12, w1.z); KR1(10); SB();
;                     QK1(7, pn1); EX2(pc0, 14, w1.w); KR1(11); SB();
;                     QK1(8, pn0); EX2(pc1, 0, w2.x); VR1(0); SB();
;                     QK1(9, pn1); EX2(pc1, 2, w2.y); VR1(1); SB();
;                     QK1(10, pn0); EX2(pc1, 4, w2.z); VR1(2); SB();
;                     QK1(11, pn1); EX2(pc1, 6, w2.w); VR1(3); SB();
;                 } else {
;                     KR1(0); KR1(1); KR1(2); KR1(3); SB();
;                     QK1(0, negm); EX2(pc0, 0, w0.x); EX2(pc0, 2, w0.y); KR1(4); SB();
;                     QK1(1, negm); EX2(pc0, 4, w0.z); EX2(pc0, 6, w0.w); KR1(5); SB();
;                     QK1(2, pn0); EX2(pc0, 8, w1.x); EX2(pc0, 10, w1.y); KR1(6); SB();
;                     QK1(3, pn1); EX2(pc0, 12, w1.z); EX2(pc0, 14, w1.w); KR1(7); SB();
;                     QK1(4, pn0); EX2(pc1, 0, w2.x); VR1(0); SB();
;                     QK1(5, pn1); EX2(pc1, 2, w2.y); VR1(1); SB();
;                     QK1(6, pn0); EX2(pc1, 4, w2.z); VR1(2); SB();
;                     QK1(7, pn1); EX2(pc1, 6, w2.w); VR1(3); SB();
;                 }
;                 PV1(0, w0); EX2(pc1, 8, w3.x); VR1(4); SB();
;                 PV1(1, w0); EX2(pc1, 10, w3.y); VR1(5); SB();
;                 PV1(2, w1); EX2(pc1, 12, w3.z); VR1(6); SB();
;                 PV1(3, w1); EX2(pc1, 14, w3.w); VR1(7); SB();
;                 lrun += sacc;
;                 PV1(4, w2); MASK_TILE(pn0, pn1, t + 1); SB();
;                 PV1(5, w2); SB();
;                 PV1(6, w3); SB();
;                 PV1(7, w3); rmn = rowmax32(pn0, pn1); if (!USE_NEGM) rmn -= mref; SB();
;     ...
;             if (hn) { STOREK(t & 1); STOREV((t + 1) & 1); }
.Lmla_p0_go:
	v_exp_f32_e32 v222, v34
	v_exp_f32_e32 v223, v35
	v_add_f32_e32 v164, 0, v222
	v_cvt_pk_bf16_f32 v206, v222, v223
	v_add_f32_e32 v164, v223, v164
	v_exp_f32_e32 v224, v36
	v_exp_f32_e32 v225, v37
	v_add_f32_e32 v164, v224, v164
	v_cvt_pk_bf16_f32 v207, v224, v225
	v_add_f32_e32 v164, v225, v164
	s_waitcnt lgkmcnt(3)
	v_mfma_f32_32x32x16_bf16 v[82:97], v[182:185], v[114:117], v[66:81]
	ds_read_b128 v[198:201], v174 offset:22592
	v_exp_f32_e32 v222, v38
	v_exp_f32_e32 v223, v39
	v_add_f32_e32 v164, v222, v164
	v_cvt_pk_bf16_f32 v208, v222, v223
	v_add_f32_e32 v164, v223, v164
	s_waitcnt lgkmcnt(3)
	v_mfma_f32_32x32x16_bf16 v[98:113], v[186:189], v[114:117], v[66:81]
	ds_read_b128 v[182:185], v174 offset:29248
	v_exp_f32_e32 v224, v40
	v_exp_f32_e32 v225, v41
	v_add_f32_e32 v164, v224, v164
	v_cvt_pk_bf16_f32 v209, v224, v225
	v_add_f32_e32 v164, v225, v164
	s_waitcnt lgkmcnt(3)
	v_mfma_f32_32x32x16_bf16 v[82:97], v[190:193], v[118:121], v[82:97]
	ds_read_b128 v[186:189], v174 offset:22624
	v_exp_f32_e32 v222, v42
	v_exp_f32_e32 v223, v43
	v_add_f32_e32 v164, v222, v164
	v_cvt_pk_bf16_f32 v210, v222, v223
	v_add_f32_e32 v164, v223, v164
	s_waitcnt lgkmcnt(3)
	v_mfma_f32_32x32x16_bf16 v[98:113], v[194:197], v[118:121], v[98:113]
	ds_read_b128 v[190:193], v174 offset:29280
	v_exp_f32_e32 v224, v44
	v_exp_f32_e32 v225, v45
	v_add_f32_e32 v164, v224, v164
	v_cvt_pk_bf16_f32 v211, v224, v225
	v_add_f32_e32 v164, v225, v164
	s_waitcnt lgkmcnt(3)
	v_mfma_f32_32x32x16_bf16 v[82:97], v[198:201], v[122:125], v[82:97]
	ds_read_b128 v[194:197], v174 offset:22656
	v_exp_f32_e32 v222, v46
	v_exp_f32_e32 v223, v47
	v_add_f32_e32 v164, v222, v164
	v_cvt_pk_bf16_f32 v212, v222, v223
	v_add_f32_e32 v164, v223, v164
	s_waitcnt lgkmcnt(3)
	v_mfma_f32_32x32x16_bf16 v[98:113], v[182:185], v[122:125], v[98:113]
	ds_read_b128 v[198:201], v174 offset:29312
	v_exp_f32_e32 v224, v48
	v_exp_f32_e32 v225, v49
	v_add_f32_e32 v164, v224, v164
	v_cvt_pk_bf16_f32 v213, v224, v225
	v_add_f32_e32 v164, v225, v164
	s_waitcnt lgkmcnt(3)
	v_mfma_f32_32x32x16_bf16 v[82:97], v[186:189], v[126:129], v[82:97]
	ds_read_b128 v[182:185], v174 offset:22688
	v_exp_f32_e32 v222, v50
	v_exp_f32_e32 v223, v51
	v_add_f32_e32 v164, v222, v164
	v_cvt_pk_bf16_f32 v214, v222, v223
	v_add_f32_e32 v164, v223, v164
	s_waitcnt lgkmcnt(3)
	v_mfma_f32_32x32x16_bf16 v[98:113], v[190:193], v[126:129], v[98:113]
	ds_read_b128 v[186:189], v174 offset:29344
	v_exp_f32_e32 v224, v52
	v_exp_f32_e32 v225, v53
	v_add_f32_e32 v164, v224, v164
	v_cvt_pk_bf16_f32 v215, v224, v225
	v_add_f32_e32 v164, v225, v164
	s_waitcnt lgkmcnt(3)
	v_mfma_f32_32x32x16_bf16 v[82:97], v[194:197], v[130:133], v[82:97]
	ds_read_b128 v[190:193], v228 offset:13312
	v_exp_f32_e32 v222, v54
	v_exp_f32_e32 v223, v55
	v_add_f32_e32 v164, v222, v164
	v_cvt_pk_bf16_f32 v216, v222, v223
	v_add_f32_e32 v164, v223, v164
	s_waitcnt lgkmcnt(3)
	v_mfma_f32_32x32x16_bf16 v[98:113], v[198:201], v[130:133], v[98:113]
	ds_read_b128 v[194:197], v228 offset:17920
	v_exp_f32_e32 v224, v56
	v_exp_f32_e32 v225, v57
	v_add_f32_e32 v164, v224, v164
	v_cvt_pk_bf16_f32 v217, v224, v225
	v_add_f32_e32 v164, v225, v164
	s_waitcnt lgkmcnt(3)
	v_mfma_f32_32x32x16_bf16 v[82:97], v[182:185], v[134:137], v[82:97]
	ds_read_b128 v[198:201], v228 offset:13344
	v_exp_f32_e32 v222, v58
	v_exp_f32_e32 v223, v59
	v_add_f32_e32 v164, v222, v164
	v_cvt_pk_bf16_f32 v218, v222, v223
	v_add_f32_e32 v164, v223, v164
	s_waitcnt lgkmcnt(3)
	v_mfma_f32_32x32x16_bf16 v[98:113], v[186:189], v[134:137], v[98:113]
	ds_read_b128 v[182:185], v228 offset:17952
	v_exp_f32_e32 v224, v60
	v_exp_f32_e32 v225, v61
	v_add_f32_e32 v164, v224, v164
	v_cvt_pk_bf16_f32 v219, v224, v225
	v_add_f32_e32 v164, v225, v164
	s_waitcnt lgkmcnt(3)
	v_mfma_f32_32x32x16_bf16 v[2:17], v[190:193], v[206:209], v[2:17]
	ds_read_b128 v[186:189], v228 offset:13376
	v_exp_f32_e32 v222, v62
	v_exp_f32_e32 v223, v63
	v_add_f32_e32 v164, v222, v164
	v_cvt_pk_bf16_f32 v220, v222, v223
	v_add_f32_e32 v164, v223, v164
	s_waitcnt lgkmcnt(3)
	v_mfma_f32_32x32x16_bf16 v[18:33], v[194:197], v[206:209], v[18:33]
	ds_read_b128 v[190:193], v228 offset:17984
	v_exp_f32_e32 v224, v64
	v_exp_f32_e32 v225, v65
	v_add_f32_e32 v164, v224, v164
	v_cvt_pk_bf16_f32 v221, v224, v225
	v_add_f32_e32 v164, v225, v164
	s_mov_b32 s13, s20
	s_mov_b32 s20, s19
	s_add_i32 s19, s19, 1
	s_cmp_eq_u32 s19, s9
	s_cselect_b32 s19, 0, s19
	s_waitcnt lgkmcnt(3)
	v_mfma_f32_32x32x16_bf16 v[2:17], v[198:201], v[210:213], v[2:17]
	ds_read_b128 v[194:197], v228 offset:13408
	v_max3_f32 v224, v82, v83, v84
	v_max3_f32 v225, v98, v99, v100
	v_max3_f32 v224, v224, v85, v86
	v_max3_f32 v225, v225, v101, v102
	s_waitcnt vmcnt(2)
	v_add_u32_e32 v222, 0xb000, v172
	ds_write_b128 v222, v[146:149] offset:26624
	v_lshl_add_u32 v222, s19, 17, v178
	global_load_dwordx4 v[146:149], v222, s[52:53]
	s_waitcnt lgkmcnt(4)
	v_mfma_f32_32x32x16_bf16 v[18:33], v[182:185], v[210:213], v[18:33]
	ds_read_b128 v[198:201], v228 offset:18016
	ds_read_b128 v[182:185], v174 offset:45056
	v_max3_f32 v224, v224, v87, v88
	v_max3_f32 v225, v225, v103, v104
	v_max3_f32 v224, v224, v89, v90
	v_max3_f32 v225, v225, v105, v106
	s_and_b64 vcc, exec, s[2:3]
	s_cbranch_vccz .Lmla_p0_nope
	v_add_u32_e32 v222, 0xb000, v176
	ds_write_b128 v222, v[138:141] offset:26752
	v_lshl_add_u32 v222, s19, 12, v179
	global_load_dwordx4 v[138:141], v222, s[62:63]
.Lmla_p0_nope:
	s_waitcnt lgkmcnt(5)
	v_mfma_f32_32x32x16_bf16 v[2:17], v[186:189], v[214:217], v[2:17]
	ds_read_b128 v[186:189], v174 offset:51712
	v_max3_f32 v224, v224, v91, v92
	v_max3_f32 v225, v225, v107, v108
	v_max3_f32 v224, v224, v93, v94
	v_max3_f32 v225, v225, v109, v110
	v_add_u32_e32 v222, 0xb000, v173
	ds_write_b128 v222, v[142:145] offset:39936
	v_lshl_add_u32 v222, s13, 7, v168
	global_load_dwordx4 v[142:145], v222, s[56:57]
	s_waitcnt lgkmcnt(6)
	v_mfma_f32_32x32x16_bf16 v[18:33], v[190:193], v[214:217], v[18:33]
	ds_read_b128 v[190:193], v174 offset:45088
	v_max3_f32 v224, v224, v95, v96
	v_max3_f32 v225, v225, v111, v112
	v_max3_f32 v224, v224, v97, v113
	v_max_f32_e32 v224, v224, v225
	s_waitcnt lgkmcnt(6)
	v_mfma_f32_32x32x16_bf16 v[2:17], v[194:197], v[218:221], v[2:17]
	ds_read_b128 v[194:197], v174 offset:51744
	v_mov_b32_e32 v225, v224
	v_add_f32_e32 v1, v1, v164
	s_add_i32 s11, s11, 1
	v_permlane32_swap_b32_e32 v224, v225
	s_cmp_eq_u32 s9, s11
	v_max_f32_e32 v167, v224, v225
	v_cmp_lt_f32_e32 vcc, s66, v167
	s_waitcnt lgkmcnt(5)
	v_mfma_f32_32x32x16_bf16 v[18:33], v[198:201], v[218:221], v[18:33]
	s_cbranch_scc1 .Lmla_exit_p0

; template <int VAR>
; __device__ __forceinline__ void attn_phase(LAS unsigned char* lds, const AttnP P, int vcu, int G, int wave_s) {
;     ...
;                 if (ND0 == 6) {
;                     KR1(0); KR1(1); KR1(2); KR1(3); SB();
;                     QK1(0, negm); EX2(pc0, 0, w0.x); KR1(4); SB();
;                     QK1(1, negm); EX2(pc0, 2, w0.y); KR1(5); SB();
;                     QK1(2, pn0); EX2(pc0, 4, w0.z); KR1(6); SB();
;                     QK1(3, pn1); EX2(pc0, 6, w0.w); KR1(7); SB();
;                     QK1(4, pn0); EX2(pc0, 8, w1.x); KR1(8); SB();
;                     QK1(5, pn1); EX2(pc0, 10, w1.y); KR1(9); SB();
;                     QK1(6, pn0); EX2(pc0, 12, w1.z); KR1(10); SB();
;                     QK1(7, pn1); EX2(pc0, 14, w1.w); KR1(11); SB();
;                     QK1(8, pn0); EX2(pc1, 0, w2.x); VR1(0); SB();
;                     QK1(9, pn1); EX2(pc1, 2, w2.y); VR1(1); SB();
;                     QK1(10, pn0); EX2(pc1, 4, w2.z); VR1(2); SB();
;                     QK1(11, pn1); EX2(pc1, 6, w2.w); VR1(3); SB();
;                 } else {
;                     KR1(0); KR1(1); KR1(2); KR1(3); SB();
;                     QK1(0, negm); EX2(pc0, 0, w0.x); EX2(pc0, 2, w0.y); KR1(4); SB();
;                     QK1(1, negm); EX2(pc0, 4, w0.z); EX2(pc0, 6, w0.w); KR1(5); SB();
;                     QK1(2, pn0); EX2(pc0, 8, w1.x); EX2(pc0, 10, w1.y); KR1(6); SB();
;                     QK1(3, pn1); EX2(pc0, 12, w1.z); EX2(pc0, 14, w1.w); KR1(7); SB();
;                     QK1(4, pn0); EX2(pc1, 0, w2.x); VR1(0); SB();
;                     QK1(5, pn1); EX2(pc1, 2, w2.y); VR1(1); SB();
;                     QK1(6, pn0); EX2(pc1, 4, w2.z); VR1(2); SB();
;                     QK1(7, pn1); EX2(pc1, 6, w2.w); VR1(3); SB();
;                 }
;                 PV1(0, w0); EX2(pc1, 8, w3.x); VR1(4); SB();
;                 PV1(1, w0); EX2(pc1, 10, w3.y); VR1(5); SB();
;                 PV1(2, w1); EX2(pc1, 12, w3.z); VR1(6); SB();
;                 PV1(3, w1); EX2(pc1, 14, w3.w); VR1(7); SB();
;                 lrun += sacc;
;                 PV1(4, w2); MASK_TILE(pn0, pn1, t + 1); SB();
;                 PV1(5, w2); SB();
;                 PV1(6, w3); SB();
;                 PV1(7, w3); rmn = rowmax32(pn0, pn1); if (!USE_NEGM) rmn -= mref; SB();
;     ...
;             if (hn) { STOREK(t & 1); STOREV((t + 1) & 1); }
.Lmla_p1_go:
	v_exp_f32_e32 v222, v82
	v_exp_f32_e32 v223, v83
	v_add_f32_e32 v164, 0, v222
	v_cvt_pk_bf16_f32 v206, v222, v223
	v_add_f32_e32 v164, v223, v164
	v_exp_f32_e32 v224, v84
	v_exp_f32_e32 v225, v85
	v_add_f32_e32 v164, v224, v164
	v_cvt_pk_bf16_f32 v207, v224, v225
	v_add_f32_e32 v164, v225, v164
	s_waitcnt lgkmcnt(4)
	v_mfma_f32_32x32x16_bf16 v[34:49], v[182:185], v[114:117], v[66:81]
	ds_read_b128 v[198:201], v174 offset:45120
	v_exp_f32_e32 v222, v86
	v_exp_f32_e32 v223, v87
	v_add_f32_e32 v164, v222, v164
	v_cvt_pk_bf16_f32 v208, v222, v223
	v_add_f32_e32 v164, v223, v164
	s_waitcnt lgkmcnt(4)
	v_mfma_f32_32x32x16_bf16 v[50:65], v[186:189], v[114:117], v[66:81]
	ds_read_b128 v[182:185], v174 offset:51776
	v_exp_f32_e32 v224, v88
	v_exp_f32_e32 v225, v89
	v_add_f32_e32 v164, v224, v164
	v_cvt_pk_bf16_f32 v209, v224, v225
	v_add_f32_e32 v164, v225, v164
	s_waitcnt lgkmcnt(3)
	v_mfma_f32_32x32x16_bf16 v[34:49], v[190:193], v[118:121], v[34:49]
	ds_read_b128 v[186:189], v174 offset:45152
	v_exp_f32_e32 v222, v90
	v_exp_f32_e32 v223, v91
	v_add_f32_e32 v164, v222, v164
	v_cvt_pk_bf16_f32 v210, v222, v223
	v_add_f32_e32 v164, v223, v164
	s_waitcnt lgkmcnt(3)
	v_mfma_f32_32x32x16_bf16 v[50:65], v[194:197], v[118:121], v[50:65]
	ds_read_b128 v[190:193], v174 offset:51808
	v_exp_f32_e32 v224, v92
	v_exp_f32_e32 v225, v93
	v_add_f32_e32 v164, v224, v164
	v_cvt_pk_bf16_f32 v211, v224, v225
	v_add_f32_e32 v164, v225, v164
	s_waitcnt lgkmcnt(3)
	v_mfma_f32_32x32x16_bf16 v[34:49], v[198:201], v[122:125], v[34:49]
	ds_read_b128 v[194:197], v174 offset:45184
	v_exp_f32_e32 v222, v94
	v_exp_f32_e32 v223, v95
	v_add_f32_e32 v164, v222, v164
	v_cvt_pk_bf16_f32 v212, v222, v223
	v_add_f32_e32 v164, v223, v164
	s_waitcnt lgkmcnt(3)
	v_mfma_f32_32x32x16_bf16 v[50:65], v[182:185], v[122:125], v[50:65]
	ds_read_b128 v[198:201], v174 offset:51840
	v_exp_f32_e32 v224, v96
	v_exp_f32_e32 v225, v97
	v_add_f32_e32 v164, v224, v164
	v_cvt_pk_bf16_f32 v213, v224, v225
	v_add_f32_e32 v164, v225, v164
	s_waitcnt lgkmcnt(3)
	v_mfma_f32_32x32x16_bf16 v[34:49], v[186:189], v[126:129], v[34:49]
	ds_read_b128 v[182:185], v174 offset:45216
	v_exp_f32_e32 v222, v98
	v_exp_f32_e32 v223, v99
	v_add_f32_e32 v164, v222, v164
	v_cvt_pk_bf16_f32 v214, v222, v223
	v_add_f32_e32 v164, v223, v164
	s_waitcnt lgkmcnt(3)
	v_mfma_f32_32x32x16_bf16 v[50:65], v[190:193], v[126:129], v[50:65]
	ds_read_b128 v[186:189], v174 offset:51872
	v_exp_f32_e32 v224, v100
	v_exp_f32_e32 v225, v101
	v_add_f32_e32 v164, v224, v164
	v_cvt_pk_bf16_f32 v215, v224, v225
	v_add_f32_e32 v164, v225, v164
	s_waitcnt lgkmcnt(3)
	v_mfma_f32_32x32x16_bf16 v[34:49], v[194:197], v[130:133], v[34:49]
	ds_read_b128 v[190:193], v228 offset:35840
	v_exp_f32_e32 v222, v102
	v_exp_f32_e32 v223, v103
	v_add_f32_e32 v164, v222, v164
	v_cvt_pk_bf16_f32 v216, v222, v223
	v_add_f32_e32 v164, v223, v164
	s_waitcnt lgkmcnt(3)
	v_mfma_f32_32x32x16_bf16 v[50:65], v[198:201], v[130:133], v[50:65]
	ds_read_b128 v[194:197], v228 offset:40448
	v_exp_f32_e32 v224, v104
	v_exp_f32_e32 v225, v105
	v_add_f32_e32 v164, v224, v164
	v_cvt_pk_bf16_f32 v217, v224, v225
	v_add_f32_e32 v164, v225, v164
	s_waitcnt lgkmcnt(3)
	v_mfma_f32_32x32x16_bf16 v[34:49], v[182:185], v[134:137], v[34:49]
	ds_read_b128 v[198:201], v228 offset:35872
	v_exp_f32_e32 v222, v106
	v_exp_f32_e32 v223, v107
	v_add_f32_e32 v164, v222, v164
	v_cvt_pk_bf16_f32 v218, v222, v223
	v_add_f32_e32 v164, v223, v164
	s_waitcnt lgkmcnt(3)
	v_mfma_f32_32x32x16_bf16 v[50:65], v[186:189], v[134:137], v[50:65]
	ds_read_b128 v[182:185], v228 offset:40480
	v_exp_f32_e32 v224, v108
	v_exp_f32_e32 v225, v109
	v_add_f32_e32 v164, v224, v164
	v_cvt_pk_bf16_f32 v219, v224, v225
	v_add_f32_e32 v164, v225, v164
	s_waitcnt lgkmcnt(3)
	v_mfma_f32_32x32x16_bf16 v[2:17], v[190:193], v[206:209], v[2:17]
	ds_read_b128 v[186:189], v228 offset:35904
	v_exp_f32_e32 v222, v110
	v_exp_f32_e32 v223, v111
	v_add_f32_e32 v164, v222, v164
	v_cvt_pk_bf16_f32 v220, v222, v223
	v_add_f32_e32 v164, v223, v164
	s_waitcnt lgkmcnt(3)
	v_mfma_f32_32x32x16_bf16 v[18:33], v[194:197], v[206:209], v[18:33]
	ds_read_b128 v[190:193], v228 offset:40512
	v_exp_f32_e32 v224, v112
	v_exp_f32_e32 v225, v113
	v_add_f32_e32 v164, v224, v164
	v_cvt_pk_bf16_f32 v221, v224, v225
	v_add_f32_e32 v164, v225, v164
	s_mov_b32 s13, s20
	s_mov_b32 s20, s19
	s_add_i32 s19, s19, 1
	s_cmp_eq_u32 s19, s9
	s_cselect_b32 s19, 0, s19
	s_waitcnt lgkmcnt(3)
	v_mfma_f32_32x32x16_bf16 v[2:17], v[198:201], v[210:213], v[2:17]
	ds_read_b128 v[194:197], v228 offset:35936
	v_max3_f32 v224, v34, v35, v36
	v_max3_f32 v225, v50, v51, v52
	v_max3_f32 v224, v224, v37, v38
	v_max3_f32 v225, v225, v53, v54
	s_waitcnt vmcnt(2)
	ds_write_b128 v172, v[150:153]
	v_lshl_add_u32 v222, s19, 17, v178
	global_load_dwordx4 v[150:153], v222, s[52:53]
	s_waitcnt lgkmcnt(4)
	v_mfma_f32_32x32x16_bf16 v[18:33], v[182:185], v[210:213], v[18:33]
	ds_read_b128 v[198:201], v228 offset:40544
	ds_read_b128 v[182:185], v229 offset:13312
	v_max3_f32 v224, v224, v39, v40
	v_max3_f32 v225, v225, v55, v56
	v_max3_f32 v224, v224, v41, v42
	v_max3_f32 v225, v225, v57, v58
	s_and_b64 vcc, exec, s[2:3]
	s_cbranch_vccz .Lmla_p1_nope
	ds_write_b128 v176, v[160:163] offset:128
	v_lshl_add_u32 v222, s19, 12, v179
	global_load_dwordx4 v[160:163], v222, s[62:63]
.Lmla_p1_nope:
	s_waitcnt lgkmcnt(5)
	v_mfma_f32_32x32x16_bf16 v[2:17], v[186:189], v[214:217], v[2:17]
	ds_read_b128 v[186:189], v229 offset:19968
	v_max3_f32 v224, v224, v43, v44
	v_max3_f32 v225, v225, v59, v60
	v_max3_f32 v224, v224, v45, v46
	v_max3_f32 v225, v225, v61, v62
	v_add_u32_e32 v222, 0xb000, v173
	ds_write_b128 v222, v[202:205] offset:49152
	v_lshl_add_u32 v222, s13, 7, v168
	global_load_dwordx4 v[202:205], v222, s[56:57]
	s_waitcnt lgkmcnt(6)
	v_mfma_f32_32x32x16_bf16 v[18:33], v[190:193], v[214:217], v[18:33]
	ds_read_b128 v[190:193], v229 offset:13344
	v_max3_f32 v224, v224, v47, v48
	v_max3_f32 v225, v225, v63, v64
	v_max3_f32 v224, v224, v49, v65
	v_max_f32_e32 v224, v224, v225
	s_waitcnt lgkmcnt(6)
	v_mfma_f32_32x32x16_bf16 v[2:17], v[194:197], v[218:221], v[2:17]
	ds_read_b128 v[194:197], v229 offset:20000
	v_mov_b32_e32 v225, v224
	v_add_f32_e32 v1, v1, v164
	s_add_i32 s11, s11, 1
	v_permlane32_swap_b32_e32 v224, v225
	s_cmp_eq_u32 s9, s11
	v_max_f32_e32 v167, v224, v225
	v_cmp_lt_f32_e32 vcc, s66, v167
	s_waitcnt lgkmcnt(5)
	v_mfma_f32_32x32x16_bf16 v[18:33], v[198:201], v[218:221], v[18:33]
	s_waitcnt lgkmcnt(2)
	s_barrier
	s_cbranch_scc1 .Lmla_exit_p1

; template <int VAR>
; __device__ __forceinline__ void attn_phase(LAS unsigned char* lds, const AttnP P, int vcu, int G, int wave_s) {
;     ...
;                 if (ND0 == 6) {
;                     KR1(0); KR1(1); KR1(2); KR1(3); SB();
;                     QK1(0, negm); EX2(pc0, 0, w0.x); KR1(4); SB();
;                     QK1(1, negm); EX2(pc0, 2, w0.y); KR1(5); SB();
;                     QK1(2, pn0); EX2(pc0, 4, w0.z); KR1(6); SB();
;                     QK1(3, pn1); EX2(pc0, 6, w0.w); KR1(7); SB();
;                     QK1(4, pn0); EX2(pc0, 8, w1.x); KR1(8); SB();
;                     QK1(5, pn1); EX2(pc0, 10, w1.y); KR1(9); SB();
;                     QK1(6, pn0); EX2(pc0, 12, w1.z); KR1(10); SB();
;                     QK1(7, pn1); EX2(pc0, 14, w1.w); KR1(11); SB();
;                     QK1(8, pn0); EX2(pc1, 0, w2.x); VR1(0); SB();
;                     QK1(9, pn1); EX2(pc1, 2, w2.y); VR1(1); SB();
;                     QK1(10, pn0); EX2(pc1, 4, w2.z); VR1(2); SB();
;                     QK1(11, pn1); EX2(pc1, 6, w2.w); VR1(3); SB();
;                 } else {
;                     KR1(0); KR1(1); KR1(2); KR1(3); SB();
;                     QK1(0, negm); EX2(pc0, 0, w0.x); EX2(pc0, 2, w0.y); KR1(4); SB();
;                     QK1(1, negm); EX2(pc0, 4, w0.z); EX2(pc0, 6, w0.w); KR1(5); SB();
;                     QK1(2, pn0); EX2(pc0, 8, w1.x); EX2(pc0, 10, w1.y); KR1(6); SB();
;                     QK1(3, pn1); EX2(pc0, 12, w1.z); EX2(pc0, 14, w1.w); KR1(7); SB();
;                     QK1(4, pn0); EX2(pc1, 0, w2.x); VR1(0); SB();
;                     QK1(5, pn1); EX2(pc1, 2, w2.y); VR1(1); SB();
;                     QK1(6, pn0); EX2(pc1, 4, w2.z); VR1(2); SB();
;                     QK1(7, pn1); EX2(pc1, 6, w2.w); VR1(3); SB();
;                 }
;                 PV1(0, w0); EX2(pc1, 8, w3.x); VR1(4); SB();
;                 PV1(1, w0); EX2(pc1, 10, w3.y); VR1(5); SB();
;                 PV1(2, w1); EX2(pc1, 12, w3.z); VR1(6); SB();
;                 PV1(3, w1); EX2(pc1, 14, w3.w); VR1(7); SB();
;                 lrun += sacc;
;                 PV1(4, w2); MASK_TILE(pn0, pn1, t + 1); SB();
;                 PV1(5, w2); SB();
;                 PV1(6, w3); SB();
;                 PV1(7, w3); rmn = rowmax32(pn0, pn1); if (!USE_NEGM) rmn -= mref; SB();
;     ...
;             if (hn) { STOREK(t & 1); STOREV((t + 1) & 1); }
.Lmla_p2_go:
	v_exp_f32_e32 v222, v34
	v_exp_f32_e32 v223, v35
	v_add_f32_e32 v164, 0, v222
	v_cvt_pk_bf16_f32 v206, v222, v223
	v_add_f32_e32 v164, v223, v164
	v_exp_f32_e32 v224, v36
	v_exp_f32_e32 v225, v37
	v_add_f32_e32 v164, v224, v164
	v_cvt_pk_bf16_f32 v207, v224, v225
	v_add_f32_e32 v164, v225, v164
	s_waitcnt lgkmcnt(3)
	v_mfma_f32_32x32x16_bf16 v[82:97], v[182:185], v[114:117], v[66:81]
	ds_read_b128 v[198:201], v229 offset:13376
	v_exp_f32_e32 v222, v38
	v_exp_f32_e32 v223, v39
	v_add_f32_e32 v164, v222, v164
	v_cvt_pk_bf16_f32 v208, v222, v223
	v_add_f32_e32 v164, v223, v164
	s_waitcnt lgkmcnt(3)
	v_mfma_f32_32x32x16_bf16 v[98:113], v[186:189], v[114:117], v[66:81]
	ds_read_b128 v[182:185], v229 offset:20032
	v_exp_f32_e32 v224, v40
	v_exp_f32_e32 v225, v41
	v_add_f32_e32 v164, v224, v164
	v_cvt_pk_bf16_f32 v209, v224, v225
	v_add_f32_e32 v164, v225, v164
	s_waitcnt lgkmcnt(3)
	v_mfma_f32_32x32x16_bf16 v[82:97], v[190:193], v[118:121], v[82:97]
	ds_read_b128 v[186:189], v229 offset:13408
	v_exp_f32_e32 v222, v42
	v_exp_f32_e32 v223, v43
	v_add_f32_e32 v164, v222, v164
	v_cvt_pk_bf16_f32 v210, v222, v223
	v_add_f32_e32 v164, v223, v164
	s_waitcnt lgkmcnt(3)
	v_mfma_f32_32x32x16_bf16 v[98:113], v[194:197], v[118:121], v[98:113]
	ds_read_b128 v[190:193], v229 offset:20064
	v_exp_f32_e32 v224, v44
	v_exp_f32_e32 v225, v45
	v_add_f32_e32 v164, v224, v164
	v_cvt_pk_bf16_f32 v211, v224, v225
	v_add_f32_e32 v164, v225, v164
	s_waitcnt lgkmcnt(3)
	v_mfma_f32_32x32x16_bf16 v[82:97], v[198:201], v[122:125], v[82:97]
	ds_read_b128 v[194:197], v229 offset:13440
	v_exp_f32_e32 v222, v46
	v_exp_f32_e32 v223, v47
	v_add_f32_e32 v164, v222, v164
	v_cvt_pk_bf16_f32 v212, v222, v223
	v_add_f32_e32 v164, v223, v164
	s_waitcnt lgkmcnt(3)
	v_mfma_f32_32x32x16_bf16 v[98:113], v[182:185], v[122:125], v[98:113]
	ds_read_b128 v[198:201], v229 offset:20096
	v_exp_f32_e32 v224, v48
	v_exp_f32_e32 v225, v49
	v_add_f32_e32 v164, v224, v164
	v_cvt_pk_bf16_f32 v213, v224, v225
	v_add_f32_e32 v164, v225, v164
	s_waitcnt lgkmcnt(3)
	v_mfma_f32_32x32x16_bf16 v[82:97], v[186:189], v[126:129], v[82:97]
	ds_read_b128 v[182:185], v229 offset:13472
	v_exp_f32_e32 v222, v50
	v_exp_f32_e32 v223, v51
	v_add_f32_e32 v164, v222, v164
	v_cvt_pk_bf16_f32 v214, v222, v223
	v_add_f32_e32 v164, v223, v164
	s_waitcnt lgkmcnt(3)
	v_mfma_f32_32x32x16_bf16 v[98:113], v[190:193], v[126:129], v[98:113]
	ds_read_b128 v[186:189], v229 offset:20128
	v_exp_f32_e32 v224, v52
	v_exp_f32_e32 v225, v53
	v_add_f32_e32 v164, v224, v164
	v_cvt_pk_bf16_f32 v215, v224, v225
	v_add_f32_e32 v164, v225, v164
	s_waitcnt lgkmcnt(3)
	v_mfma_f32_32x32x16_bf16 v[82:97], v[194:197], v[130:133], v[82:97]
	ds_read_b128 v[190:193], v181 offset:39936
	v_exp_f32_e32 v222, v54
	v_exp_f32_e32 v223, v55
	v_add_f32_e32 v164, v222, v164
	v_cvt_pk_bf16_f32 v216, v222, v223
	v_add_f32_e32 v164, v223, v164
	s_waitcnt lgkmcnt(3)
	v_mfma_f32_32x32x16_bf16 v[98:113], v[198:201], v[130:133], v[98:113]
	ds_read_b128 v[194:197], v181 offset:44544
	v_exp_f32_e32 v224, v56
	v_exp_f32_e32 v225, v57
	v_add_f32_e32 v164, v224, v164
	v_cvt_pk_bf16_f32 v217, v224, v225
	v_add_f32_e32 v164, v225, v164
	s_waitcnt lgkmcnt(3)
	v_mfma_f32_32x32x16_bf16 v[82:97], v[182:185], v[134:137], v[82:97]
	ds_read_b128 v[198:201], v181 offset:39968
	v_exp_f32_e32 v222, v58
	v_exp_f32_e32 v223, v59
	v_add_f32_e32 v164, v222, v164
	v_cvt_pk_bf16_f32 v218, v222, v223
	v_add_f32_e32 v164, v223, v164
	s_waitcnt lgkmcnt(3)
	v_mfma_f32_32x32x16_bf16 v[98:113], v[186:189], v[134:137], v[98:113]
	ds_read_b128 v[182:185], v181 offset:44576
	v_exp_f32_e32 v224, v60
	v_exp_f32_e32 v225, v61
	v_add_f32_e32 v164, v224, v164
	v_cvt_pk_bf16_f32 v219, v224, v225
	v_add_f32_e32 v164, v225, v164
	s_waitcnt lgkmcnt(3)
	v_mfma_f32_32x32x16_bf16 v[2:17], v[190:193], v[206:209], v[2:17]
	ds_read_b128 v[186:189], v181 offset:40000
	v_exp_f32_e32 v222, v62
	v_exp_f32_e32 v223, v63
	v_add_f32_e32 v164, v222, v164
	v_cvt_pk_bf16_f32 v220, v222, v223
	v_add_f32_e32 v164, v223, v164
	s_waitcnt lgkmcnt(3)
	v_mfma_f32_32x32x16_bf16 v[18:33], v[194:197], v[206:209], v[18:33]
	ds_read_b128 v[190:193], v181 offset:44608
	v_exp_f32_e32 v224, v64
	v_exp_f32_e32 v225, v65
	v_add_f32_e32 v164, v224, v164
	v_cvt_pk_bf16_f32 v221, v224, v225
	v_add_f32_e32 v164, v225, v164
	s_mov_b32 s13, s20
	s_mov_b32 s20, s19
	s_add_i32 s19, s19, 1
	s_cmp_eq_u32 s19, s9
	s_cselect_b32 s19, 0, s19
	s_waitcnt lgkmcnt(3)
	v_mfma_f32_32x32x16_bf16 v[2:17], v[198:201], v[210:213], v[2:17]
	ds_read_b128 v[194:197], v181 offset:40032
	v_max3_f32 v224, v82, v83, v84
	v_max3_f32 v225, v98, v99, v100
	v_max3_f32 v224, v224, v85, v86
	v_max3_f32 v225, v225, v101, v102
	s_waitcnt vmcnt(2)
	ds_write_b128 v172, v[146:149] offset:22528
	v_lshl_add_u32 v222, s19, 17, v178
	global_load_dwordx4 v[146:149], v222, s[52:53]
	s_waitcnt lgkmcnt(4)
	v_mfma_f32_32x32x16_bf16 v[18:33], v[182:185], v[210:213], v[18:33]
	ds_read_b128 v[198:201], v181 offset:44640
	ds_read_b128 v[182:185], v229 offset:26624
	v_max3_f32 v224, v224, v87, v88
	v_max3_f32 v225, v225, v103, v104
	v_max3_f32 v224, v224, v89, v90
	v_max3_f32 v225, v225, v105, v106
	s_and_b64 vcc, exec, s[2:3]
	s_cbranch_vccz .Lmla_p2_nope
	ds_write_b128 v176, v[138:141] offset:22656
	v_lshl_add_u32 v222, s19, 12, v179
	global_load_dwordx4 v[138:141], v222, s[62:63]
.Lmla_p2_nope:
	s_waitcnt lgkmcnt(5)
	v_mfma_f32_32x32x16_bf16 v[2:17], v[186:189], v[214:217], v[2:17]
	ds_read_b128 v[186:189], v229 offset:33280
	v_max3_f32 v224, v224, v91, v92
	v_max3_f32 v225, v225, v107, v108
	v_max3_f32 v224, v224, v93, v94
	v_max3_f32 v225, v225, v109, v110
	ds_write_b128 v173, v[142:145] offset:13312
	v_lshl_add_u32 v222, s13, 7, v168
	global_load_dwordx4 v[142:145], v222, s[56:57]
	s_waitcnt lgkmcnt(6)
	v_mfma_f32_32x32x16_bf16 v[18:33], v[190:193], v[214:217], v[18:33]
	ds_read_b128 v[190:193], v229 offset:26656
	v_max3_f32 v224, v224, v95, v96
	v_max3_f32 v225, v225, v111, v112
	v_max3_f32 v224, v224, v97, v113
	v_max_f32_e32 v224, v224, v225
	s_waitcnt lgkmcnt(6)
	v_mfma_f32_32x32x16_bf16 v[2:17], v[194:197], v[218:221], v[2:17]
	ds_read_b128 v[194:197], v229 offset:33312
	v_mov_b32_e32 v225, v224
	v_add_f32_e32 v1, v1, v164
	s_add_i32 s11, s11, 1
	v_permlane32_swap_b32_e32 v224, v225
	s_cmp_eq_u32 s9, s11
	v_max_f32_e32 v167, v224, v225
	v_cmp_lt_f32_e32 vcc, s66, v167
	s_waitcnt lgkmcnt(5)
	v_mfma_f32_32x32x16_bf16 v[18:33], v[198:201], v[218:221], v[18:33]
	s_cbranch_scc1 .Lmla_exit_p2

; template <int VAR>
; __device__ __forceinline__ void attn_phase(LAS unsigned char* lds, const AttnP P, int vcu, int G, int wave_s) {
;     ...
;                 if (ND0 == 6) {
;                     KR1(0); KR1(1); KR1(2); KR1(3); SB();
;                     QK1(0, negm); EX2(pc0, 0, w0.x); KR1(4); SB();
;                     QK1(1, negm); EX2(pc0, 2, w0.y); KR1(5); SB();
;                     QK1(2, pn0); EX2(pc0, 4, w0.z); KR1(6); SB();
;                     QK1(3, pn1); EX2(pc0, 6, w0.w); KR1(7); SB();
;                     QK1(4, pn0); EX2(pc0, 8, w1.x); KR1(8); SB();
;                     QK1(5, pn1); EX2(pc0, 10, w1.y); KR1(9); SB();
;                     QK1(6, pn0); EX2(pc0, 12, w1.z); KR1(10); SB();
;                     QK1(7, pn1); EX2(pc0, 14, w1.w); KR1(11); SB();
;                     QK1(8, pn0); EX2(pc1, 0, w2.x); VR1(0); SB();
;                     QK1(9, pn1); EX2(pc1, 2, w2.y); VR1(1); SB();
;                     QK1(10, pn0); EX2(pc1, 4, w2.z); VR1(2); SB();
;                     QK1(11, pn1); EX2(pc1, 6, w2.w); VR1(3); SB();
;                 } else {
;                     KR1(0); KR1(1); KR1(2); KR1(3); SB();
;                     QK1(0, negm); EX2(pc0, 0, w0.x); EX2(pc0, 2, w0.y); KR1(4); SB();
;                     QK1(1, negm); EX2(pc0, 4, w0.z); EX2(pc0, 6, w0.w); KR1(5); SB();
;                     QK1(2, pn0); EX2(pc0, 8, w1.x); EX2(pc0, 10, w1.y); KR1(6); SB();
;                     QK1(3, pn1); EX2(pc0, 12, w1.z); EX2(pc0, 14, w1.w); KR1(7); SB();
;                     QK1(4, pn0); EX2(pc1, 0, w2.x); VR1(0); SB();
;                     QK1(5, pn1); EX2(pc1, 2, w2.y); VR1(1); SB();
;                     QK1(6, pn0); EX2(pc1, 4, w2.z); VR1(2); SB();
;                     QK1(7, pn1); EX2(pc1, 6, w2.w); VR1(3); SB();
;                 }
;                 PV1(0, w0); EX2(pc1, 8, w3.x); VR1(4); SB();
;                 PV1(1, w0); EX2(pc1, 10, w3.y); VR1(5); SB();
;                 PV1(2, w1); EX2(pc1, 12, w3.z); VR1(6); SB();
;                 PV1(3, w1); EX2(pc1, 14, w3.w); VR1(7); SB();
;                 lrun += sacc;
;                 PV1(4, w2); MASK_TILE(pn0, pn1, t + 1); SB();
;                 PV1(5, w2); SB();
;                 PV1(6, w3); SB();
;                 PV1(7, w3); rmn = rowmax32(pn0, pn1); if (!USE_NEGM) rmn -= mref; SB();
;     ...
;             if (hn) { STOREK(t & 1); STOREV((t + 1) & 1); }
.Lmla_p3_go:
	v_exp_f32_e32 v222, v82
	v_exp_f32_e32 v223, v83
	v_add_f32_e32 v164, 0, v222
	v_cvt_pk_bf16_f32 v206, v222, v223
	v_add_f32_e32 v164, v223, v164
	v_exp_f32_e32 v224, v84
	v_exp_f32_e32 v225, v85
	v_add_f32_e32 v164, v224, v164
	v_cvt_pk_bf16_f32 v207, v224, v225
	v_add_f32_e32 v164, v225, v164
	s_waitcnt lgkmcnt(4)
	v_mfma_f32_32x32x16_bf16 v[34:49], v[182:185], v[114:117], v[66:81]
	ds_read_b128 v[198:201], v229 offset:26688
	v_exp_f32_e32 v222, v86
	v_exp_f32_e32 v223, v87
	v_add_f32_e32 v164, v222, v164
	v_cvt_pk_bf16_f32 v208, v222, v223
	v_add_f32_e32 v164, v223, v164
	s_waitcnt lgkmcnt(4)
	v_mfma_f32_32x32x16_bf16 v[50:65], v[186:189], v[114:117], v[66:81]
	ds_read_b128 v[182:185], v229 offset:33344
	v_exp_f32_e32 v224, v88
	v_exp_f32_e32 v225, v89
	v_add_f32_e32 v164, v224, v164
	v_cvt_pk_bf16_f32 v209, v224, v225
	v_add_f32_e32 v164, v225, v164
	s_waitcnt lgkmcnt(3)
	v_mfma_f32_32x32x16_bf16 v[34:49], v[190:193], v[118:121], v[34:49]
	ds_read_b128 v[186:189], v229 offset:26720
	v_exp_f32_e32 v222, v90
	v_exp_f32_e32 v223, v91
	v_add_f32_e32 v164, v222, v164
	v_cvt_pk_bf16_f32 v210, v222, v223
	v_add_f32_e32 v164, v223, v164
	s_waitcnt lgkmcnt(3)
	v_mfma_f32_32x32x16_bf16 v[50:65], v[194:197], v[118:121], v[50:65]
	ds_read_b128 v[190:193], v229 offset:33376
	v_exp_f32_e32 v224, v92
	v_exp_f32_e32 v225, v93
	v_add_f32_e32 v164, v224, v164
	v_cvt_pk_bf16_f32 v211, v224, v225
	v_add_f32_e32 v164, v225, v164
	s_waitcnt lgkmcnt(3)
	v_mfma_f32_32x32x16_bf16 v[34:49], v[198:201], v[122:125], v[34:49]
	ds_read_b128 v[194:197], v229 offset:26752
	v_exp_f32_e32 v222, v94
	v_exp_f32_e32 v223, v95
	v_add_f32_e32 v164, v222, v164
	v_cvt_pk_bf16_f32 v212, v222, v223
	v_add_f32_e32 v164, v223, v164
	s_waitcnt lgkmcnt(3)
	v_mfma_f32_32x32x16_bf16 v[50:65], v[182:185], v[122:125], v[50:65]
	ds_read_b128 v[198:201], v229 offset:33408
	v_exp_f32_e32 v224, v96
	v_exp_f32_e32 v225, v97
	v_add_f32_e32 v164, v224, v164
	v_cvt_pk_bf16_f32 v213, v224, v225
	v_add_f32_e32 v164, v225, v164
	s_waitcnt lgkmcnt(3)
	v_mfma_f32_32x32x16_bf16 v[34:49], v[186:189], v[126:129], v[34:49]
	ds_read_b128 v[182:185], v229 offset:26784
	v_exp_f32_e32 v222, v98
	v_exp_f32_e32 v223, v99
	v_add_f32_e32 v164, v222, v164
	v_cvt_pk_bf16_f32 v214, v222, v223
	v_add_f32_e32 v164, v223, v164
	s_waitcnt lgkmcnt(3)
	v_mfma_f32_32x32x16_bf16 v[50:65], v[190:193], v[126:129], v[50:65]
	ds_read_b128 v[186:189], v229 offset:33440
	v_exp_f32_e32 v224, v100
	v_exp_f32_e32 v225, v101
	v_add_f32_e32 v164, v224, v164
	v_cvt_pk_bf16_f32 v215, v224, v225
	v_add_f32_e32 v164, v225, v164
	s_waitcnt lgkmcnt(3)
	v_mfma_f32_32x32x16_bf16 v[34:49], v[194:197], v[130:133], v[34:49]
	ds_read_b128 v[190:193], v181 offset:49152
	v_exp_f32_e32 v222, v102
	v_exp_f32_e32 v223, v103
	v_add_f32_e32 v164, v222, v164
	v_cvt_pk_bf16_f32 v216, v222, v223
	v_add_f32_e32 v164, v223, v164
	s_waitcnt lgkmcnt(3)
	v_mfma_f32_32x32x16_bf16 v[50:65], v[198:201], v[130:133], v[50:65]
	ds_read_b128 v[194:197], v181 offset:53760
	v_exp_f32_e32 v224, v104
	v_exp_f32_e32 v225, v105
	v_add_f32_e32 v164, v224, v164
	v_cvt_pk_bf16_f32 v217, v224, v225
	v_add_f32_e32 v164, v225, v164
	s_waitcnt lgkmcnt(3)
	v_mfma_f32_32x32x16_bf16 v[34:49], v[182:185], v[134:137], v[34:49]
	ds_read_b128 v[198:201], v181 offset:49184
	v_exp_f32_e32 v222, v106
	v_exp_f32_e32 v223, v107
	v_add_f32_e32 v164, v222, v164
	v_cvt_pk_bf16_f32 v218, v222, v223
	v_add_f32_e32 v164, v223, v164
	s_waitcnt lgkmcnt(3)
	v_mfma_f32_32x32x16_bf16 v[50:65], v[186:189], v[134:137], v[50:65]
	ds_read_b128 v[182:185], v181 offset:53792
	v_exp_f32_e32 v224, v108
	v_exp_f32_e32 v225, v109
	v_add_f32_e32 v164, v224, v164
	v_cvt_pk_bf16_f32 v219, v224, v225
	v_add_f32_e32 v164, v225, v164
	s_waitcnt lgkmcnt(3)
	v_mfma_f32_32x32x16_bf16 v[2:17], v[190:193], v[206:209], v[2:17]
	ds_read_b128 v[186:189], v181 offset:49216
	v_exp_f32_e32 v222, v110
	v_exp_f32_e32 v223, v111
	v_add_f32_e32 v164, v222, v164
	v_cvt_pk_bf16_f32 v220, v222, v223
	v_add_f32_e32 v164, v223, v164
	s_waitcnt lgkmcnt(3)
	v_mfma_f32_32x32x16_bf16 v[18:33], v[194:197], v[206:209], v[18:33]
	ds_read_b128 v[190:193], v181 offset:53824
	v_exp_f32_e32 v224, v112
	v_exp_f32_e32 v225, v113
	v_add_f32_e32 v164, v224, v164
	v_cvt_pk_bf16_f32 v221, v224, v225
	v_add_f32_e32 v164, v225, v164
	s_mov_b32 s13, s20
	s_mov_b32 s20, s19
	s_add_i32 s19, s19, 1
	s_cmp_eq_u32 s19, s9
	s_cselect_b32 s19, 0, s19
	s_waitcnt lgkmcnt(3)
	v_mfma_f32_32x32x16_bf16 v[2:17], v[198:201], v[210:213], v[2:17]
	ds_read_b128 v[194:197], v181 offset:49248
	v_max3_f32 v224, v34, v35, v36
	v_max3_f32 v225, v50, v51, v52
	v_max3_f32 v224, v224, v37, v38
	v_max3_f32 v225, v225, v53, v54
	s_waitcnt vmcnt(2)
	ds_write_b128 v172, v[150:153] offset:45056
	v_lshl_add_u32 v222, s19, 17, v178
	global_load_dwordx4 v[150:153], v222, s[52:53]
	s_waitcnt lgkmcnt(4)
	v_mfma_f32_32x32x16_bf16 v[18:33], v[182:185], v[210:213], v[18:33]
	ds_read_b128 v[198:201], v181 offset:53856
	ds_read_b128 v[182:185], v174
	v_max3_f32 v224, v224, v39, v40
	v_max3_f32 v225, v225, v55, v56
	v_max3_f32 v224, v224, v41, v42
	v_max3_f32 v225, v225, v57, v58
	s_and_b64 vcc, exec, s[2:3]
	s_cbranch_vccz .Lmla_p3_nope
	ds_write_b128 v176, v[160:163] offset:45184
	v_lshl_add_u32 v222, s19, 12, v179
	global_load_dwordx4 v[160:163], v222, s[62:63]
.Lmla_p3_nope:
	s_waitcnt lgkmcnt(5)
	v_mfma_f32_32x32x16_bf16 v[2:17], v[186:189], v[214:217], v[2:17]
	ds_read_b128 v[186:189], v174 offset:6656
	v_max3_f32 v224, v224, v43, v44
	v_max3_f32 v225, v225, v59, v60
	v_max3_f32 v224, v224, v45, v46
	v_max3_f32 v225, v225, v61, v62
	ds_write_b128 v173, v[202:205] offset:35840
	v_lshl_add_u32 v222, s13, 7, v168
	global_load_dwordx4 v[202:205], v222, s[56:57]
	s_waitcnt lgkmcnt(6)
	v_mfma_f32_32x32x16_bf16 v[18:33], v[190:193], v[214:217], v[18:33]
	ds_read_b128 v[190:193], v174 offset:32
	v_max3_f32 v224, v224, v47, v48
	v_max3_f32 v225, v225, v63, v64
	v_max3_f32 v224, v224, v49, v65
	v_max_f32_e32 v224, v224, v225
	s_waitcnt lgkmcnt(6)
	v_mfma_f32_32x32x16_bf16 v[2:17], v[194:197], v[218:221], v[2:17]
	ds_read_b128 v[194:197], v174 offset:6688
	v_mov_b32_e32 v225, v224
	v_add_f32_e32 v1, v1, v164
	s_add_i32 s11, s11, 1
	v_permlane32_swap_b32_e32 v224, v225
	s_cmp_eq_u32 s9, s11
	v_max_f32_e32 v167, v224, v225
	v_cmp_lt_f32_e32 vcc, s66, v167
	s_waitcnt lgkmcnt(5)
	v_mfma_f32_32x32x16_bf16 v[18:33], v[198:201], v[218:221], v[18:33]
	s_waitcnt lgkmcnt(2)
	s_barrier
	s_cbranch_scc1 .Lmla_exit_p3

; template <int VAR>
; __device__ __forceinline__ void attn_phase(LAS unsigned char* lds, const AttnP P, int vcu, int G, int wave_s) {
;     ...
;                 if (ND0 == 6) {
;                     KR1(0); KR1(1); KR1(2); KR1(3); SB();
;                     QK1(0, negm); EX2(pc0, 0, w0.x); KR1(4); SB();
;                     QK1(1, negm); EX2(pc0, 2, w0.y); KR1(5); SB();
;                     QK1(2, pn0); EX2(pc0, 4, w0.z); KR1(6); SB();
;                     QK1(3, pn1); EX2(pc0, 6, w0.w); KR1(7); SB();
;                     QK1(4, pn0); EX2(pc0, 8, w1.x); KR1(8); SB();
;                     QK1(5, pn1); EX2(pc0, 10, w1.y); KR1(9); SB();
;                     QK1(6, pn0); EX2(pc0, 12, w1.z); KR1(10); SB();
;                     QK1(7, pn1); EX2(pc0, 14, w1.w); KR1(11); SB();
;                     QK1(8, pn0); EX2(pc1, 0, w2.x); VR1(0); SB();
;                     QK1(9, pn1); EX2(pc1, 2, w2.y); VR1(1); SB();
;                     QK1(10, pn0); EX2(pc1, 4, w2.z); VR1(2); SB();
;                     QK1(11, pn1); EX2(pc1, 6, w2.w); VR1(3); SB();
;                 } else {
;                     KR1(0); KR1(1); KR1(2); KR1(3); SB();
;                     QK1(0, negm); EX2(pc0, 0, w0.x); EX2(pc0, 2, w0.y); KR1(4); SB();
;                     QK1(1, negm); EX2(pc0, 4, w0.z); EX2(pc0, 6, w0.w); KR1(5); SB();
;                     QK1(2, pn0); EX2(pc0, 8, w1.x); EX2(pc0, 10, w1.y); KR1(6); SB();
;                     QK1(3, pn1); EX2(pc0, 12, w1.z); EX2(pc0, 14, w1.w); KR1(7); SB();
;                     QK1(4, pn0); EX2(pc1, 0, w2.x); VR1(0); SB();
;                     QK1(5, pn1); EX2(pc1, 2, w2.y); VR1(1); SB();
;                     QK1(6, pn0); EX2(pc1, 4, w2.z); VR1(2); SB();
;                     QK1(7, pn1); EX2(pc1, 6, w2.w); VR1(3); SB();
;                 }
;                 PV1(0, w0); EX2(pc1, 8, w3.x); VR1(4); SB();
;                 PV1(1, w0); EX2(pc1, 10, w3.y); VR1(5); SB();
;                 PV1(2, w1); EX2(pc1, 12, w3.z); VR1(6); SB();
;                 PV1(3, w1); EX2(pc1, 14, w3.w); VR1(7); SB();
;                 lrun += sacc;
;                 PV1(4, w2); MASK_TILE(pn0, pn1, t + 1); SB();
;                 PV1(5, w2); SB();
;                 PV1(6, w3); SB();
;                 PV1(7, w3); rmn = rowmax32(pn0, pn1); if (!USE_NEGM) rmn -= mref; SB();
;     ...
;             if (hn) { STOREK(t & 1); STOREV((t + 1) & 1); }
.Lmla_p4_go:
	v_exp_f32_e32 v222, v34
	v_exp_f32_e32 v223, v35
	v_add_f32_e32 v164, 0, v222
	v_cvt_pk_bf16_f32 v206, v222, v223
	v_add_f32_e32 v164, v223, v164
	v_exp_f32_e32 v224, v36
	v_exp_f32_e32 v225, v37
	v_add_f32_e32 v164, v224, v164
	v_cvt_pk_bf16_f32 v207, v224, v225
	v_add_f32_e32 v164, v225, v164
	s_waitcnt lgkmcnt(3)
	v_mfma_f32_32x32x16_bf16 v[82:97], v[182:185], v[114:117], v[66:81]
	ds_read_b128 v[198:201], v174 offset:64
	v_exp_f32_e32 v222, v38
	v_exp_f32_e32 v223, v39
	v_add_f32_e32 v164, v222, v164
	v_cvt_pk_bf16_f32 v208, v222, v223
	v_add_f32_e32 v164, v223, v164
	s_waitcnt lgkmcnt(3)
	v_mfma_f32_32x32x16_bf16 v[98:113], v[186:189], v[114:117], v[66:81]
	ds_read_b128 v[182:185], v174 offset:6720
	v_exp_f32_e32 v224, v40
	v_exp_f32_e32 v225, v41
	v_add_f32_e32 v164, v224, v164
	v_cvt_pk_bf16_f32 v209, v224, v225
	v_add_f32_e32 v164, v225, v164
	s_waitcnt lgkmcnt(3)
	v_mfma_f32_32x32x16_bf16 v[82:97], v[190:193], v[118:121], v[82:97]
	ds_read_b128 v[186:189], v174 offset:96
	v_exp_f32_e32 v222, v42
	v_exp_f32_e32 v223, v43
	v_add_f32_e32 v164, v222, v164
	v_cvt_pk_bf16_f32 v210, v222, v223
	v_add_f32_e32 v164, v223, v164
	s_waitcnt lgkmcnt(3)
	v_mfma_f32_32x32x16_bf16 v[98:113], v[194:197], v[118:121], v[98:113]
	ds_read_b128 v[190:193], v174 offset:6752
	v_exp_f32_e32 v224, v44
	v_exp_f32_e32 v225, v45
	v_add_f32_e32 v164, v224, v164
	v_cvt_pk_bf16_f32 v211, v224, v225
	v_add_f32_e32 v164, v225, v164
	s_waitcnt lgkmcnt(3)
	v_mfma_f32_32x32x16_bf16 v[82:97], v[198:201], v[122:125], v[82:97]
	ds_read_b128 v[194:197], v174 offset:128
	v_exp_f32_e32 v222, v46
	v_exp_f32_e32 v223, v47
	v_add_f32_e32 v164, v222, v164
	v_cvt_pk_bf16_f32 v212, v222, v223
	v_add_f32_e32 v164, v223, v164
	s_waitcnt lgkmcnt(3)
	v_mfma_f32_32x32x16_bf16 v[98:113], v[182:185], v[122:125], v[98:113]
	ds_read_b128 v[198:201], v174 offset:6784
	v_exp_f32_e32 v224, v48
	v_exp_f32_e32 v225, v49
	v_add_f32_e32 v164, v224, v164
	v_cvt_pk_bf16_f32 v213, v224, v225
	v_add_f32_e32 v164, v225, v164
	s_waitcnt lgkmcnt(3)
	v_mfma_f32_32x32x16_bf16 v[82:97], v[186:189], v[126:129], v[82:97]
	ds_read_b128 v[182:185], v174 offset:160
	v_exp_f32_e32 v222, v50
	v_exp_f32_e32 v223, v51
	v_add_f32_e32 v164, v222, v164
	v_cvt_pk_bf16_f32 v214, v222, v223
	v_add_f32_e32 v164, v223, v164
	s_waitcnt lgkmcnt(3)
	v_mfma_f32_32x32x16_bf16 v[98:113], v[190:193], v[126:129], v[98:113]
	ds_read_b128 v[186:189], v174 offset:6816
	v_exp_f32_e32 v224, v52
	v_exp_f32_e32 v225, v53
	v_add_f32_e32 v164, v224, v164
	v_cvt_pk_bf16_f32 v215, v224, v225
	v_add_f32_e32 v164, v225, v164
	s_waitcnt lgkmcnt(3)
	v_mfma_f32_32x32x16_bf16 v[82:97], v[194:197], v[130:133], v[82:97]
	ds_read_b128 v[190:193], v228 offset:13312
	v_exp_f32_e32 v222, v54
	v_exp_f32_e32 v223, v55
	v_add_f32_e32 v164, v222, v164
	v_cvt_pk_bf16_f32 v216, v222, v223
	v_add_f32_e32 v164, v223, v164
	s_waitcnt lgkmcnt(3)
	v_mfma_f32_32x32x16_bf16 v[98:113], v[198:201], v[130:133], v[98:113]
	ds_read_b128 v[194:197], v228 offset:17920
	v_exp_f32_e32 v224, v56
	v_exp_f32_e32 v225, v57
	v_add_f32_e32 v164, v224, v164
	v_cvt_pk_bf16_f32 v217, v224, v225
	v_add_f32_e32 v164, v225, v164
	s_waitcnt lgkmcnt(3)
	v_mfma_f32_32x32x16_bf16 v[82:97], v[182:185], v[134:137], v[82:97]
	ds_read_b128 v[198:201], v228 offset:13344
	v_exp_f32_e32 v222, v58
	v_exp_f32_e32 v223, v59
	v_add_f32_e32 v164, v222, v164
	v_cvt_pk_bf16_f32 v218, v222, v223
	v_add_f32_e32 v164, v223, v164
	s_waitcnt lgkmcnt(3)
	v_mfma_f32_32x32x16_bf16 v[98:113], v[186:189], v[134:137], v[98:113]
	ds_read_b128 v[182:185], v228 offset:17952
	v_exp_f32_e32 v224, v60
	v_exp_f32_e32 v225, v61
	v_add_f32_e32 v164, v224, v164
	v_cvt_pk_bf16_f32 v219, v224, v225
	v_add_f32_e32 v164, v225, v164
	s_waitcnt lgkmcnt(3)
	v_mfma_f32_32x32x16_bf16 v[2:17], v[190:193], v[206:209], v[2:17]
	ds_read_b128 v[186:189], v228 offset:13376
	v_exp_f32_e32 v222, v62
	v_exp_f32_e32 v223, v63
	v_add_f32_e32 v164, v222, v164
	v_cvt_pk_bf16_f32 v220, v222, v223
	v_add_f32_e32 v164, v223, v164
	s_waitcnt lgkmcnt(3)
	v_mfma_f32_32x32x16_bf16 v[18:33], v[194:197], v[206:209], v[18:33]
	ds_read_b128 v[190:193], v228 offset:17984
	v_exp_f32_e32 v224, v64
	v_exp_f32_e32 v225, v65
	v_add_f32_e32 v164, v224, v164
	v_cvt_pk_bf16_f32 v221, v224, v225
	v_add_f32_e32 v164, v225, v164
	s_mov_b32 s13, s20
	s_mov_b32 s20, s19
	s_add_i32 s19, s19, 1
	s_cmp_eq_u32 s19, s9
	s_cselect_b32 s19, 0, s19
	s_waitcnt lgkmcnt(3)
	v_mfma_f32_32x32x16_bf16 v[2:17], v[198:201], v[210:213], v[2:17]
	ds_read_b128 v[194:197], v228 offset:13408
	v_max3_f32 v224, v82, v83, v84
	v_max3_f32 v225, v98, v99, v100
	v_max3_f32 v224, v224, v85, v86
	v_max3_f32 v225, v225, v101, v102
	s_waitcnt vmcnt(2)
	ds_write_b128 v172, v[146:149] offset:58368
	v_lshl_add_u32 v222, s19, 17, v178
	global_load_dwordx4 v[146:149], v222, s[52:53]
	s_waitcnt lgkmcnt(4)
	v_mfma_f32_32x32x16_bf16 v[18:33], v[182:185], v[210:213], v[18:33]
	ds_read_b128 v[198:201], v228 offset:18016
	ds_read_b128 v[182:185], v174 offset:22528
	v_max3_f32 v224, v224, v87, v88
	v_max3_f32 v225, v225, v103, v104
	v_max3_f32 v224, v224, v89, v90
	v_max3_f32 v225, v225, v105, v106
	s_and_b64 vcc, exec, s[2:3]
	s_cbranch_vccz .Lmla_p4_nope
	ds_write_b128 v176, v[138:141] offset:58496
	v_lshl_add_u32 v222, s19, 12, v179
	global_load_dwordx4 v[138:141], v222, s[62:63]
.Lmla_p4_nope:
	s_waitcnt lgkmcnt(5)
	v_mfma_f32_32x32x16_bf16 v[2:17], v[186:189], v[214:217], v[2:17]
	ds_read_b128 v[186:189], v174 offset:29184
	v_max3_f32 v224, v224, v91, v92
	v_max3_f32 v225, v225, v107, v108
	v_max3_f32 v224, v224, v93, v94
	v_max3_f32 v225, v225, v109, v110
	v_add_u32_e32 v222, 0xb000, v173
	ds_write_b128 v222, v[142:145] offset:39936
	v_lshl_add_u32 v222, s13, 7, v168
	global_load_dwordx4 v[142:145], v222, s[56:57]
	s_waitcnt lgkmcnt(6)
	v_mfma_f32_32x32x16_bf16 v[18:33], v[190:193], v[214:217], v[18:33]
	ds_read_b128 v[190:193], v174 offset:22560
	v_max3_f32 v224, v224, v95, v96
	v_max3_f32 v225, v225, v111, v112
	v_max3_f32 v224, v224, v97, v113
	v_max_f32_e32 v224, v224, v225
	s_waitcnt lgkmcnt(6)
	v_mfma_f32_32x32x16_bf16 v[2:17], v[194:197], v[218:221], v[2:17]
	ds_read_b128 v[194:197], v174 offset:29216
	v_mov_b32_e32 v225, v224
	v_add_f32_e32 v1, v1, v164
	s_add_i32 s11, s11, 1
	v_permlane32_swap_b32_e32 v224, v225
	s_cmp_eq_u32 s9, s11
	v_max_f32_e32 v167, v224, v225
	v_cmp_lt_f32_e32 vcc, s66, v167
	s_waitcnt lgkmcnt(5)
	v_mfma_f32_32x32x16_bf16 v[18:33], v[198:201], v[218:221], v[18:33]
	s_cbranch_scc1 .Lmla_exit_p4

; template <int VAR>
; __device__ __forceinline__ void attn_phase(LAS unsigned char* lds, const AttnP P, int vcu, int G, int wave_s) {
;     ...
;                 if (ND0 == 6) {
;                     KR1(0); KR1(1); KR1(2); KR1(3); SB();
;                     QK1(0, negm); EX2(pc0, 0, w0.x); KR1(4); SB();
;                     QK1(1, negm); EX2(pc0, 2, w0.y); KR1(5); SB();
;                     QK1(2, pn0); EX2(pc0, 4, w0.z); KR1(6); SB();
;                     QK1(3, pn1); EX2(pc0, 6, w0.w); KR1(7); SB();
;                     QK1(4, pn0); EX2(pc0, 8, w1.x); KR1(8); SB();
;                     QK1(5, pn1); EX2(pc0, 10, w1.y); KR1(9); SB();
;                     QK1(6, pn0); EX2(pc0, 12, w1.z); KR1(10); SB();
;                     QK1(7, pn1); EX2(pc0, 14, w1.w); KR1(11); SB();
;                     QK1(8, pn0); EX2(pc1, 0, w2.x); VR1(0); SB();
;                     QK1(9, pn1); EX2(pc1, 2, w2.y); VR1(1); SB();
;                     QK1(10, pn0); EX2(pc1, 4, w2.z); VR1(2); SB();
;                     QK1(11, pn1); EX2(pc1, 6, w2.w); VR1(3); SB();
;                 } else {
;                     KR1(0); KR1(1); KR1(2); KR1(3); SB();
;                     QK1(0, negm); EX2(pc0, 0, w0.x); EX2(pc0, 2, w0.y); KR1(4); SB();
;                     QK1(1, negm); EX2(pc0, 4, w0.z); EX2(pc0, 6, w0.w); KR1(5); SB();
;                     QK1(2, pn0); EX2(pc0, 8, w1.x); EX2(pc0, 10, w1.y); KR1(6); SB();
;                     QK1(3, pn1); EX2(pc0, 12, w1.z); EX2(pc0, 14, w1.w); KR1(7); SB();
;                     QK1(4, pn0); EX2(pc1, 0, w2.x); VR1(0); SB();
;                     QK1(5, pn1); EX2(pc1, 2, w2.y); VR1(1); SB();
;                     QK1(6, pn0); EX2(pc1, 4, w2.z); VR1(2); SB();
;                     QK1(7, pn1); EX2(pc1, 6, w2.w); VR1(3); SB();
;                 }
;                 PV1(0, w0); EX2(pc1, 8, w3.x); VR1(4); SB();
;                 PV1(1, w0); EX2(pc1, 10, w3.y); VR1(5); SB();
;                 PV1(2, w1); EX2(pc1, 12, w3.z); VR1(6); SB();
;                 PV1(3, w1); EX2(pc1, 14, w3.w); VR1(7); SB();
;                 lrun += sacc;
;                 PV1(4, w2); MASK_TILE(pn0, pn1, t + 1); SB();
;                 PV1(5, w2); SB();
;                 PV1(6, w3); SB();
;                 PV1(7, w3); rmn = rowmax32(pn0, pn1); if (!USE_NEGM) rmn -= mref; SB();
;     ...
;             if (hn) { STOREK(t & 1); STOREV((t + 1) & 1); }
.Lmla_p5_go:
	v_exp_f32_e32 v222, v82
	v_exp_f32_e32 v223, v83
	v_add_f32_e32 v164, 0, v222
	v_cvt_pk_bf16_f32 v206, v222, v223
	v_add_f32_e32 v164, v223, v164
	v_exp_f32_e32 v224, v84
	v_exp_f32_e32 v225, v85
	v_add_f32_e32 v164, v224, v164
	v_cvt_pk_bf16_f32 v207, v224, v225
	v_add_f32_e32 v164, v225, v164
	s_waitcnt lgkmcnt(4)
	v_mfma_f32_32x32x16_bf16 v[34:49], v[182:185], v[114:117], v[66:81]
	ds_read_b128 v[198:201], v174 offset:22592
	v_exp_f32_e32 v222, v86
	v_exp_f32_e32 v223, v87
	v_add_f32_e32 v164, v222, v164
	v_cvt_pk_bf16_f32 v208, v222, v223
	v_add_f32_e32 v164, v223, v164
	s_waitcnt lgkmcnt(4)
	v_mfma_f32_32x32x16_bf16 v[50:65], v[186:189], v[114:117], v[66:81]
	ds_read_b128 v[182:185], v174 offset:29248
	v_exp_f32_e32 v224, v88
	v_exp_f32_e32 v225, v89
	v_add_f32_e32 v164, v224, v164
	v_cvt_pk_bf16_f32 v209, v224, v225
	v_add_f32_e32 v164, v225, v164
	s_waitcnt lgkmcnt(3)
	v_mfma_f32_32x32x16_bf16 v[34:49], v[190:193], v[118:121], v[34:49]
	ds_read_b128 v[186:189], v174 offset:22624
	v_exp_f32_e32 v222, v90
	v_exp_f32_e32 v223, v91
	v_add_f32_e32 v164, v222, v164
	v_cvt_pk_bf16_f32 v210, v222, v223
	v_add_f32_e32 v164, v223, v164
	s_waitcnt lgkmcnt(3)
	v_mfma_f32_32x32x16_bf16 v[50:65], v[194:197], v[118:121], v[50:65]
	ds_read_b128 v[190:193], v174 offset:29280
	v_exp_f32_e32 v224, v92
	v_exp_f32_e32 v225, v93
	v_add_f32_e32 v164, v224, v164
	v_cvt_pk_bf16_f32 v211, v224, v225
	v_add_f32_e32 v164, v225, v164
	s_waitcnt lgkmcnt(3)
	v_mfma_f32_32x32x16_bf16 v[34:49], v[198:201], v[122:125], v[34:49]
	ds_read_b128 v[194:197], v174 offset:22656
	v_exp_f32_e32 v222, v94
	v_exp_f32_e32 v223, v95
	v_add_f32_e32 v164, v222, v164
	v_cvt_pk_bf16_f32 v212, v222, v223
	v_add_f32_e32 v164, v223, v164
	s_waitcnt lgkmcnt(3)
	v_mfma_f32_32x32x16_bf16 v[50:65], v[182:185], v[122:125], v[50:65]
	ds_read_b128 v[198:201], v174 offset:29312
	v_exp_f32_e32 v224, v96
	v_exp_f32_e32 v225, v97
	v_add_f32_e32 v164, v224, v164
	v_cvt_pk_bf16_f32 v213, v224, v225
	v_add_f32_e32 v164, v225, v164
	s_waitcnt lgkmcnt(3)
	v_mfma_f32_32x32x16_bf16 v[34:49], v[186:189], v[126:129], v[34:49]
	ds_read_b128 v[182:185], v174 offset:22688
	v_exp_f32_e32 v222, v98
	v_exp_f32_e32 v223, v99
	v_add_f32_e32 v164, v222, v164
	v_cvt_pk_bf16_f32 v214, v222, v223
	v_add_f32_e32 v164, v223, v164
	s_waitcnt lgkmcnt(3)
	v_mfma_f32_32x32x16_bf16 v[50:65], v[190:193], v[126:129], v[50:65]
	ds_read_b128 v[186:189], v174 offset:29344
	v_exp_f32_e32 v224, v100
	v_exp_f32_e32 v225, v101
	v_add_f32_e32 v164, v224, v164
	v_cvt_pk_bf16_f32 v215, v224, v225
	v_add_f32_e32 v164, v225, v164
	s_waitcnt lgkmcnt(3)
	v_mfma_f32_32x32x16_bf16 v[34:49], v[194:197], v[130:133], v[34:49]
	ds_read_b128 v[190:193], v228 offset:35840
	v_exp_f32_e32 v222, v102
	v_exp_f32_e32 v223, v103
	v_add_f32_e32 v164, v222, v164
	v_cvt_pk_bf16_f32 v216, v222, v223
	v_add_f32_e32 v164, v223, v164
	s_waitcnt lgkmcnt(3)
	v_mfma_f32_32x32x16_bf16 v[50:65], v[198:201], v[130:133], v[50:65]
	ds_read_b128 v[194:197], v228 offset:40448
	v_exp_f32_e32 v224, v104
	v_exp_f32_e32 v225, v105
	v_add_f32_e32 v164, v224, v164
	v_cvt_pk_bf16_f32 v217, v224, v225
	v_add_f32_e32 v164, v225, v164
	s_waitcnt lgkmcnt(3)
	v_mfma_f32_32x32x16_bf16 v[34:49], v[182:185], v[134:137], v[34:49]
	ds_read_b128 v[198:201], v228 offset:35872
	v_exp_f32_e32 v222, v106
	v_exp_f32_e32 v223, v107
	v_add_f32_e32 v164, v222, v164
	v_cvt_pk_bf16_f32 v218, v222, v223
	v_add_f32_e32 v164, v223, v164
	s_waitcnt lgkmcnt(3)
	v_mfma_f32_32x32x16_bf16 v[50:65], v[186:189], v[134:137], v[50:65]
	ds_read_b128 v[182:185], v228 offset:40480
	v_exp_f32_e32 v224, v108
	v_exp_f32_e32 v225, v109
	v_add_f32_e32 v164, v224, v164
	v_cvt_pk_bf16_f32 v219, v224, v225
	v_add_f32_e32 v164, v225, v164
	s_waitcnt lgkmcnt(3)
	v_mfma_f32_32x32x16_bf16 v[2:17], v[190:193], v[206:209], v[2:17]
	ds_read_b128 v[186:189], v228 offset:35904
	v_exp_f32_e32 v222, v110
	v_exp_f32_e32 v223, v111
	v_add_f32_e32 v164, v222, v164
	v_cvt_pk_bf16_f32 v220, v222, v223
	v_add_f32_e32 v164, v223, v164
	s_waitcnt lgkmcnt(3)
	v_mfma_f32_32x32x16_bf16 v[18:33], v[194:197], v[206:209], v[18:33]
	ds_read_b128 v[190:193], v228 offset:40512
	v_exp_f32_e32 v224, v112
	v_exp_f32_e32 v225, v113
	v_add_f32_e32 v164, v224, v164
	v_cvt_pk_bf16_f32 v221, v224, v225
	v_add_f32_e32 v164, v225, v164
	s_mov_b32 s13, s20
	s_mov_b32 s20, s19
	s_add_i32 s19, s19, 1
	s_cmp_eq_u32 s19, s9
	s_cselect_b32 s19, 0, s19
	s_waitcnt lgkmcnt(3)
	v_mfma_f32_32x32x16_bf16 v[2:17], v[198:201], v[210:213], v[2:17]
	ds_read_b128 v[194:197], v228 offset:35936
	v_max3_f32 v224, v34, v35, v36
	v_max3_f32 v225, v50, v51, v52
	v_max3_f32 v224, v224, v37, v38
	v_max3_f32 v225, v225, v53, v54
	s_waitcnt vmcnt(2)
	v_add_u32_e32 v222, 0xb000, v172
	ds_write_b128 v222, v[150:153] offset:26624
	v_lshl_add_u32 v222, s19, 17, v178
	global_load_dwordx4 v[150:153], v222, s[52:53]
	s_waitcnt lgkmcnt(4)
	v_mfma_f32_32x32x16_bf16 v[18:33], v[182:185], v[210:213], v[18:33]
	ds_read_b128 v[198:201], v228 offset:40544
	ds_read_b128 v[182:185], v174 offset:45056
	v_max3_f32 v224, v224, v39, v40
	v_max3_f32 v225, v225, v55, v56
	v_max3_f32 v224, v224, v41, v42
	v_max3_f32 v225, v225, v57, v58
	s_and_b64 vcc, exec, s[2:3]
	s_cbranch_vccz .Lmla_p5_nope
	v_add_u32_e32 v222, 0xb000, v176
	ds_write_b128 v222, v[160:163] offset:26752
	v_lshl_add_u32 v222, s19, 12, v179
	global_load_dwordx4 v[160:163], v222, s[62:63]
.Lmla_p5_nope:
	s_waitcnt lgkmcnt(5)
	v_mfma_f32_32x32x16_bf16 v[2:17], v[186:189], v[214:217], v[2:17]
	ds_read_b128 v[186:189], v174 offset:51712
	v_max3_f32 v224, v224, v43, v44
	v_max3_f32 v225, v225, v59, v60
	v_max3_f32 v224, v224, v45, v46
	v_max3_f32 v225, v225, v61, v62
	v_add_u32_e32 v222, 0xb000, v173
	ds_write_b128 v222, v[202:205] offset:49152
	v_lshl_add_u32 v222, s13, 7, v168
	global_load_dwordx4 v[202:205], v222, s[56:57]
	s_waitcnt lgkmcnt(6)
	v_mfma_f32_32x32x16_bf16 v[18:33], v[190:193], v[214:217], v[18:33]
	ds_read_b128 v[190:193], v174 offset:45088
	v_max3_f32 v224, v224, v47, v48
	v_max3_f32 v225, v225, v63, v64
	v_max3_f32 v224, v224, v49, v65
	v_max_f32_e32 v224, v224, v225
	s_waitcnt lgkmcnt(6)
	v_mfma_f32_32x32x16_bf16 v[2:17], v[194:197], v[218:221], v[2:17]
	ds_read_b128 v[194:197], v174 offset:51744
	v_mov_b32_e32 v225, v224
	v_add_f32_e32 v1, v1, v164
	s_add_i32 s11, s11, 1
	v_permlane32_swap_b32_e32 v224, v225
	s_cmp_eq_u32 s9, s11
	v_max_f32_e32 v167, v224, v225
	v_cmp_lt_f32_e32 vcc, s66, v167
	s_waitcnt lgkmcnt(5)
	v_mfma_f32_32x32x16_bf16 v[18:33], v[198:201], v[218:221], v[18:33]
	s_waitcnt lgkmcnt(2)
	s_barrier
	s_cbranch_scc1 .Lmla_exit_p5

; template <int VAR>
; __device__ __forceinline__ void attn_phase(LAS unsigned char* lds, const AttnP P, int vcu, int G, int wave_s) {
;     ...
;                 if (ND0 == 6) {
;                     KR1(0); KR1(1); KR1(2); KR1(3); SB();
;                     QK1(0, negm); EX2(pc0, 0, w0.x); KR1(4); SB();
;                     QK1(1, negm); EX2(pc0, 2, w0.y); KR1(5); SB();
;                     QK1(2, pn0); EX2(pc0, 4, w0.z); KR1(6); SB();
;                     QK1(3, pn1); EX2(pc0, 6, w0.w); KR1(7); SB();
;                     QK1(4, pn0); EX2(pc0, 8, w1.x); KR1(8); SB();
;                     QK1(5, pn1); EX2(pc0, 10, w1.y); KR1(9); SB();
;                     QK1(6, pn0); EX2(pc0, 12, w1.z); KR1(10); SB();
;                     QK1(7, pn1); EX2(pc0, 14, w1.w); KR1(11); SB();
;                     QK1(8, pn0); EX2(pc1, 0, w2.x); VR1(0); SB();
;                     QK1(9, pn1); EX2(pc1, 2, w2.y); VR1(1); SB();
;                     QK1(10, pn0); EX2(pc1, 4, w2.z); VR1(2); SB();
;                     QK1(11, pn1); EX2(pc1, 6, w2.w); VR1(3); SB();
;                 } else {
;                     KR1(0); KR1(1); KR1(2); KR1(3); SB();
;                     QK1(0, negm); EX2(pc0, 0, w0.x); EX2(pc0, 2, w0.y); KR1(4); SB();
;                     QK1(1, negm); EX2(pc0, 4, w0.z); EX2(pc0, 6, w0.w); KR1(5); SB();
;                     QK1(2, pn0); EX2(pc0, 8, w1.x); EX2(pc0, 10, w1.y); KR1(6); SB();
;                     QK1(3, pn1); EX2(pc0, 12, w1.z); EX2(pc0, 14, w1.w); KR1(7); SB();
;                     QK1(4, pn0); EX2(pc1, 0, w2.x); VR1(0); SB();
;                     QK1(5, pn1); EX2(pc1, 2, w2.y); VR1(1); SB();
;                     QK1(6, pn0); EX2(pc1, 4, w2.z); VR1(2); SB();
;                     QK1(7, pn1); EX2(pc1, 6, w2.w); VR1(3); SB();
;                 }
;                 PV1(0, w0); EX2(pc1, 8, w3.x); VR1(4); SB();
;                 PV1(1, w0); EX2(pc1, 10, w3.y); VR1(5); SB();
;                 PV1(2, w1); EX2(pc1, 12, w3.z); VR1(6); SB();
;                 PV1(3, w1); EX2(pc1, 14, w3.w); VR1(7); SB();
;                 lrun += sacc;
;                 PV1(4, w2); MASK_TILE(pn0, pn1, t + 1); SB();
;                 PV1(5, w2); SB();
;                 PV1(6, w3); SB();
;                 PV1(7, w3); rmn = rowmax32(pn0, pn1); if (!USE_NEGM) rmn -= mref; SB();
;     ...
;             if (hn) { STOREK(t & 1); STOREV((t + 1) & 1); }
.Lmla_p6_go:
	v_exp_f32_e32 v222, v34
	v_exp_f32_e32 v223, v35
	v_add_f32_e32 v164, 0, v222
	v_cvt_pk_bf16_f32 v206, v222, v223
	v_add_f32_e32 v164, v223, v164
	v_exp_f32_e32 v224, v36
	v_exp_f32_e32 v225, v37
	v_add_f32_e32 v164, v224, v164
	v_cvt_pk_bf16_f32 v207, v224, v225
	v_add_f32_e32 v164, v225, v164
	s_waitcnt lgkmcnt(3)
	v_mfma_f32_32x32x16_bf16 v[82:97], v[182:185], v[114:117], v[66:81]
	ds_read_b128 v[198:201], v174 offset:45120
	v_exp_f32_e32 v222, v38
	v_exp_f32_e32 v223, v39
	v_add_f32_e32 v164, v222, v164
	v_cvt_pk_bf16_f32 v208, v222, v223
	v_add_f32_e32 v164, v223, v164
	s_waitcnt lgkmcnt(3)
	v_mfma_f32_32x32x16_bf16 v[98:113], v[186:189], v[114:117], v[66:81]
	ds_read_b128 v[182:185], v174 offset:51776
	v_exp_f32_e32 v224, v40
	v_exp_f32_e32 v225, v41
	v_add_f32_e32 v164, v224, v164
	v_cvt_pk_bf16_f32 v209, v224, v225
	v_add_f32_e32 v164, v225, v164
	s_waitcnt lgkmcnt(3)
	v_mfma_f32_32x32x16_bf16 v[82:97], v[190:193], v[118:121], v[82:97]
	ds_read_b128 v[186:189], v174 offset:45152
	v_exp_f32_e32 v222, v42
	v_exp_f32_e32 v223, v43
	v_add_f32_e32 v164, v222, v164
	v_cvt_pk_bf16_f32 v210, v222, v223
	v_add_f32_e32 v164, v223, v164
	s_waitcnt lgkmcnt(3)
	v_mfma_f32_32x32x16_bf16 v[98:113], v[194:197], v[118:121], v[98:113]
	ds_read_b128 v[190:193], v174 offset:51808
	v_exp_f32_e32 v224, v44
	v_exp_f32_e32 v225, v45
	v_add_f32_e32 v164, v224, v164
	v_cvt_pk_bf16_f32 v211, v224, v225
	v_add_f32_e32 v164, v225, v164
	s_waitcnt lgkmcnt(3)
	v_mfma_f32_32x32x16_bf16 v[82:97], v[198:201], v[122:125], v[82:97]
	ds_read_b128 v[194:197], v174 offset:45184
	v_exp_f32_e32 v222, v46
	v_exp_f32_e32 v223, v47
	v_add_f32_e32 v164, v222, v164
	v_cvt_pk_bf16_f32 v212, v222, v223
	v_add_f32_e32 v164, v223, v164
	s_waitcnt lgkmcnt(3)
	v_mfma_f32_32x32x16_bf16 v[98:113], v[182:185], v[122:125], v[98:113]
	ds_read_b128 v[198:201], v174 offset:51840
	v_exp_f32_e32 v224, v48
	v_exp_f32_e32 v225, v49
	v_add_f32_e32 v164, v224, v164
	v_cvt_pk_bf16_f32 v213, v224, v225
	v_add_f32_e32 v164, v225, v164
	s_waitcnt lgkmcnt(3)
	v_mfma_f32_32x32x16_bf16 v[82:97], v[186:189], v[126:129], v[82:97]
	ds_read_b128 v[182:185], v174 offset:45216
	v_exp_f32_e32 v222, v50
	v_exp_f32_e32 v223, v51
	v_add_f32_e32 v164, v222, v164
	v_cvt_pk_bf16_f32 v214, v222, v223
	v_add_f32_e32 v164, v223, v164
	s_waitcnt lgkmcnt(3)
	v_mfma_f32_32x32x16_bf16 v[98:113], v[190:193], v[126:129], v[98:113]
	ds_read_b128 v[186:189], v174 offset:51872
	v_exp_f32_e32 v224, v52
	v_exp_f32_e32 v225, v53
	v_add_f32_e32 v164, v224, v164
	v_cvt_pk_bf16_f32 v215, v224, v225
	v_add_f32_e32 v164, v225, v164
	s_waitcnt lgkmcnt(3)
	v_mfma_f32_32x32x16_bf16 v[82:97], v[194:197], v[130:133], v[82:97]
	ds_read_b128 v[190:193], v181 offset:39936
	v_exp_f32_e32 v222, v54
	v_exp_f32_e32 v223, v55
	v_add_f32_e32 v164, v222, v164
	v_cvt_pk_bf16_f32 v216, v222, v223
	v_add_f32_e32 v164, v223, v164
	s_waitcnt lgkmcnt(3)
	v_mfma_f32_32x32x16_bf16 v[98:113], v[198:201], v[130:133], v[98:113]
	ds_read_b128 v[194:197], v181 offset:44544
	v_exp_f32_e32 v224, v56
	v_exp_f32_e32 v225, v57
	v_add_f32_e32 v164, v224, v164
	v_cvt_pk_bf16_f32 v217, v224, v225
	v_add_f32_e32 v164, v225, v164
	s_waitcnt lgkmcnt(3)
	v_mfma_f32_32x32x16_bf16 v[82:97], v[182:185], v[134:137], v[82:97]
	ds_read_b128 v[198:201], v181 offset:39968
	v_exp_f32_e32 v222, v58
	v_exp_f32_e32 v223, v59
	v_add_f32_e32 v164, v222, v164
	v_cvt_pk_bf16_f32 v218, v222, v223
	v_add_f32_e32 v164, v223, v164
	s_waitcnt lgkmcnt(3)
	v_mfma_f32_32x32x16_bf16 v[98:113], v[186:189], v[134:137], v[98:113]
	ds_read_b128 v[182:185], v181 offset:44576
	v_exp_f32_e32 v224, v60
	v_exp_f32_e32 v225, v61
	v_add_f32_e32 v164, v224, v164
	v_cvt_pk_bf16_f32 v219, v224, v225
	v_add_f32_e32 v164, v225, v164
	s_waitcnt lgkmcnt(3)
	v_mfma_f32_32x32x16_bf16 v[2:17], v[190:193], v[206:209], v[2:17]
	ds_read_b128 v[186:189], v181 offset:40000
	v_exp_f32_e32 v222, v62
	v_exp_f32_e32 v223, v63
	v_add_f32_e32 v164, v222, v164
	v_cvt_pk_bf16_f32 v220, v222, v223
	v_add_f32_e32 v164, v223, v164
	s_waitcnt lgkmcnt(3)
	v_mfma_f32_32x32x16_bf16 v[18:33], v[194:197], v[206:209], v[18:33]
	ds_read_b128 v[190:193], v181 offset:44608
	v_exp_f32_e32 v224, v64
	v_exp_f32_e32 v225, v65
	v_add_f32_e32 v164, v224, v164
	v_cvt_pk_bf16_f32 v221, v224, v225
	v_add_f32_e32 v164, v225, v164
	s_mov_b32 s13, s20
	s_mov_b32 s20, s19
	s_add_i32 s19, s19, 1
	s_cmp_eq_u32 s19, s9
	s_cselect_b32 s19, 0, s19
	s_waitcnt lgkmcnt(3)
	v_mfma_f32_32x32x16_bf16 v[2:17], v[198:201], v[210:213], v[2:17]
	ds_read_b128 v[194:197], v181 offset:40032
	v_max3_f32 v224, v82, v83, v84
	v_max3_f32 v225, v98, v99, v100
	v_max3_f32 v224, v224, v85, v86
	v_max3_f32 v225, v225, v101, v102
	s_waitcnt vmcnt(2)
	ds_write_b128 v172, v[146:149]
	v_lshl_add_u32 v222, s19, 17, v178
	global_load_dwordx4 v[146:149], v222, s[52:53]
	s_waitcnt lgkmcnt(4)
	v_mfma_f32_32x32x16_bf16 v[18:33], v[182:185], v[210:213], v[18:33]
	ds_read_b128 v[198:201], v181 offset:44640
	ds_read_b128 v[182:185], v229 offset:13312
	v_max3_f32 v224, v224, v87, v88
	v_max3_f32 v225, v225, v103, v104
	v_max3_f32 v224, v224, v89, v90
	v_max3_f32 v225, v225, v105, v106
	s_and_b64 vcc, exec, s[2:3]
	s_cbranch_vccz .Lmla_p6_nope
	ds_write_b128 v176, v[138:141] offset:128
	v_lshl_add_u32 v222, s19, 12, v179
	global_load_dwordx4 v[138:141], v222, s[62:63]
.Lmla_p6_nope:
	s_waitcnt lgkmcnt(5)
	v_mfma_f32_32x32x16_bf16 v[2:17], v[186:189], v[214:217], v[2:17]
	ds_read_b128 v[186:189], v229 offset:19968
	v_max3_f32 v224, v224, v91, v92
	v_max3_f32 v225, v225, v107, v108
	v_max3_f32 v224, v224, v93, v94
	v_max3_f32 v225, v225, v109, v110
	ds_write_b128 v173, v[142:145] offset:13312
	v_lshl_add_u32 v222, s13, 7, v168
	global_load_dwordx4 v[142:145], v222, s[56:57]
	s_waitcnt lgkmcnt(6)
	v_mfma_f32_32x32x16_bf16 v[18:33], v[190:193], v[214:217], v[18:33]
	ds_read_b128 v[190:193], v229 offset:13344
	v_max3_f32 v224, v224, v95, v96
	v_max3_f32 v225, v225, v111, v112
	v_max3_f32 v224, v224, v97, v113
	v_max_f32_e32 v224, v224, v225
	s_waitcnt lgkmcnt(6)
	v_mfma_f32_32x32x16_bf16 v[2:17], v[194:197], v[218:221], v[2:17]
	ds_read_b128 v[194:197], v229 offset:20000
	v_mov_b32_e32 v225, v224
	v_add_f32_e32 v1, v1, v164
	s_add_i32 s11, s11, 1
	v_permlane32_swap_b32_e32 v224, v225
	s_cmp_eq_u32 s9, s11
	v_max_f32_e32 v167, v224, v225
	v_cmp_lt_f32_e32 vcc, s66, v167
	s_waitcnt lgkmcnt(5)
	v_mfma_f32_32x32x16_bf16 v[18:33], v[198:201], v[218:221], v[18:33]
	s_cbranch_scc1 .Lmla_exit_p6

; template <int VAR>
; __device__ __forceinline__ void attn_phase(LAS unsigned char* lds, const AttnP P, int vcu, int G, int wave_s) {
;     ...
;                 if (ND0 == 6) {
;                     KR1(0); KR1(1); KR1(2); KR1(3); SB();
;                     QK1(0, negm); EX2(pc0, 0, w0.x); KR1(4); SB();
;                     QK1(1, negm); EX2(pc0, 2, w0.y); KR1(5); SB();
;                     QK1(2, pn0); EX2(pc0, 4, w0.z); KR1(6); SB();
;                     QK1(3, pn1); EX2(pc0, 6, w0.w); KR1(7); SB();
;                     QK1(4, pn0); EX2(pc0, 8, w1.x); KR1(8); SB();
;                     QK1(5, pn1); EX2(pc0, 10, w1.y); KR1(9); SB();
;                     QK1(6, pn0); EX2(pc0, 12, w1.z); KR1(10); SB();
;                     QK1(7, pn1); EX2(pc0, 14, w1.w); KR1(11); SB();
;                     QK1(8, pn0); EX2(pc1, 0, w2.x); VR1(0); SB();
;                     QK1(9, pn1); EX2(pc1, 2, w2.y); VR1(1); SB();
;                     QK1(10, pn0); EX2(pc1, 4, w2.z); VR1(2); SB();
;                     QK1(11, pn1); EX2(pc1, 6, w2.w); VR1(3); SB();
;                 } else {
;                     KR1(0); KR1(1); KR1(2); KR1(3); SB();
;                     QK1(0, negm); EX2(pc0, 0, w0.x); EX2(pc0, 2, w0.y); KR1(4); SB();
;                     QK1(1, negm); EX2(pc0, 4, w0.z); EX2(pc0, 6, w0.w); KR1(5); SB();
;                     QK1(2, pn0); EX2(pc0, 8, w1.x); EX2(pc0, 10, w1.y); KR1(6); SB();
;                     QK1(3, pn1); EX2(pc0, 12, w1.z); EX2(pc0, 14, w1.w); KR1(7); SB();
;                     QK1(4, pn0); EX2(pc1, 0, w2.x); VR1(0); SB();
;                     QK1(5, pn1); EX2(pc1, 2, w2.y); VR1(1); SB();
;                     QK1(6, pn0); EX2(pc1, 4, w2.z); VR1(2); SB();
;                     QK1(7, pn1); EX2(pc1, 6, w2.w); VR1(3); SB();
;                 }
;                 PV1(0, w0); EX2(pc1, 8, w3.x); VR1(4); SB();
;                 PV1(1, w0); EX2(pc1, 10, w3.y); VR1(5); SB();
;                 PV1(2, w1); EX2(pc1, 12, w3.z); VR1(6); SB();
;                 PV1(3, w1); EX2(pc1, 14, w3.w); VR1(7); SB();
;                 lrun += sacc;
;                 PV1(4, w2); MASK_TILE(pn0, pn1, t + 1); SB();
;                 PV1(5, w2); SB();
;                 PV1(6, w3); SB();
;                 PV1(7, w3); rmn = rowmax32(pn0, pn1); if (!USE_NEGM) rmn -= mref; SB();
;     ...
;             if (hn) { STOREK(t & 1); STOREV((t + 1) & 1); }
.Lmla_p7_go:
	v_exp_f32_e32 v222, v82
	v_exp_f32_e32 v223, v83
	v_add_f32_e32 v164, 0, v222
	v_cvt_pk_bf16_f32 v206, v222, v223
	v_add_f32_e32 v164, v223, v164
	v_exp_f32_e32 v224, v84
	v_exp_f32_e32 v225, v85
	v_add_f32_e32 v164, v224, v164
	v_cvt_pk_bf16_f32 v207, v224, v225
	v_add_f32_e32 v164, v225, v164
	s_waitcnt lgkmcnt(4)
	v_mfma_f32_32x32x16_bf16 v[34:49], v[182:185], v[114:117], v[66:81]
	ds_read_b128 v[198:201], v229 offset:13376
	v_exp_f32_e32 v222, v86
	v_exp_f32_e32 v223, v87
	v_add_f32_e32 v164, v222, v164
	v_cvt_pk_bf16_f32 v208, v222, v223
	v_add_f32_e32 v164, v223, v164
	s_waitcnt lgkmcnt(4)
	v_mfma_f32_32x32x16_bf16 v[50:65], v[186:189], v[114:117], v[66:81]
	ds_read_b128 v[182:185], v229 offset:20032
	v_exp_f32_e32 v224, v88
	v_exp_f32_e32 v225, v89
	v_add_f32_e32 v164, v224, v164
	v_cvt_pk_bf16_f32 v209, v224, v225
	v_add_f32_e32 v164, v225, v164
	s_waitcnt lgkmcnt(3)
	v_mfma_f32_32x32x16_bf16 v[34:49], v[190:193], v[118:121], v[34:49]
	ds_read_b128 v[186:189], v229 offset:13408
	v_exp_f32_e32 v222, v90
	v_exp_f32_e32 v223, v91
	v_add_f32_e32 v164, v222, v164
	v_cvt_pk_bf16_f32 v210, v222, v223
	v_add_f32_e32 v164, v223, v164
	s_waitcnt lgkmcnt(3)
	v_mfma_f32_32x32x16_bf16 v[50:65], v[194:197], v[118:121], v[50:65]
	ds_read_b128 v[190:193], v229 offset:20064
	v_exp_f32_e32 v224, v92
	v_exp_f32_e32 v225, v93
	v_add_f32_e32 v164, v224, v164
	v_cvt_pk_bf16_f32 v211, v224, v225
	v_add_f32_e32 v164, v225, v164
	s_waitcnt lgkmcnt(3)
	v_mfma_f32_32x32x16_bf16 v[34:49], v[198:201], v[122:125], v[34:49]
	ds_read_b128 v[194:197], v229 offset:13440
	v_exp_f32_e32 v222, v94
	v_exp_f32_e32 v223, v95
	v_add_f32_e32 v164, v222, v164
	v_cvt_pk_bf16_f32 v212, v222, v223
	v_add_f32_e32 v164, v223, v164
	s_waitcnt lgkmcnt(3)
	v_mfma_f32_32x32x16_bf16 v[50:65], v[182:185], v[122:125], v[50:65]
	ds_read_b128 v[198:201], v229 offset:20096
	v_exp_f32_e32 v224, v96
	v_exp_f32_e32 v225, v97
	v_add_f32_e32 v164, v224, v164
	v_cvt_pk_bf16_f32 v213, v224, v225
	v_add_f32_e32 v164, v225, v164
	s_waitcnt lgkmcnt(3)
	v_mfma_f32_32x32x16_bf16 v[34:49], v[186:189], v[126:129], v[34:49]
	ds_read_b128 v[182:185], v229 offset:13472
	v_exp_f32_e32 v222, v98
	v_exp_f32_e32 v223, v99
	v_add_f32_e32 v164, v222, v164
	v_cvt_pk_bf16_f32 v214, v222, v223
	v_add_f32_e32 v164, v223, v164
	s_waitcnt lgkmcnt(3)
	v_mfma_f32_32x32x16_bf16 v[50:65], v[190:193], v[126:129], v[50:65]
	ds_read_b128 v[186:189], v229 offset:20128
	v_exp_f32_e32 v224, v100
	v_exp_f32_e32 v225, v101
	v_add_f32_e32 v164, v224, v164
	v_cvt_pk_bf16_f32 v215, v224, v225
	v_add_f32_e32 v164, v225, v164
	s_waitcnt lgkmcnt(3)
	v_mfma_f32_32x32x16_bf16 v[34:49], v[194:197], v[130:133], v[34:49]
	ds_read_b128 v[190:193], v181 offset:49152
	v_exp_f32_e32 v222, v102
	v_exp_f32_e32 v223, v103
	v_add_f32_e32 v164, v222, v164
	v_cvt_pk_bf16_f32 v216, v222, v223
	v_add_f32_e32 v164, v223, v164
	s_waitcnt lgkmcnt(3)
	v_mfma_f32_32x32x16_bf16 v[50:65], v[198:201], v[130:133], v[50:65]
	ds_read_b128 v[194:197], v181 offset:53760
	v_exp_f32_e32 v224, v104
	v_exp_f32_e32 v225, v105
	v_add_f32_e32 v164, v224, v164
	v_cvt_pk_bf16_f32 v217, v224, v225
	v_add_f32_e32 v164, v225, v164
	s_waitcnt lgkmcnt(3)
	v_mfma_f32_32x32x16_bf16 v[34:49], v[182:185], v[134:137], v[34:49]
	ds_read_b128 v[198:201], v181 offset:49184
	v_exp_f32_e32 v222, v106
	v_exp_f32_e32 v223, v107
	v_add_f32_e32 v164, v222, v164
	v_cvt_pk_bf16_f32 v218, v222, v223
	v_add_f32_e32 v164, v223, v164
	s_waitcnt lgkmcnt(3)
	v_mfma_f32_32x32x16_bf16 v[50:65], v[186:189], v[134:137], v[50:65]
	ds_read_b128 v[182:185], v181 offset:53792
	v_exp_f32_e32 v224, v108
	v_exp_f32_e32 v225, v109
	v_add_f32_e32 v164, v224, v164
	v_cvt_pk_bf16_f32 v219, v224, v225
	v_add_f32_e32 v164, v225, v164
	s_waitcnt lgkmcnt(3)
	v_mfma_f32_32x32x16_bf16 v[2:17], v[190:193], v[206:209], v[2:17]
	ds_read_b128 v[186:189], v181 offset:49216
	v_exp_f32_e32 v222, v110
	v_exp_f32_e32 v223, v111
	v_add_f32_e32 v164, v222, v164
	v_cvt_pk_bf16_f32 v220, v222, v223
	v_add_f32_e32 v164, v223, v164
	s_waitcnt lgkmcnt(3)
	v_mfma_f32_32x32x16_bf16 v[18:33], v[194:197], v[206:209], v[18:33]
	ds_read_b128 v[190:193], v181 offset:53824
	v_exp_f32_e32 v224, v112
	v_exp_f32_e32 v225, v113
	v_add_f32_e32 v164, v224, v164
	v_cvt_pk_bf16_f32 v221, v224, v225
	v_add_f32_e32 v164, v225, v164
	s_mov_b32 s13, s20
	s_mov_b32 s20, s19
	s_add_i32 s19, s19, 1
	s_cmp_eq_u32 s19, s9
	s_cselect_b32 s19, 0, s19
	s_waitcnt lgkmcnt(3)
	v_mfma_f32_32x32x16_bf16 v[2:17], v[198:201], v[210:213], v[2:17]
	ds_read_b128 v[194:197], v181 offset:49248
	v_max3_f32 v224, v34, v35, v36
	v_max3_f32 v225, v50, v51, v52
	v_max3_f32 v224, v224, v37, v38
	v_max3_f32 v225, v225, v53, v54
	s_waitcnt vmcnt(2)
	ds_write_b128 v172, v[150:153] offset:22528
	v_lshl_add_u32 v222, s19, 17, v178
	global_load_dwordx4 v[150:153], v222, s[52:53]
	s_waitcnt lgkmcnt(4)
	v_mfma_f32_32x32x16_bf16 v[18:33], v[182:185], v[210:213], v[18:33]
	ds_read_b128 v[198:201], v181 offset:53856
	ds_read_b128 v[182:185], v229 offset:26624
	v_max3_f32 v224, v224, v39, v40
	v_max3_f32 v225, v225, v55, v56
	v_max3_f32 v224, v224, v41, v42
	v_max3_f32 v225, v225, v57, v58
	s_and_b64 vcc, exec, s[2:3]
	s_cbranch_vccz .Lmla_p7_nope
	ds_write_b128 v176, v[160:163] offset:22656
	v_lshl_add_u32 v222, s19, 12, v179
	global_load_dwordx4 v[160:163], v222, s[62:63]
.Lmla_p7_nope:
	s_waitcnt lgkmcnt(5)
	v_mfma_f32_32x32x16_bf16 v[2:17], v[186:189], v[214:217], v[2:17]
	ds_read_b128 v[186:189], v229 offset:33280
	v_max3_f32 v224, v224, v43, v44
	v_max3_f32 v225, v225, v59, v60
	v_max3_f32 v224, v224, v45, v46
	v_max3_f32 v225, v225, v61, v62
	ds_write_b128 v173, v[202:205] offset:35840
	v_lshl_add_u32 v222, s13, 7, v168
	global_load_dwordx4 v[202:205], v222, s[56:57]
	s_waitcnt lgkmcnt(6)
	v_mfma_f32_32x32x16_bf16 v[18:33], v[190:193], v[214:217], v[18:33]
	ds_read_b128 v[190:193], v229 offset:26656
	v_max3_f32 v224, v224, v47, v48
	v_max3_f32 v225, v225, v63, v64
	v_max3_f32 v224, v224, v49, v65
	v_max_f32_e32 v224, v224, v225
	s_waitcnt lgkmcnt(6)
	v_mfma_f32_32x32x16_bf16 v[2:17], v[194:197], v[218:221], v[2:17]
	ds_read_b128 v[194:197], v229 offset:33312
	v_mov_b32_e32 v225, v224
	v_add_f32_e32 v1, v1, v164
	s_add_i32 s11, s11, 1
	v_permlane32_swap_b32_e32 v224, v225
	s_cmp_eq_u32 s9, s11
	v_max_f32_e32 v167, v224, v225
	v_cmp_lt_f32_e32 vcc, s66, v167
	s_waitcnt lgkmcnt(5)
	v_mfma_f32_32x32x16_bf16 v[18:33], v[198:201], v[218:221], v[18:33]
	s_waitcnt lgkmcnt(2)
	s_barrier
	s_cbranch_scc1 .Lmla_exit_p7

; template <int VAR>
; __device__ __forceinline__ void attn_phase(LAS unsigned char* lds, const AttnP P, int vcu, int G, int wave_s) {
;     ...
;                 if (ND0 == 6) {
;                     KR1(0); KR1(1); KR1(2); KR1(3); SB();
;                     QK1(0, negm); EX2(pc0, 0, w0.x); KR1(4); SB();
;                     QK1(1, negm); EX2(pc0, 2, w0.y); KR1(5); SB();
;                     QK1(2, pn0); EX2(pc0, 4, w0.z); KR1(6); SB();
;                     QK1(3, pn1); EX2(pc0, 6, w0.w); KR1(7); SB();
;                     QK1(4, pn0); EX2(pc0, 8, w1.x); KR1(8); SB();
;                     QK1(5, pn1); EX2(pc0, 10, w1.y); KR1(9); SB();
;                     QK1(6, pn0); EX2(pc0, 12, w1.z); KR1(10); SB();
;                     QK1(7, pn1); EX2(pc0, 14, w1.w); KR1(11); SB();
;                     QK1(8, pn0); EX2(pc1, 0, w2.x); VR1(0); SB();
;                     QK1(9, pn1); EX2(pc1, 2, w2.y); VR1(1); SB();
;                     QK1(10, pn0); EX2(pc1, 4, w2.z); VR1(2); SB();
;                     QK1(11, pn1); EX2(pc1, 6, w2.w); VR1(3); SB();
;                 } else {
;                     KR1(0); KR1(1); KR1(2); KR1(3); SB();
;                     QK1(0, negm); EX2(pc0, 0, w0.x); EX2(pc0, 2, w0.y); KR1(4); SB();
;                     QK1(1, negm); EX2(pc0, 4, w0.z); EX2(pc0, 6, w0.w); KR1(5); SB();
;                     QK1(2, pn0); EX2(pc0, 8, w1.x); EX2(pc0, 10, w1.y); KR1(6); SB();
;                     QK1(3, pn1); EX2(pc0, 12, w1.z); EX2(pc0, 14, w1.w); KR1(7); SB();
;                     QK1(4, pn0); EX2(pc1, 0, w2.x); VR1(0); SB();
;                     QK1(5, pn1); EX2(pc1, 2, w2.y); VR1(1); SB();
;                     QK1(6, pn0); EX2(pc1, 4, w2.z); VR1(2); SB();
;                     QK1(7, pn1); EX2(pc1, 6, w2.w); VR1(3); SB();
;                 }
;                 PV1(0, w0); EX2(pc1, 8, w3.x); VR1(4); SB();
;                 PV1(1, w0); EX2(pc1, 10, w3.y); VR1(5); SB();
;                 PV1(2, w1); EX2(pc1, 12, w3.z); VR1(6); SB();
;                 PV1(3, w1); EX2(pc1, 14, w3.w); VR1(7); SB();
;                 lrun += sacc;
;                 PV1(4, w2); MASK_TILE(pn0, pn1, t + 1); SB();
;                 PV1(5, w2); SB();
;                 PV1(6, w3); SB();
;                 PV1(7, w3); rmn = rowmax32(pn0, pn1); if (!USE_NEGM) rmn -= mref; SB();
;     ...
;             if (hn) { STOREK(t & 1); STOREV((t + 1) & 1); }
.Lmla_p8_go:
	v_exp_f32_e32 v222, v34
	v_exp_f32_e32 v223, v35
	v_add_f32_e32 v164, 0, v222
	v_cvt_pk_bf16_f32 v206, v222, v223
	v_add_f32_e32 v164, v223, v164
	v_exp_f32_e32 v224, v36
	v_exp_f32_e32 v225, v37
	v_add_f32_e32 v164, v224, v164
	v_cvt_pk_bf16_f32 v207, v224, v225
	v_add_f32_e32 v164, v225, v164
	s_waitcnt lgkmcnt(3)
	v_mfma_f32_32x32x16_bf16 v[82:97], v[182:185], v[114:117], v[66:81]
	ds_read_b128 v[198:201], v229 offset:26688
	v_exp_f32_e32 v222, v38
	v_exp_f32_e32 v223, v39
	v_add_f32_e32 v164, v222, v164
	v_cvt_pk_bf16_f32 v208, v222, v223
	v_add_f32_e32 v164, v223, v164
	s_waitcnt lgkmcnt(3)
	v_mfma_f32_32x32x16_bf16 v[98:113], v[186:189], v[114:117], v[66:81]
	ds_read_b128 v[182:185], v229 offset:33344
	v_exp_f32_e32 v224, v40
	v_exp_f32_e32 v225, v41
	v_add_f32_e32 v164, v224, v164
	v_cvt_pk_bf16_f32 v209, v224, v225
	v_add_f32_e32 v164, v225, v164
	s_waitcnt lgkmcnt(3)
	v_mfma_f32_32x32x16_bf16 v[82:97], v[190:193], v[118:121], v[82:97]
	ds_read_b128 v[186:189], v229 offset:26720
	v_exp_f32_e32 v222, v42
	v_exp_f32_e32 v223, v43
	v_add_f32_e32 v164, v222, v164
	v_cvt_pk_bf16_f32 v210, v222, v223
	v_add_f32_e32 v164, v223, v164
	s_waitcnt lgkmcnt(3)
	v_mfma_f32_32x32x16_bf16 v[98:113], v[194:197], v[118:121], v[98:113]
	ds_read_b128 v[190:193], v229 offset:33376
	v_exp_f32_e32 v224, v44
	v_exp_f32_e32 v225, v45
	v_add_f32_e32 v164, v224, v164
	v_cvt_pk_bf16_f32 v211, v224, v225
	v_add_f32_e32 v164, v225, v164
	s_waitcnt lgkmcnt(3)
	v_mfma_f32_32x32x16_bf16 v[82:97], v[198:201], v[122:125], v[82:97]
	ds_read_b128 v[194:197], v229 offset:26752
	v_exp_f32_e32 v222, v46
	v_exp_f32_e32 v223, v47
	v_add_f32_e32 v164, v222, v164
	v_cvt_pk_bf16_f32 v212, v222, v223
	v_add_f32_e32 v164, v223, v164
	s_waitcnt lgkmcnt(3)
	v_mfma_f32_32x32x16_bf16 v[98:113], v[182:185], v[122:125], v[98:113]
	ds_read_b128 v[198:201], v229 offset:33408
	v_exp_f32_e32 v224, v48
	v_exp_f32_e32 v225, v49
	v_add_f32_e32 v164, v224, v164
	v_cvt_pk_bf16_f32 v213, v224, v225
	v_add_f32_e32 v164, v225, v164
	s_waitcnt lgkmcnt(3)
	v_mfma_f32_32x32x16_bf16 v[82:97], v[186:189], v[126:129], v[82:97]
	ds_read_b128 v[182:185], v229 offset:26784
	v_exp_f32_e32 v222, v50
	v_exp_f32_e32 v223, v51
	v_add_f32_e32 v164, v222, v164
	v_cvt_pk_bf16_f32 v214, v222, v223
	v_add_f32_e32 v164, v223, v164
	s_waitcnt lgkmcnt(3)
	v_mfma_f32_32x32x16_bf16 v[98:113], v[190:193], v[126:129], v[98:113]
	ds_read_b128 v[186:189], v229 offset:33440
	v_exp_f32_e32 v224, v52
	v_exp_f32_e32 v225, v53
	v_add_f32_e32 v164, v224, v164
	v_cvt_pk_bf16_f32 v215, v224, v225
	v_add_f32_e32 v164, v225, v164
	s_waitcnt lgkmcnt(3)
	v_mfma_f32_32x32x16_bf16 v[82:97], v[194:197], v[130:133], v[82:97]
	ds_read_b128 v[190:193], v228 offset:13312
	v_exp_f32_e32 v222, v54
	v_exp_f32_e32 v223, v55
	v_add_f32_e32 v164, v222, v164
	v_cvt_pk_bf16_f32 v216, v222, v223
	v_add_f32_e32 v164, v223, v164
	s_waitcnt lgkmcnt(3)
	v_mfma_f32_32x32x16_bf16 v[98:113], v[198:201], v[130:133], v[98:113]
	ds_read_b128 v[194:197], v228 offset:17920
	v_exp_f32_e32 v224, v56
	v_exp_f32_e32 v225, v57
	v_add_f32_e32 v164, v224, v164
	v_cvt_pk_bf16_f32 v217, v224, v225
	v_add_f32_e32 v164, v225, v164
	s_waitcnt lgkmcnt(3)
	v_mfma_f32_32x32x16_bf16 v[82:97], v[182:185], v[134:137], v[82:97]
	ds_read_b128 v[198:201], v228 offset:13344
	v_exp_f32_e32 v222, v58
	v_exp_f32_e32 v223, v59
	v_add_f32_e32 v164, v222, v164
	v_cvt_pk_bf16_f32 v218, v222, v223
	v_add_f32_e32 v164, v223, v164
	s_waitcnt lgkmcnt(3)
	v_mfma_f32_32x32x16_bf16 v[98:113], v[186:189], v[134:137], v[98:113]
	ds_read_b128 v[182:185], v228 offset:17952
	v_exp_f32_e32 v224, v60
	v_exp_f32_e32 v225, v61
	v_add_f32_e32 v164, v224, v164
	v_cvt_pk_bf16_f32 v219, v224, v225
	v_add_f32_e32 v164, v225, v164
	s_waitcnt lgkmcnt(3)
	v_mfma_f32_32x32x16_bf16 v[2:17], v[190:193], v[206:209], v[2:17]
	ds_read_b128 v[186:189], v228 offset:13376
	v_exp_f32_e32 v222, v62
	v_exp_f32_e32 v223, v63
	v_add_f32_e32 v164, v222, v164
	v_cvt_pk_bf16_f32 v220, v222, v223
	v_add_f32_e32 v164, v223, v164
	s_waitcnt lgkmcnt(3)
	v_mfma_f32_32x32x16_bf16 v[18:33], v[194:197], v[206:209], v[18:33]
	ds_read_b128 v[190:193], v228 offset:17984
	v_exp_f32_e32 v224, v64
	v_exp_f32_e32 v225, v65
	v_add_f32_e32 v164, v224, v164
	v_cvt_pk_bf16_f32 v221, v224, v225
	v_add_f32_e32 v164, v225, v164
	s_mov_b32 s13, s20
	s_mov_b32 s20, s19
	s_add_i32 s19, s19, 1
	s_cmp_eq_u32 s19, s9
	s_cselect_b32 s19, 0, s19
	s_waitcnt lgkmcnt(3)
	v_mfma_f32_32x32x16_bf16 v[2:17], v[198:201], v[210:213], v[2:17]
	ds_read_b128 v[194:197], v228 offset:13408
	v_max3_f32 v224, v82, v83, v84
	v_max3_f32 v225, v98, v99, v100
	v_max3_f32 v224, v224, v85, v86
	v_max3_f32 v225, v225, v101, v102
	s_waitcnt vmcnt(2)
	ds_write_b128 v172, v[146:149] offset:45056
	v_lshl_add_u32 v222, s19, 17, v178
	global_load_dwordx4 v[146:149], v222, s[52:53]
	s_waitcnt lgkmcnt(4)
	v_mfma_f32_32x32x16_bf16 v[18:33], v[182:185], v[210:213], v[18:33]
	ds_read_b128 v[198:201], v228 offset:18016
	ds_read_b128 v[182:185], v174
	v_max3_f32 v224, v224, v87, v88
	v_max3_f32 v225, v225, v103, v104
	v_max3_f32 v224, v224, v89, v90
	v_max3_f32 v225, v225, v105, v106
	s_and_b64 vcc, exec, s[2:3]
	s_cbranch_vccz .Lmla_p8_nope
	ds_write_b128 v176, v[138:141] offset:45184
	v_lshl_add_u32 v222, s19, 12, v179
	global_load_dwordx4 v[138:141], v222, s[62:63]
.Lmla_p8_nope:
	s_waitcnt lgkmcnt(5)
	v_mfma_f32_32x32x16_bf16 v[2:17], v[186:189], v[214:217], v[2:17]
	ds_read_b128 v[186:189], v174 offset:6656
	v_max3_f32 v224, v224, v91, v92
	v_max3_f32 v225, v225, v107, v108
	v_max3_f32 v224, v224, v93, v94
	v_max3_f32 v225, v225, v109, v110
	v_add_u32_e32 v222, 0xb000, v173
	ds_write_b128 v222, v[142:145] offset:39936
	v_lshl_add_u32 v222, s13, 7, v168
	global_load_dwordx4 v[142:145], v222, s[56:57]
	s_waitcnt lgkmcnt(6)
	v_mfma_f32_32x32x16_bf16 v[18:33], v[190:193], v[214:217], v[18:33]
	ds_read_b128 v[190:193], v174 offset:32
	v_max3_f32 v224, v224, v95, v96
	v_max3_f32 v225, v225, v111, v112
	v_max3_f32 v224, v224, v97, v113
	v_max_f32_e32 v224, v224, v225
	s_waitcnt lgkmcnt(6)
	v_mfma_f32_32x32x16_bf16 v[2:17], v[194:197], v[218:221], v[2:17]
	ds_read_b128 v[194:197], v174 offset:6688
	v_mov_b32_e32 v225, v224
	v_add_f32_e32 v1, v1, v164
	s_add_i32 s11, s11, 1
	v_permlane32_swap_b32_e32 v224, v225
	s_cmp_eq_u32 s9, s11
	v_max_f32_e32 v167, v224, v225
	v_cmp_lt_f32_e32 vcc, s66, v167
	s_waitcnt lgkmcnt(5)
	v_mfma_f32_32x32x16_bf16 v[18:33], v[198:201], v[218:221], v[18:33]
	s_cbranch_scc1 .Lmla_exit_p8

; template <int VAR>
; __device__ __forceinline__ void attn_phase(LAS unsigned char* lds, const AttnP P, int vcu, int G, int wave_s) {
;     ...
;                 if (ND0 == 6) {
;                     KR1(0); KR1(1); KR1(2); KR1(3); SB();
;                     QK1(0, negm); EX2(pc0, 0, w0.x); KR1(4); SB();
;                     QK1(1, negm); EX2(pc0, 2, w0.y); KR1(5); SB();
;                     QK1(2, pn0); EX2(pc0, 4, w0.z); KR1(6); SB();
;                     QK1(3, pn1); EX2(pc0, 6, w0.w); KR1(7); SB();
;                     QK1(4, pn0); EX2(pc0, 8, w1.x); KR1(8); SB();
;                     QK1(5, pn1); EX2(pc0, 10, w1.y); KR1(9); SB();
;                     QK1(6, pn0); EX2(pc0, 12, w1.z); KR1(10); SB();
;                     QK1(7, pn1); EX2(pc0, 14, w1.w); KR1(11); SB();
;                     QK1(8, pn0); EX2(pc1, 0, w2.x); VR1(0); SB();
;                     QK1(9, pn1); EX2(pc1, 2, w2.y); VR1(1); SB();
;                     QK1(10, pn0); EX2(pc1, 4, w2.z); VR1(2); SB();
;                     QK1(11, pn1); EX2(pc1, 6, w2.w); VR1(3); SB();
;                 } else {
;                     KR1(0); KR1(1); KR1(2); KR1(3); SB();
;                     QK1(0, negm); EX2(pc0, 0, w0.x); EX2(pc0, 2, w0.y); KR1(4); SB();
;                     QK1(1, negm); EX2(pc0, 4, w0.z); EX2(pc0, 6, w0.w); KR1(5); SB();
;                     QK1(2, pn0); EX2(pc0, 8, w1.x); EX2(pc0, 10, w1.y); KR1(6); SB();
;                     QK1(3, pn1); EX2(pc0, 12, w1.z); EX2(pc0, 14, w1.w); KR1(7); SB();
;                     QK1(4, pn0); EX2(pc1, 0, w2.x); VR1(0); SB();
;                     QK1(5, pn1); EX2(pc1, 2, w2.y); VR1(1); SB();
;                     QK1(6, pn0); EX2(pc1, 4, w2.z); VR1(2); SB();
;                     QK1(7, pn1); EX2(pc1, 6, w2.w); VR1(3); SB();
;                 }
;                 PV1(0, w0); EX2(pc1, 8, w3.x); VR1(4); SB();
;                 PV1(1, w0); EX2(pc1, 10, w3.y); VR1(5); SB();
;                 PV1(2, w1); EX2(pc1, 12, w3.z); VR1(6); SB();
;                 PV1(3, w1); EX2(pc1, 14, w3.w); VR1(7); SB();
;                 lrun += sacc;
;                 PV1(4, w2); MASK_TILE(pn0, pn1, t + 1); SB();
;                 PV1(5, w2); SB();
;                 PV1(6, w3); SB();
;                 PV1(7, w3); rmn = rowmax32(pn0, pn1); if (!USE_NEGM) rmn -= mref; SB();
;     ...
;             if (hn) { STOREK(t & 1); STOREV((t + 1) & 1); }
.Lmla_p9_go:
	v_exp_f32_e32 v222, v82
	v_exp_f32_e32 v223, v83
	v_add_f32_e32 v164, 0, v222
	v_cvt_pk_bf16_f32 v206, v222, v223
	v_add_f32_e32 v164, v223, v164
	v_exp_f32_e32 v224, v84
	v_exp_f32_e32 v225, v85
	v_add_f32_e32 v164, v224, v164
	v_cvt_pk_bf16_f32 v207, v224, v225
	v_add_f32_e32 v164, v225, v164
	s_waitcnt lgkmcnt(4)
	v_mfma_f32_32x32x16_bf16 v[34:49], v[182:185], v[114:117], v[66:81]
	ds_read_b128 v[198:201], v174 offset:64
	v_exp_f32_e32 v222, v86
	v_exp_f32_e32 v223, v87
	v_add_f32_e32 v164, v222, v164
	v_cvt_pk_bf16_f32 v208, v222, v223
	v_add_f32_e32 v164, v223, v164
	s_waitcnt lgkmcnt(4)
	v_mfma_f32_32x32x16_bf16 v[50:65], v[186:189], v[114:117], v[66:81]
	ds_read_b128 v[182:185], v174 offset:6720
	v_exp_f32_e32 v224, v88
	v_exp_f32_e32 v225, v89
	v_add_f32_e32 v164, v224, v164
	v_cvt_pk_bf16_f32 v209, v224, v225
	v_add_f32_e32 v164, v225, v164
	s_waitcnt lgkmcnt(3)
	v_mfma_f32_32x32x16_bf16 v[34:49], v[190:193], v[118:121], v[34:49]
	ds_read_b128 v[186:189], v174 offset:96
	v_exp_f32_e32 v222, v90
	v_exp_f32_e32 v223, v91
	v_add_f32_e32 v164, v222, v164
	v_cvt_pk_bf16_f32 v210, v222, v223
	v_add_f32_e32 v164, v223, v164
	s_waitcnt lgkmcnt(3)
	v_mfma_f32_32x32x16_bf16 v[50:65], v[194:197], v[118:121], v[50:65]
	ds_read_b128 v[190:193], v174 offset:6752
	v_exp_f32_e32 v224, v92
	v_exp_f32_e32 v225, v93
	v_add_f32_e32 v164, v224, v164
	v_cvt_pk_bf16_f32 v211, v224, v225
	v_add_f32_e32 v164, v225, v164
	s_waitcnt lgkmcnt(3)
	v_mfma_f32_32x32x16_bf16 v[34:49], v[198:201], v[122:125], v[34:49]
	ds_read_b128 v[194:197], v174 offset:128
	v_exp_f32_e32 v222, v94
	v_exp_f32_e32 v223, v95
	v_add_f32_e32 v164, v222, v164
	v_cvt_pk_bf16_f32 v212, v222, v223
	v_add_f32_e32 v164, v223, v164
	s_waitcnt lgkmcnt(3)
	v_mfma_f32_32x32x16_bf16 v[50:65], v[182:185], v[122:125], v[50:65]
	ds_read_b128 v[198:201], v174 offset:6784
	v_exp_f32_e32 v224, v96
	v_exp_f32_e32 v225, v97
	v_add_f32_e32 v164, v224, v164
	v_cvt_pk_bf16_f32 v213, v224, v225
	v_add_f32_e32 v164, v225, v164
	s_waitcnt lgkmcnt(3)
	v_mfma_f32_32x32x16_bf16 v[34:49], v[186:189], v[126:129], v[34:49]
	ds_read_b128 v[182:185], v174 offset:160
	v_exp_f32_e32 v222, v98
	v_exp_f32_e32 v223, v99
	v_add_f32_e32 v164, v222, v164
	v_cvt_pk_bf16_f32 v214, v222, v223
	v_add_f32_e32 v164, v223, v164
	s_waitcnt lgkmcnt(3)
	v_mfma_f32_32x32x16_bf16 v[50:65], v[190:193], v[126:129], v[50:65]
	ds_read_b128 v[186:189], v174 offset:6816
	v_exp_f32_e32 v224, v100
	v_exp_f32_e32 v225, v101
	v_add_f32_e32 v164, v224, v164
	v_cvt_pk_bf16_f32 v215, v224, v225
	v_add_f32_e32 v164, v225, v164
	s_waitcnt lgkmcnt(3)
	v_mfma_f32_32x32x16_bf16 v[34:49], v[194:197], v[130:133], v[34:49]
	ds_read_b128 v[190:193], v228 offset:35840
	v_exp_f32_e32 v222, v102
	v_exp_f32_e32 v223, v103
	v_add_f32_e32 v164, v222, v164
	v_cvt_pk_bf16_f32 v216, v222, v223
	v_add_f32_e32 v164, v223, v164
	s_waitcnt lgkmcnt(3)
	v_mfma_f32_32x32x16_bf16 v[50:65], v[198:201], v[130:133], v[50:65]
	ds_read_b128 v[194:197], v228 offset:40448
	v_exp_f32_e32 v224, v104
	v_exp_f32_e32 v225, v105
	v_add_f32_e32 v164, v224, v164
	v_cvt_pk_bf16_f32 v217, v224, v225
	v_add_f32_e32 v164, v225, v164
	s_waitcnt lgkmcnt(3)
	v_mfma_f32_32x32x16_bf16 v[34:49], v[182:185], v[134:137], v[34:49]
	ds_read_b128 v[198:201], v228 offset:35872
	v_exp_f32_e32 v222, v106
	v_exp_f32_e32 v223, v107
	v_add_f32_e32 v164, v222, v164
	v_cvt_pk_bf16_f32 v218, v222, v223
	v_add_f32_e32 v164, v223, v164
	s_waitcnt lgkmcnt(3)
	v_mfma_f32_32x32x16_bf16 v[50:65], v[186:189], v[134:137], v[50:65]
	ds_read_b128 v[182:185], v228 offset:40480
	v_exp_f32_e32 v224, v108
	v_exp_f32_e32 v225, v109
	v_add_f32_e32 v164, v224, v164
	v_cvt_pk_bf16_f32 v219, v224, v225
	v_add_f32_e32 v164, v225, v164
	s_waitcnt lgkmcnt(3)
	v_mfma_f32_32x32x16_bf16 v[2:17], v[190:193], v[206:209], v[2:17]
	ds_read_b128 v[186:189], v228 offset:35904
	v_exp_f32_e32 v222, v110
	v_exp_f32_e32 v223, v111
	v_add_f32_e32 v164, v222, v164
	v_cvt_pk_bf16_f32 v220, v222, v223
	v_add_f32_e32 v164, v223, v164
	s_waitcnt lgkmcnt(3)
	v_mfma_f32_32x32x16_bf16 v[18:33], v[194:197], v[206:209], v[18:33]
	ds_read_b128 v[190:193], v228 offset:40512
	v_exp_f32_e32 v224, v112
	v_exp_f32_e32 v225, v113
	v_add_f32_e32 v164, v224, v164
	v_cvt_pk_bf16_f32 v221, v224, v225
	v_add_f32_e32 v164, v225, v164
	s_mov_b32 s13, s20
	s_mov_b32 s20, s19
	s_add_i32 s19, s19, 1
	s_cmp_eq_u32 s19, s9
	s_cselect_b32 s19, 0, s19
	s_waitcnt lgkmcnt(3)
	v_mfma_f32_32x32x16_bf16 v[2:17], v[198:201], v[210:213], v[2:17]
	ds_read_b128 v[194:197], v228 offset:35936
	v_max3_f32 v224, v34, v35, v36
	v_max3_f32 v225, v50, v51, v52
	v_max3_f32 v224, v224, v37, v38
	v_max3_f32 v225, v225, v53, v54
	s_waitcnt vmcnt(2)
	ds_write_b128 v172, v[150:153] offset:58368
	v_lshl_add_u32 v222, s19, 17, v178
	global_load_dwordx4 v[150:153], v222, s[52:53]
	s_waitcnt lgkmcnt(4)
	v_mfma_f32_32x32x16_bf16 v[18:33], v[182:185], v[210:213], v[18:33]
	ds_read_b128 v[198:201], v228 offset:40544
	ds_read_b128 v[182:185], v174 offset:22528
	v_max3_f32 v224, v224, v39, v40
	v_max3_f32 v225, v225, v55, v56
	v_max3_f32 v224, v224, v41, v42
	v_max3_f32 v225, v225, v57, v58
	s_and_b64 vcc, exec, s[2:3]
	s_cbranch_vccz .Lmla_p9_nope
	ds_write_b128 v176, v[160:163] offset:58496
	v_lshl_add_u32 v222, s19, 12, v179
	global_load_dwordx4 v[160:163], v222, s[62:63]
.Lmla_p9_nope:
	s_waitcnt lgkmcnt(5)
	v_mfma_f32_32x32x16_bf16 v[2:17], v[186:189], v[214:217], v[2:17]
	ds_read_b128 v[186:189], v174 offset:29184
	v_max3_f32 v224, v224, v43, v44
	v_max3_f32 v225, v225, v59, v60
	v_max3_f32 v224, v224, v45, v46
	v_max3_f32 v225, v225, v61, v62
	v_add_u32_e32 v222, 0xb000, v173
	ds_write_b128 v222, v[202:205] offset:49152
	v_lshl_add_u32 v222, s13, 7, v168
	global_load_dwordx4 v[202:205], v222, s[56:57]
	s_waitcnt lgkmcnt(6)
	v_mfma_f32_32x32x16_bf16 v[18:33], v[190:193], v[214:217], v[18:33]
	ds_read_b128 v[190:193], v174 offset:22560
	v_max3_f32 v224, v224, v47, v48
	v_max3_f32 v225, v225, v63, v64
	v_max3_f32 v224, v224, v49, v65
	v_max_f32_e32 v224, v224, v225
	s_waitcnt lgkmcnt(6)
	v_mfma_f32_32x32x16_bf16 v[2:17], v[194:197], v[218:221], v[2:17]
	ds_read_b128 v[194:197], v174 offset:29216
	v_mov_b32_e32 v225, v224
	v_add_f32_e32 v1, v1, v164
	s_add_i32 s11, s11, 1
	v_permlane32_swap_b32_e32 v224, v225
	s_cmp_eq_u32 s9, s11
	v_max_f32_e32 v167, v224, v225
	v_cmp_lt_f32_e32 vcc, s66, v167
	s_waitcnt lgkmcnt(5)
	v_mfma_f32_32x32x16_bf16 v[18:33], v[198:201], v[218:221], v[18:33]
	s_waitcnt lgkmcnt(2)
	s_barrier
	s_cbranch_scc1 .Lmla_exit_p9

; template <int VAR>
; __device__ __forceinline__ void attn_phase(LAS unsigned char* lds, const AttnP P, int vcu, int G, int wave_s) {
;     ...
;                 if (ND0 == 6) {
;                     KR1(0); KR1(1); KR1(2); KR1(3); SB();
;                     QK1(0, negm); EX2(pc0, 0, w0.x); KR1(4); SB();
;                     QK1(1, negm); EX2(pc0, 2, w0.y); KR1(5); SB();
;                     QK1(2, pn0); EX2(pc0, 4, w0.z); KR1(6); SB();
;                     QK1(3, pn1); EX2(pc0, 6, w0.w); KR1(7); SB();
;                     QK1(4, pn0); EX2(pc0, 8, w1.x); KR1(8); SB();
;                     QK1(5, pn1); EX2(pc0, 10, w1.y); KR1(9); SB();
;                     QK1(6, pn0); EX2(pc0, 12, w1.z); KR1(10); SB();
;                     QK1(7, pn1); EX2(pc0, 14, w1.w); KR1(11); SB();
;                     QK1(8, pn0); EX2(pc1, 0, w2.x); VR1(0); SB();
;                     QK1(9, pn1); EX2(pc1, 2, w2.y); VR1(1); SB();
;                     QK1(10, pn0); EX2(pc1, 4, w2.z); VR1(2); SB();
;                     QK1(11, pn1); EX2(pc1, 6, w2.w); VR1(3); SB();
;                 } else {
;                     KR1(0); KR1(1); KR1(2); KR1(3); SB();
;                     QK1(0, negm); EX2(pc0, 0, w0.x); EX2(pc0, 2, w0.y); KR1(4); SB();
;                     QK1(1, negm); EX2(pc0, 4, w0.z); EX2(pc0, 6, w0.w); KR1(5); SB();
;                     QK1(2, pn0); EX2(pc0, 8, w1.x); EX2(pc0, 10, w1.y); KR1(6); SB();
;                     QK1(3, pn1); EX2(pc0, 12, w1.z); EX2(pc0, 14, w1.w); KR1(7); SB();
;                     QK1(4, pn0); EX2(pc1, 0, w2.x); VR1(0); SB();
;                     QK1(5, pn1); EX2(pc1, 2, w2.y); VR1(1); SB();
;                     QK1(6, pn0); EX2(pc1, 4, w2.z); VR1(2); SB();
;                     QK1(7, pn1); EX2(pc1, 6, w2.w); VR1(3); SB();
;                 }
;                 PV1(0, w0); EX2(pc1, 8, w3.x); VR1(4); SB();
;                 PV1(1, w0); EX2(pc1, 10, w3.y); VR1(5); SB();
;                 PV1(2, w1); EX2(pc1, 12, w3.z); VR1(6); SB();
;                 PV1(3, w1); EX2(pc1, 14, w3.w); VR1(7); SB();
;                 lrun += sacc;
;                 PV1(4, w2); MASK_TILE(pn0, pn1, t + 1); SB();
;                 PV1(5, w2); SB();
;                 PV1(6, w3); SB();
;                 PV1(7, w3); rmn = rowmax32(pn0, pn1); if (!USE_NEGM) rmn -= mref; SB();
;     ...
;             if (hn) { STOREK(t & 1); STOREV((t + 1) & 1); }
.Lmla_p10_go:
	v_exp_f32_e32 v222, v34
	v_exp_f32_e32 v223, v35
	v_add_f32_e32 v164, 0, v222
	v_cvt_pk_bf16_f32 v206, v222, v223
	v_add_f32_e32 v164, v223, v164
	v_exp_f32_e32 v224, v36
	v_exp_f32_e32 v225, v37
	v_add_f32_e32 v164, v224, v164
	v_cvt_pk_bf16_f32 v207, v224, v225
	v_add_f32_e32 v164, v225, v164
	s_waitcnt lgkmcnt(3)
	v_mfma_f32_32x32x16_bf16 v[82:97], v[182:185], v[114:117], v[66:81]
	ds_read_b128 v[198:201], v174 offset:22592
	v_exp_f32_e32 v222, v38
	v_exp_f32_e32 v223, v39
	v_add_f32_e32 v164, v222, v164
	v_cvt_pk_bf16_f32 v208, v222, v223
	v_add_f32_e32 v164, v223, v164
	s_waitcnt lgkmcnt(3)
	v_mfma_f32_32x32x16_bf16 v[98:113], v[186:189], v[114:117], v[66:81]
	ds_read_b128 v[182:185], v174 offset:29248
	v_exp_f32_e32 v224, v40
	v_exp_f32_e32 v225, v41
	v_add_f32_e32 v164, v224, v164
	v_cvt_pk_bf16_f32 v209, v224, v225
	v_add_f32_e32 v164, v225, v164
	s_waitcnt lgkmcnt(3)
	v_mfma_f32_32x32x16_bf16 v[82:97], v[190:193], v[118:121], v[82:97]
	ds_read_b128 v[186:189], v174 offset:22624
	v_exp_f32_e32 v222, v42
	v_exp_f32_e32 v223, v43
	v_add_f32_e32 v164, v222, v164
	v_cvt_pk_bf16_f32 v210, v222, v223
	v_add_f32_e32 v164, v223, v164
	s_waitcnt lgkmcnt(3)
	v_mfma_f32_32x32x16_bf16 v[98:113], v[194:197], v[118:121], v[98:113]
	ds_read_b128 v[190:193], v174 offset:29280
	v_exp_f32_e32 v224, v44
	v_exp_f32_e32 v225, v45
	v_add_f32_e32 v164, v224, v164
	v_cvt_pk_bf16_f32 v211, v224, v225
	v_add_f32_e32 v164, v225, v164
	s_waitcnt lgkmcnt(3)
	v_mfma_f32_32x32x16_bf16 v[82:97], v[198:201], v[122:125], v[82:97]
	ds_read_b128 v[194:197], v174 offset:22656
	v_exp_f32_e32 v222, v46
	v_exp_f32_e32 v223, v47
	v_add_f32_e32 v164, v222, v164
	v_cvt_pk_bf16_f32 v212, v222, v223
	v_add_f32_e32 v164, v223, v164
	s_waitcnt lgkmcnt(3)
	v_mfma_f32_32x32x16_bf16 v[98:113], v[182:185], v[122:125], v[98:113]
	ds_read_b128 v[198:201], v174 offset:29312
	v_exp_f32_e32 v224, v48
	v_exp_f32_e32 v225, v49
	v_add_f32_e32 v164, v224, v164
	v_cvt_pk_bf16_f32 v213, v224, v225
	v_add_f32_e32 v164, v225, v164
	s_waitcnt lgkmcnt(3)
	v_mfma_f32_32x32x16_bf16 v[82:97], v[186:189], v[126:129], v[82:97]
	ds_read_b128 v[182:185], v174 offset:22688
	v_exp_f32_e32 v222, v50
	v_exp_f32_e32 v223, v51
	v_add_f32_e32 v164, v222, v164
	v_cvt_pk_bf16_f32 v214, v222, v223
	v_add_f32_e32 v164, v223, v164
	s_waitcnt lgkmcnt(3)
	v_mfma_f32_32x32x16_bf16 v[98:113], v[190:193], v[126:129], v[98:113]
	ds_read_b128 v[186:189], v174 offset:29344
	v_exp_f32_e32 v224, v52
	v_exp_f32_e32 v225, v53
	v_add_f32_e32 v164, v224, v164
	v_cvt_pk_bf16_f32 v215, v224, v225
	v_add_f32_e32 v164, v225, v164
	s_waitcnt lgkmcnt(3)
	v_mfma_f32_32x32x16_bf16 v[82:97], v[194:197], v[130:133], v[82:97]
	ds_read_b128 v[190:193], v181 offset:39936
	v_exp_f32_e32 v222, v54
	v_exp_f32_e32 v223, v55
	v_add_f32_e32 v164, v222, v164
	v_cvt_pk_bf16_f32 v216, v222, v223
	v_add_f32_e32 v164, v223, v164
	s_waitcnt lgkmcnt(3)
	v_mfma_f32_32x32x16_bf16 v[98:113], v[198:201], v[130:133], v[98:113]
	ds_read_b128 v[194:197], v181 offset:44544
	v_exp_f32_e32 v224, v56
	v_exp_f32_e32 v225, v57
	v_add_f32_e32 v164, v224, v164
	v_cvt_pk_bf16_f32 v217, v224, v225
	v_add_f32_e32 v164, v225, v164
	s_waitcnt lgkmcnt(3)
	v_mfma_f32_32x32x16_bf16 v[82:97], v[182:185], v[134:137], v[82:97]
	ds_read_b128 v[198:201], v181 offset:39968
	v_exp_f32_e32 v222, v58
	v_exp_f32_e32 v223, v59
	v_add_f32_e32 v164, v222, v164
	v_cvt_pk_bf16_f32 v218, v222, v223
	v_add_f32_e32 v164, v223, v164
	s_waitcnt lgkmcnt(3)
	v_mfma_f32_32x32x16_bf16 v[98:113], v[186:189], v[134:137], v[98:113]
	ds_read_b128 v[182:185], v181 offset:44576
	v_exp_f32_e32 v224, v60
	v_exp_f32_e32 v225, v61
	v_add_f32_e32 v164, v224, v164
	v_cvt_pk_bf16_f32 v219, v224, v225
	v_add_f32_e32 v164, v225, v164
	s_waitcnt lgkmcnt(3)
	v_mfma_f32_32x32x16_bf16 v[2:17], v[190:193], v[206:209], v[2:17]
	ds_read_b128 v[186:189], v181 offset:40000
	v_exp_f32_e32 v222, v62
	v_exp_f32_e32 v223, v63
	v_add_f32_e32 v164, v222, v164
	v_cvt_pk_bf16_f32 v220, v222, v223
	v_add_f32_e32 v164, v223, v164
	s_waitcnt lgkmcnt(3)
	v_mfma_f32_32x32x16_bf16 v[18:33], v[194:197], v[206:209], v[18:33]
	ds_read_b128 v[190:193], v181 offset:44608
	v_exp_f32_e32 v224, v64
	v_exp_f32_e32 v225, v65
	v_add_f32_e32 v164, v224, v164
	v_cvt_pk_bf16_f32 v221, v224, v225
	v_add_f32_e32 v164, v225, v164
	s_mov_b32 s13, s20
	s_mov_b32 s20, s19
	s_add_i32 s19, s19, 1
	s_cmp_eq_u32 s19, s9
	s_cselect_b32 s19, 0, s19
	s_waitcnt lgkmcnt(3)
	v_mfma_f32_32x32x16_bf16 v[2:17], v[198:201], v[210:213], v[2:17]
	ds_read_b128 v[194:197], v181 offset:40032
	v_max3_f32 v224, v82, v83, v84
	v_max3_f32 v225, v98, v99, v100
	v_max3_f32 v224, v224, v85, v86
	v_max3_f32 v225, v225, v101, v102
	s_waitcnt vmcnt(2)
	v_add_u32_e32 v222, 0xb000, v172
	ds_write_b128 v222, v[146:149] offset:26624
	v_lshl_add_u32 v222, s19, 17, v178
	global_load_dwordx4 v[146:149], v222, s[52:53]
	s_waitcnt lgkmcnt(4)
	v_mfma_f32_32x32x16_bf16 v[18:33], v[182:185], v[210:213], v[18:33]
	ds_read_b128 v[198:201], v181 offset:44640
	ds_read_b128 v[182:185], v174 offset:45056
	v_max3_f32 v224, v224, v87, v88
	v_max3_f32 v225, v225, v103, v104
	v_max3_f32 v224, v224, v89, v90
	v_max3_f32 v225, v225, v105, v106
	s_and_b64 vcc, exec, s[2:3]
	s_cbranch_vccz .Lmla_p10_nope
	v_add_u32_e32 v222, 0xb000, v176
	ds_write_b128 v222, v[138:141] offset:26752
	v_lshl_add_u32 v222, s19, 12, v179
	global_load_dwordx4 v[138:141], v222, s[62:63]
.Lmla_p10_nope:
	s_waitcnt lgkmcnt(5)
	v_mfma_f32_32x32x16_bf16 v[2:17], v[186:189], v[214:217], v[2:17]
	ds_read_b128 v[186:189], v174 offset:51712
	v_max3_f32 v224, v224, v91, v92
	v_max3_f32 v225, v225, v107, v108
	v_max3_f32 v224, v224, v93, v94
	v_max3_f32 v225, v225, v109, v110
	ds_write_b128 v173, v[142:145] offset:13312
	v_lshl_add_u32 v222, s13, 7, v168
	global_load_dwordx4 v[142:145], v222, s[56:57]
	s_waitcnt lgkmcnt(6)
	v_mfma_f32_32x32x16_bf16 v[18:33], v[190:193], v[214:217], v[18:33]
	ds_read_b128 v[190:193], v174 offset:45088
	v_max3_f32 v224, v224, v95, v96
	v_max3_f32 v225, v225, v111, v112
	v_max3_f32 v224, v224, v97, v113
	v_max_f32_e32 v224, v224, v225
	s_waitcnt lgkmcnt(6)
	v_mfma_f32_32x32x16_bf16 v[2:17], v[194:197], v[218:221], v[2:17]
	ds_read_b128 v[194:197], v174 offset:51744
	v_mov_b32_e32 v225, v224
	v_add_f32_e32 v1, v1, v164
	s_add_i32 s11, s11, 1
	v_permlane32_swap_b32_e32 v224, v225
	s_cmp_eq_u32 s9, s11
	v_max_f32_e32 v167, v224, v225
	v_cmp_lt_f32_e32 vcc, s66, v167
	s_waitcnt lgkmcnt(5)
	v_mfma_f32_32x32x16_bf16 v[18:33], v[198:201], v[218:221], v[18:33]
	s_cbranch_scc1 .Lmla_exit_p10

; template <int VAR>
; __device__ __forceinline__ void attn_phase(LAS unsigned char* lds, const AttnP P, int vcu, int G, int wave_s) {
;     ...
;                 if (ND0 == 6) {
;                     KR1(0); KR1(1); KR1(2); KR1(3); SB();
;                     QK1(0, negm); EX2(pc0, 0, w0.x); KR1(4); SB();
;                     QK1(1, negm); EX2(pc0, 2, w0.y); KR1(5); SB();
;                     QK1(2, pn0); EX2(pc0, 4, w0.z); KR1(6); SB();
;                     QK1(3, pn1); EX2(pc0, 6, w0.w); KR1(7); SB();
;                     QK1(4, pn0); EX2(pc0, 8, w1.x); KR1(8); SB();
;                     QK1(5, pn1); EX2(pc0, 10, w1.y); KR1(9); SB();
;                     QK1(6, pn0); EX2(pc0, 12, w1.z); KR1(10); SB();
;                     QK1(7, pn1); EX2(pc0, 14, w1.w); KR1(11); SB();
;                     QK1(8, pn0); EX2(pc1, 0, w2.x); VR1(0); SB();
;                     QK1(9, pn1); EX2(pc1, 2, w2.y); VR1(1); SB();
;                     QK1(10, pn0); EX2(pc1, 4, w2.z); VR1(2); SB();
;                     QK1(11, pn1); EX2(pc1, 6, w2.w); VR1(3); SB();
;                 } else {
;                     KR1(0); KR1(1); KR1(2); KR1(3); SB();
;                     QK1(0, negm); EX2(pc0, 0, w0.x); EX2(pc0, 2, w0.y); KR1(4); SB();
;                     QK1(1, negm); EX2(pc0, 4, w0.z); EX2(pc0, 6, w0.w); KR1(5); SB();
;                     QK1(2, pn0); EX2(pc0, 8, w1.x); EX2(pc0, 10, w1.y); KR1(6); SB();
;                     QK1(3, pn1); EX2(pc0, 12, w1.z); EX2(pc0, 14, w1.w); KR1(7); SB();
;                     QK1(4, pn0); EX2(pc1, 0, w2.x); VR1(0); SB();
;                     QK1(5, pn1); EX2(pc1, 2, w2.y); VR1(1); SB();
;                     QK1(6, pn0); EX2(pc1, 4, w2.z); VR1(2); SB();
;                     QK1(7, pn1); EX2(pc1, 6, w2.w); VR1(3); SB();
;                 }
;                 PV1(0, w0); EX2(pc1, 8, w3.x); VR1(4); SB();
;                 PV1(1, w0); EX2(pc1, 10, w3.y); VR1(5); SB();
;                 PV1(2, w1); EX2(pc1, 12, w3.z); VR1(6); SB();
;                 PV1(3, w1); EX2(pc1, 14, w3.w); VR1(7); SB();
;                 lrun += sacc;
;                 PV1(4, w2); MASK_TILE(pn0, pn1, t + 1); SB();
;                 PV1(5, w2); SB();
;                 PV1(6, w3); SB();
;                 PV1(7, w3); rmn = rowmax32(pn0, pn1); if (!USE_NEGM) rmn -= mref; SB();
;     ...
;             if (hn) { STOREK(t & 1); STOREV((t + 1) & 1); }
.Lmla_p11_go:
	v_exp_f32_e32 v222, v82
	v_exp_f32_e32 v223, v83
	v_add_f32_e32 v164, 0, v222
	v_cvt_pk_bf16_f32 v206, v222, v223
	v_add_f32_e32 v164, v223, v164
	v_exp_f32_e32 v224, v84
	v_exp_f32_e32 v225, v85
	v_add_f32_e32 v164, v224, v164
	v_cvt_pk_bf16_f32 v207, v224, v225
	v_add_f32_e32 v164, v225, v164
	s_waitcnt lgkmcnt(4)
	v_mfma_f32_32x32x16_bf16 v[34:49], v[182:185], v[114:117], v[66:81]
	ds_read_b128 v[198:201], v174 offset:45120
	v_exp_f32_e32 v222, v86
	v_exp_f32_e32 v223, v87
	v_add_f32_e32 v164, v222, v164
	v_cvt_pk_bf16_f32 v208, v222, v223
	v_add_f32_e32 v164, v223, v164
	s_waitcnt lgkmcnt(4)
	v_mfma_f32_32x32x16_bf16 v[50:65], v[186:189], v[114:117], v[66:81]
	ds_read_b128 v[182:185], v174 offset:51776
	v_exp_f32_e32 v224, v88
	v_exp_f32_e32 v225, v89
	v_add_f32_e32 v164, v224, v164
	v_cvt_pk_bf16_f32 v209, v224, v225
	v_add_f32_e32 v164, v225, v164
	s_waitcnt lgkmcnt(3)
	v_mfma_f32_32x32x16_bf16 v[34:49], v[190:193], v[118:121], v[34:49]
	ds_read_b128 v[186:189], v174 offset:45152
	v_exp_f32_e32 v222, v90
	v_exp_f32_e32 v223, v91
	v_add_f32_e32 v164, v222, v164
	v_cvt_pk_bf16_f32 v210, v222, v223
	v_add_f32_e32 v164, v223, v164
	s_waitcnt lgkmcnt(3)
	v_mfma_f32_32x32x16_bf16 v[50:65], v[194:197], v[118:121], v[50:65]
	ds_read_b128 v[190:193], v174 offset:51808
	v_exp_f32_e32 v224, v92
	v_exp_f32_e32 v225, v93
	v_add_f32_e32 v164, v224, v164
	v_cvt_pk_bf16_f32 v211, v224, v225
	v_add_f32_e32 v164, v225, v164
	s_waitcnt lgkmcnt(3)
	v_mfma_f32_32x32x16_bf16 v[34:49], v[198:201], v[122:125], v[34:49]
	ds_read_b128 v[194:197], v174 offset:45184
	v_exp_f32_e32 v222, v94
	v_exp_f32_e32 v223, v95
	v_add_f32_e32 v164, v222, v164
	v_cvt_pk_bf16_f32 v212, v222, v223
	v_add_f32_e32 v164, v223, v164
	s_waitcnt lgkmcnt(3)
	v_mfma_f32_32x32x16_bf16 v[50:65], v[182:185], v[122:125], v[50:65]
	ds_read_b128 v[198:201], v174 offset:51840
	v_exp_f32_e32 v224, v96
	v_exp_f32_e32 v225, v97
	v_add_f32_e32 v164, v224, v164
	v_cvt_pk_bf16_f32 v213, v224, v225
	v_add_f32_e32 v164, v225, v164
	s_waitcnt lgkmcnt(3)
	v_mfma_f32_32x32x16_bf16 v[34:49], v[186:189], v[126:129], v[34:49]
	ds_read_b128 v[182:185], v174 offset:45216
	v_exp_f32_e32 v222, v98
	v_exp_f32_e32 v223, v99
	v_add_f32_e32 v164, v222, v164
	v_cvt_pk_bf16_f32 v214, v222, v223
	v_add_f32_e32 v164, v223, v164
	s_waitcnt lgkmcnt(3)
	v_mfma_f32_32x32x16_bf16 v[50:65], v[190:193], v[126:129], v[50:65]
	ds_read_b128 v[186:189], v174 offset:51872
	v_exp_f32_e32 v224, v100
	v_exp_f32_e32 v225, v101
	v_add_f32_e32 v164, v224, v164
	v_cvt_pk_bf16_f32 v215, v224, v225
	v_add_f32_e32 v164, v225, v164
	s_waitcnt lgkmcnt(3)
	v_mfma_f32_32x32x16_bf16 v[34:49], v[194:197], v[130:133], v[34:49]
	ds_read_b128 v[190:193], v181 offset:49152
	v_exp_f32_e32 v222, v102
	v_exp_f32_e32 v223, v103
	v_add_f32_e32 v164, v222, v164
	v_cvt_pk_bf16_f32 v216, v222, v223
	v_add_f32_e32 v164, v223, v164
	s_waitcnt lgkmcnt(3)
	v_mfma_f32_32x32x16_bf16 v[50:65], v[198:201], v[130:133], v[50:65]
	ds_read_b128 v[194:197], v181 offset:53760
	v_exp_f32_e32 v224, v104
	v_exp_f32_e32 v225, v105
	v_add_f32_e32 v164, v224, v164
	v_cvt_pk_bf16_f32 v217, v224, v225
	v_add_f32_e32 v164, v225, v164
	s_waitcnt lgkmcnt(3)
	v_mfma_f32_32x32x16_bf16 v[34:49], v[182:185], v[134:137], v[34:49]
	ds_read_b128 v[198:201], v181 offset:49184
	v_exp_f32_e32 v222, v106
	v_exp_f32_e32 v223, v107
	v_add_f32_e32 v164, v222, v164
	v_cvt_pk_bf16_f32 v218, v222, v223
	v_add_f32_e32 v164, v223, v164
	s_waitcnt lgkmcnt(3)
	v_mfma_f32_32x32x16_bf16 v[50:65], v[186:189], v[134:137], v[50:65]
	ds_read_b128 v[182:185], v181 offset:53792
	v_exp_f32_e32 v224, v108
	v_exp_f32_e32 v225, v109
	v_add_f32_e32 v164, v224, v164
	v_cvt_pk_bf16_f32 v219, v224, v225
	v_add_f32_e32 v164, v225, v164
	s_waitcnt lgkmcnt(3)
	v_mfma_f32_32x32x16_bf16 v[2:17], v[190:193], v[206:209], v[2:17]
	ds_read_b128 v[186:189], v181 offset:49216
	v_exp_f32_e32 v222, v110
	v_exp_f32_e32 v223, v111
	v_add_f32_e32 v164, v222, v164
	v_cvt_pk_bf16_f32 v220, v222, v223
	v_add_f32_e32 v164, v223, v164
	s_waitcnt lgkmcnt(3)
	v_mfma_f32_32x32x16_bf16 v[18:33], v[194:197], v[206:209], v[18:33]
	ds_read_b128 v[190:193], v181 offset:53824
	v_exp_f32_e32 v224, v112
	v_exp_f32_e32 v225, v113
	v_add_f32_e32 v164, v224, v164
	v_cvt_pk_bf16_f32 v221, v224, v225
	v_add_f32_e32 v164, v225, v164
	s_mov_b32 s13, s20
	s_mov_b32 s20, s19
	s_add_i32 s19, s19, 1
	s_cmp_eq_u32 s19, s9
	s_cselect_b32 s19, 0, s19
	s_waitcnt lgkmcnt(3)
	v_mfma_f32_32x32x16_bf16 v[2:17], v[198:201], v[210:213], v[2:17]
	ds_read_b128 v[194:197], v181 offset:49248
	v_max3_f32 v224, v34, v35, v36
	v_max3_f32 v225, v50, v51, v52
	v_max3_f32 v224, v224, v37, v38
	v_max3_f32 v225, v225, v53, v54
	s_waitcnt vmcnt(2)
	ds_write_b128 v172, v[150:153]
	v_lshl_add_u32 v222, s19, 17, v178
	global_load_dwordx4 v[150:153], v222, s[52:53]
	s_waitcnt lgkmcnt(4)
	v_mfma_f32_32x32x16_bf16 v[18:33], v[182:185], v[210:213], v[18:33]
	ds_read_b128 v[198:201], v181 offset:53856
	ds_read_b128 v[182:185], v229 offset:13312
	v_max3_f32 v224, v224, v39, v40
	v_max3_f32 v225, v225, v55, v56
	v_max3_f32 v224, v224, v41, v42
	v_max3_f32 v225, v225, v57, v58
	s_and_b64 vcc, exec, s[2:3]
	s_cbranch_vccz .Lmla_p11_nope
	ds_write_b128 v176, v[160:163] offset:128
	v_lshl_add_u32 v222, s19, 12, v179
	global_load_dwordx4 v[160:163], v222, s[62:63]
.Lmla_p11_nope:
	s_waitcnt lgkmcnt(5)
	v_mfma_f32_32x32x16_bf16 v[2:17], v[186:189], v[214:217], v[2:17]
	ds_read_b128 v[186:189], v229 offset:19968
	v_max3_f32 v224, v224, v43, v44
	v_max3_f32 v225, v225, v59, v60
	v_max3_f32 v224, v224, v45, v46
	v_max3_f32 v225, v225, v61, v62
	ds_write_b128 v173, v[202:205] offset:35840
	v_lshl_add_u32 v222, s13, 7, v168
	global_load_dwordx4 v[202:205], v222, s[56:57]
	s_waitcnt lgkmcnt(6)
	v_mfma_f32_32x32x16_bf16 v[18:33], v[190:193], v[214:217], v[18:33]
	ds_read_b128 v[190:193], v229 offset:13344
	v_max3_f32 v224, v224, v47, v48
	v_max3_f32 v225, v225, v63, v64
	v_max3_f32 v224, v224, v49, v65
	v_max_f32_e32 v224, v224, v225
	s_waitcnt lgkmcnt(6)
	v_mfma_f32_32x32x16_bf16 v[2:17], v[194:197], v[218:221], v[2:17]
	ds_read_b128 v[194:197], v229 offset:20000
	v_mov_b32_e32 v225, v224
	v_add_f32_e32 v1, v1, v164
	s_add_i32 s11, s11, 1
	v_permlane32_swap_b32_e32 v224, v225
	s_cmp_eq_u32 s9, s11
	v_max_f32_e32 v167, v224, v225
	v_cmp_lt_f32_e32 vcc, s66, v167
	s_waitcnt lgkmcnt(5)
	v_mfma_f32_32x32x16_bf16 v[18:33], v[198:201], v[218:221], v[18:33]
	s_waitcnt lgkmcnt(2)
	s_barrier
	s_cbranch_scc1 .Lmla_exit_p11

; template <int VAR>
; __device__ __forceinline__ void attn_phase(LAS unsigned char* lds, const AttnP P, int vcu, int G, int wave_s) {
;     ...
;                 if (ND0 == 6) {
;                     KR1(0); KR1(1); KR1(2); KR1(3); SB();
;                     QK1(0, negm); EX2(pc0, 0, w0.x); KR1(4); SB();
;                     QK1(1, negm); EX2(pc0, 2, w0.y); KR1(5); SB();
;                     QK1(2, pn0); EX2(pc0, 4, w0.z); KR1(6); SB();
;                     QK1(3, pn1); EX2(pc0, 6, w0.w); KR1(7); SB();
;                     QK1(4, pn0); EX2(pc0, 8, w1.x); KR1(8); SB();
;                     QK1(5, pn1); EX2(pc0, 10, w1.y); KR1(9); SB();
;                     QK1(6, pn0); EX2(pc0, 12, w1.z); KR1(10); SB();
;                     QK1(7, pn1); EX2(pc0, 14, w1.w); KR1(11); SB();
;                     QK1(8, pn0); EX2(pc1, 0, w2.x); VR1(0); SB();
;                     QK1(9, pn1); EX2(pc1, 2, w2.y); VR1(1); SB();
;                     QK1(10, pn0); EX2(pc1, 4, w2.z); VR1(2); SB();
;                     QK1(11, pn1); EX2(pc1, 6, w2.w); VR1(3); SB();
;                 } else {
;                     KR1(0); KR1(1); KR1(2); KR1(3); SB();
;                     QK1(0, negm); EX2(pc0, 0, w0.x); EX2(pc0, 2, w0.y); KR1(4); SB();
;                     QK1(1, negm); EX2(pc0, 4, w0.z); EX2(pc0, 6, w0.w); KR1(5); SB();
;                     QK1(2, pn0); EX2(pc0, 8, w1.x); EX2(pc0, 10, w1.y); KR1(6); SB();
;                     QK1(3, pn1); EX2(pc0, 12, w1.z); EX2(pc0, 14, w1.w); KR1(7); SB();
;                     QK1(4, pn0); EX2(pc1, 0, w2.x); VR1(0); SB();
;                     QK1(5, pn1); EX2(pc1, 2, w2.y); VR1(1); SB();
;                     QK1(6, pn0); EX2(pc1, 4, w2.z); VR1(2); SB();
;                     QK1(7, pn1); EX2(pc1, 6, w2.w); VR1(3); SB();
;                 }
;                 PV1(0, w0); EX2(pc1, 8, w3.x); VR1(4); SB();
;                 PV1(1, w0); EX2(pc1, 10, w3.y); VR1(5); SB();
;                 PV1(2, w1); EX2(pc1, 12, w3.z); VR1(6); SB();
;                 PV1(3, w1); EX2(pc1, 14, w3.w); VR1(7); SB();
;                 lrun += sacc;
;                 PV1(4, w2); MASK_TILE(pn0, pn1, t + 1); SB();
;                 PV1(5, w2); SB();
;                 PV1(6, w3); SB();
;                 PV1(7, w3); rmn = rowmax32(pn0, pn1); if (!USE_NEGM) rmn -= mref; SB();
;     ...
;             if (hn) { STOREK(t & 1); STOREV((t + 1) & 1); }
.Lmla_p12_go:
	v_exp_f32_e32 v222, v34
	v_exp_f32_e32 v223, v35
	v_add_f32_e32 v164, 0, v222
	v_cvt_pk_bf16_f32 v206, v222, v223
	v_add_f32_e32 v164, v223, v164
	v_exp_f32_e32 v224, v36
	v_exp_f32_e32 v225, v37
	v_add_f32_e32 v164, v224, v164
	v_cvt_pk_bf16_f32 v207, v224, v225
	v_add_f32_e32 v164, v225, v164
	s_waitcnt lgkmcnt(3)
	v_mfma_f32_32x32x16_bf16 v[82:97], v[182:185], v[114:117], v[66:81]
	ds_read_b128 v[198:201], v229 offset:13376
	v_exp_f32_e32 v222, v38
	v_exp_f32_e32 v223, v39
	v_add_f32_e32 v164, v222, v164
	v_cvt_pk_bf16_f32 v208, v222, v223
	v_add_f32_e32 v164, v223, v164
	s_waitcnt lgkmcnt(3)
	v_mfma_f32_32x32x16_bf16 v[98:113], v[186:189], v[114:117], v[66:81]
	ds_read_b128 v[182:185], v229 offset:20032
	v_exp_f32_e32 v224, v40
	v_exp_f32_e32 v225, v41
	v_add_f32_e32 v164, v224, v164
	v_cvt_pk_bf16_f32 v209, v224, v225
	v_add_f32_e32 v164, v225, v164
	s_waitcnt lgkmcnt(3)
	v_mfma_f32_32x32x16_bf16 v[82:97], v[190:193], v[118:121], v[82:97]
	ds_read_b128 v[186:189], v229 offset:13408
	v_exp_f32_e32 v222, v42
	v_exp_f32_e32 v223, v43
	v_add_f32_e32 v164, v222, v164
	v_cvt_pk_bf16_f32 v210, v222, v223
	v_add_f32_e32 v164, v223, v164
	s_waitcnt lgkmcnt(3)
	v_mfma_f32_32x32x16_bf16 v[98:113], v[194:197], v[118:121], v[98:113]
	ds_read_b128 v[190:193], v229 offset:20064
	v_exp_f32_e32 v224, v44
	v_exp_f32_e32 v225, v45
	v_add_f32_e32 v164, v224, v164
	v_cvt_pk_bf16_f32 v211, v224, v225
	v_add_f32_e32 v164, v225, v164
	s_waitcnt lgkmcnt(3)
	v_mfma_f32_32x32x16_bf16 v[82:97], v[198:201], v[122:125], v[82:97]
	ds_read_b128 v[194:197], v229 offset:13440
	v_exp_f32_e32 v222, v46
	v_exp_f32_e32 v223, v47
	v_add_f32_e32 v164, v222, v164
	v_cvt_pk_bf16_f32 v212, v222, v223
	v_add_f32_e32 v164, v223, v164
	s_waitcnt lgkmcnt(3)
	v_mfma_f32_32x32x16_bf16 v[98:113], v[182:185], v[122:125], v[98:113]
	ds_read_b128 v[198:201], v229 offset:20096
	v_exp_f32_e32 v224, v48
	v_exp_f32_e32 v225, v49
	v_add_f32_e32 v164, v224, v164
	v_cvt_pk_bf16_f32 v213, v224, v225
	v_add_f32_e32 v164, v225, v164
	s_waitcnt lgkmcnt(3)
	v_mfma_f32_32x32x16_bf16 v[82:97], v[186:189], v[126:129], v[82:97]
	ds_read_b128 v[182:185], v229 offset:13472
	v_exp_f32_e32 v222, v50
	v_exp_f32_e32 v223, v51
	v_add_f32_e32 v164, v222, v164
	v_cvt_pk_bf16_f32 v214, v222, v223
	v_add_f32_e32 v164, v223, v164
	s_waitcnt lgkmcnt(3)
	v_mfma_f32_32x32x16_bf16 v[98:113], v[190:193], v[126:129], v[98:113]
	ds_read_b128 v[186:189], v229 offset:20128
	v_exp_f32_e32 v224, v52
	v_exp_f32_e32 v225, v53
	v_add_f32_e32 v164, v224, v164
	v_cvt_pk_bf16_f32 v215, v224, v225
	v_add_f32_e32 v164, v225, v164
	s_waitcnt lgkmcnt(3)
	v_mfma_f32_32x32x16_bf16 v[82:97], v[194:197], v[130:133], v[82:97]
	ds_read_b128 v[190:193], v228 offset:13312
	v_exp_f32_e32 v222, v54
	v_exp_f32_e32 v223, v55
	v_add_f32_e32 v164, v222, v164
	v_cvt_pk_bf16_f32 v216, v222, v223
	v_add_f32_e32 v164, v223, v164
	s_waitcnt lgkmcnt(3)
	v_mfma_f32_32x32x16_bf16 v[98:113], v[198:201], v[130:133], v[98:113]
	ds_read_b128 v[194:197], v228 offset:17920
	v_exp_f32_e32 v224, v56
	v_exp_f32_e32 v225, v57
	v_add_f32_e32 v164, v224, v164
	v_cvt_pk_bf16_f32 v217, v224, v225
	v_add_f32_e32 v164, v225, v164
	s_waitcnt lgkmcnt(3)
	v_mfma_f32_32x32x16_bf16 v[82:97], v[182:185], v[134:137], v[82:97]
	ds_read_b128 v[198:201], v228 offset:13344
	v_exp_f32_e32 v222, v58
	v_exp_f32_e32 v223, v59
	v_add_f32_e32 v164, v222, v164
	v_cvt_pk_bf16_f32 v218, v222, v223
	v_add_f32_e32 v164, v223, v164
	s_waitcnt lgkmcnt(3)
	v_mfma_f32_32x32x16_bf16 v[98:113], v[186:189], v[134:137], v[98:113]
	ds_read_b128 v[182:185], v228 offset:17952
	v_exp_f32_e32 v224, v60
	v_exp_f32_e32 v225, v61
	v_add_f32_e32 v164, v224, v164
	v_cvt_pk_bf16_f32 v219, v224, v225
	v_add_f32_e32 v164, v225, v164
	s_waitcnt lgkmcnt(3)
	v_mfma_f32_32x32x16_bf16 v[2:17], v[190:193], v[206:209], v[2:17]
	ds_read_b128 v[186:189], v228 offset:13376
	v_exp_f32_e32 v222, v62
	v_exp_f32_e32 v223, v63
	v_add_f32_e32 v164, v222, v164
	v_cvt_pk_bf16_f32 v220, v222, v223
	v_add_f32_e32 v164, v223, v164
	s_waitcnt lgkmcnt(3)
	v_mfma_f32_32x32x16_bf16 v[18:33], v[194:197], v[206:209], v[18:33]
	ds_read_b128 v[190:193], v228 offset:17984
	v_exp_f32_e32 v224, v64
	v_exp_f32_e32 v225, v65
	v_add_f32_e32 v164, v224, v164
	v_cvt_pk_bf16_f32 v221, v224, v225
	v_add_f32_e32 v164, v225, v164
	s_mov_b32 s13, s20
	s_mov_b32 s20, s19
	s_add_i32 s19, s19, 1
	s_cmp_eq_u32 s19, s9
	s_cselect_b32 s19, 0, s19
	s_waitcnt lgkmcnt(3)
	v_mfma_f32_32x32x16_bf16 v[2:17], v[198:201], v[210:213], v[2:17]
	ds_read_b128 v[194:197], v228 offset:13408
	v_max3_f32 v224, v82, v83, v84
	v_max3_f32 v225, v98, v99, v100
	v_max3_f32 v224, v224, v85, v86
	v_max3_f32 v225, v225, v101, v102
	s_waitcnt vmcnt(2)
	ds_write_b128 v172, v[146:149] offset:22528
	v_lshl_add_u32 v222, s19, 17, v178
	global_load_dwordx4 v[146:149], v222, s[52:53]
	s_waitcnt lgkmcnt(4)
	v_mfma_f32_32x32x16_bf16 v[18:33], v[182:185], v[210:213], v[18:33]
	ds_read_b128 v[198:201], v228 offset:18016
	ds_read_b128 v[182:185], v229 offset:26624
	v_max3_f32 v224, v224, v87, v88
	v_max3_f32 v225, v225, v103, v104
	v_max3_f32 v224, v224, v89, v90
	v_max3_f32 v225, v225, v105, v106
	s_and_b64 vcc, exec, s[2:3]
	s_cbranch_vccz .Lmla_p12_nope
	ds_write_b128 v176, v[138:141] offset:22656
	v_lshl_add_u32 v222, s19, 12, v179
	global_load_dwordx4 v[138:141], v222, s[62:63]
.Lmla_p12_nope:
	s_waitcnt lgkmcnt(5)
	v_mfma_f32_32x32x16_bf16 v[2:17], v[186:189], v[214:217], v[2:17]
	ds_read_b128 v[186:189], v229 offset:33280
	v_max3_f32 v224, v224, v91, v92
	v_max3_f32 v225, v225, v107, v108
	v_max3_f32 v224, v224, v93, v94
	v_max3_f32 v225, v225, v109, v110
	v_add_u32_e32 v222, 0xb000, v173
	ds_write_b128 v222, v[142:145] offset:39936
	v_lshl_add_u32 v222, s13, 7, v168
	global_load_dwordx4 v[142:145], v222, s[56:57]
	s_waitcnt lgkmcnt(6)
	v_mfma_f32_32x32x16_bf16 v[18:33], v[190:193], v[214:217], v[18:33]
	ds_read_b128 v[190:193], v229 offset:26656
	v_max3_f32 v224, v224, v95, v96
	v_max3_f32 v225, v225, v111, v112
	v_max3_f32 v224, v224, v97, v113
	v_max_f32_e32 v224, v224, v225
	s_waitcnt lgkmcnt(6)
	v_mfma_f32_32x32x16_bf16 v[2:17], v[194:197], v[218:221], v[2:17]
	ds_read_b128 v[194:197], v229 offset:33312
	v_mov_b32_e32 v225, v224
	v_add_f32_e32 v1, v1, v164
	s_add_i32 s11, s11, 1
	v_permlane32_swap_b32_e32 v224, v225
	s_cmp_eq_u32 s9, s11
	v_max_f32_e32 v167, v224, v225
	v_cmp_lt_f32_e32 vcc, s66, v167
	s_waitcnt lgkmcnt(5)
	v_mfma_f32_32x32x16_bf16 v[18:33], v[198:201], v[218:221], v[18:33]
	s_cbranch_scc1 .Lmla_exit_p12

; template <int VAR>
; __device__ __forceinline__ void attn_phase(LAS unsigned char* lds, const AttnP P, int vcu, int G, int wave_s) {
;     ...
;                 if (ND0 == 6) {
;                     KR1(0); KR1(1); KR1(2); KR1(3); SB();
;                     QK1(0, negm); EX2(pc0, 0, w0.x); KR1(4); SB();
;                     QK1(1, negm); EX2(pc0, 2, w0.y); KR1(5); SB();
;                     QK1(2, pn0); EX2(pc0, 4, w0.z); KR1(6); SB();
;                     QK1(3, pn1); EX2(pc0, 6, w0.w); KR1(7); SB();
;                     QK1(4, pn0); EX2(pc0, 8, w1.x); KR1(8); SB();
;                     QK1(5, pn1); EX2(pc0, 10, w1.y); KR1(9); SB();
;                     QK1(6, pn0); EX2(pc0, 12, w1.z); KR1(10); SB();
;                     QK1(7, pn1); EX2(pc0, 14, w1.w); KR1(11); SB();
;                     QK1(8, pn0); EX2(pc1, 0, w2.x); VR1(0); SB();
;                     QK1(9, pn1); EX2(pc1, 2, w2.y); VR1(1); SB();
;                     QK1(10, pn0); EX2(pc1, 4, w2.z); VR1(2); SB();
;                     QK1(11, pn1); EX2(pc1, 6, w2.w); VR1(3); SB();
;                 } else {
;                     KR1(0); KR1(1); KR1(2); KR1(3); SB();
;                     QK1(0, negm); EX2(pc0, 0, w0.x); EX2(pc0, 2, w0.y); KR1(4); SB();
;                     QK1(1, negm); EX2(pc0, 4, w0.z); EX2(pc0, 6, w0.w); KR1(5); SB();
;                     QK1(2, pn0); EX2(pc0, 8, w1.x); EX2(pc0, 10, w1.y); KR1(6); SB();
;                     QK1(3, pn1); EX2(pc0, 12, w1.z); EX2(pc0, 14, w1.w); KR1(7); SB();
;                     QK1(4, pn0); EX2(pc1, 0, w2.x); VR1(0); SB();
;                     QK1(5, pn1); EX2(pc1, 2, w2.y); VR1(1); SB();
;                     QK1(6, pn0); EX2(pc1, 4, w2.z); VR1(2); SB();
;                     QK1(7, pn1); EX2(pc1, 6, w2.w); VR1(3); SB();
;                 }
;                 PV1(0, w0); EX2(pc1, 8, w3.x); VR1(4); SB();
;                 PV1(1, w0); EX2(pc1, 10, w3.y); VR1(5); SB();
;                 PV1(2, w1); EX2(pc1, 12, w3.z); VR1(6); SB();
;                 PV1(3, w1); EX2(pc1, 14, w3.w); VR1(7); SB();
;                 lrun += sacc;
;                 PV1(4, w2); MASK_TILE(pn0, pn1, t + 1); SB();
;                 PV1(5, w2); SB();
;                 PV1(6, w3); SB();
;                 PV1(7, w3); rmn = rowmax32(pn0, pn1); if (!USE_NEGM) rmn -= mref; SB();
;     ...
;             if (hn) { STOREK(t & 1); STOREV((t + 1) & 1); }
;             __syncthreads();
.Lmla_p13_go:
	v_exp_f32_e32 v222, v82
	v_exp_f32_e32 v223, v83
	v_add_f32_e32 v164, 0, v222
	v_cvt_pk_bf16_f32 v206, v222, v223
	v_add_f32_e32 v164, v223, v164
	v_exp_f32_e32 v224, v84
	v_exp_f32_e32 v225, v85
	v_add_f32_e32 v164, v224, v164
	v_cvt_pk_bf16_f32 v207, v224, v225
	v_add_f32_e32 v164, v225, v164
	s_waitcnt lgkmcnt(4)
	v_mfma_f32_32x32x16_bf16 v[34:49], v[182:185], v[114:117], v[66:81]
	ds_read_b128 v[198:201], v229 offset:26688
	v_exp_f32_e32 v222, v86
	v_exp_f32_e32 v223, v87
	v_add_f32_e32 v164, v222, v164
	v_cvt_pk_bf16_f32 v208, v222, v223
	v_add_f32_e32 v164, v223, v164
	s_waitcnt lgkmcnt(4)
	v_mfma_f32_32x32x16_bf16 v[50:65], v[186:189], v[114:117], v[66:81]
	ds_read_b128 v[182:185], v229 offset:33344
	v_exp_f32_e32 v224, v88
	v_exp_f32_e32 v225, v89
	v_add_f32_e32 v164, v224, v164
	v_cvt_pk_bf16_f32 v209, v224, v225
	v_add_f32_e32 v164, v225, v164
	s_waitcnt lgkmcnt(3)
	v_mfma_f32_32x32x16_bf16 v[34:49], v[190:193], v[118:121], v[34:49]
	ds_read_b128 v[186:189], v229 offset:26720
	v_exp_f32_e32 v222, v90
	v_exp_f32_e32 v223, v91
	v_add_f32_e32 v164, v222, v164
	v_cvt_pk_bf16_f32 v210, v222, v223
	v_add_f32_e32 v164, v223, v164
	s_waitcnt lgkmcnt(3)
	v_mfma_f32_32x32x16_bf16 v[50:65], v[194:197], v[118:121], v[50:65]
	ds_read_b128 v[190:193], v229 offset:33376
	v_exp_f32_e32 v224, v92
	v_exp_f32_e32 v225, v93
	v_add_f32_e32 v164, v224, v164
	v_cvt_pk_bf16_f32 v211, v224, v225
	v_add_f32_e32 v164, v225, v164
	s_waitcnt lgkmcnt(3)
	v_mfma_f32_32x32x16_bf16 v[34:49], v[198:201], v[122:125], v[34:49]
	ds_read_b128 v[194:197], v229 offset:26752
	v_exp_f32_e32 v222, v94
	v_exp_f32_e32 v223, v95
	v_add_f32_e32 v164, v222, v164
	v_cvt_pk_bf16_f32 v212, v222, v223
	v_add_f32_e32 v164, v223, v164
	s_waitcnt lgkmcnt(3)
	v_mfma_f32_32x32x16_bf16 v[50:65], v[182:185], v[122:125], v[50:65]
	ds_read_b128 v[198:201], v229 offset:33408
	v_exp_f32_e32 v224, v96
	v_exp_f32_e32 v225, v97
	v_add_f32_e32 v164, v224, v164
	v_cvt_pk_bf16_f32 v213, v224, v225
	v_add_f32_e32 v164, v225, v164
	s_waitcnt lgkmcnt(3)
	v_mfma_f32_32x32x16_bf16 v[34:49], v[186:189], v[126:129], v[34:49]
	ds_read_b128 v[182:185], v229 offset:26784
	v_exp_f32_e32 v222, v98
	v_exp_f32_e32 v223, v99
	v_add_f32_e32 v164, v222, v164
	v_cvt_pk_bf16_f32 v214, v222, v223
	v_add_f32_e32 v164, v223, v164
	s_waitcnt lgkmcnt(3)
	v_mfma_f32_32x32x16_bf16 v[50:65], v[190:193], v[126:129], v[50:65]
	ds_read_b128 v[186:189], v229 offset:33440
	v_exp_f32_e32 v224, v100
	v_exp_f32_e32 v225, v101
	v_add_f32_e32 v164, v224, v164
	v_cvt_pk_bf16_f32 v215, v224, v225
	v_add_f32_e32 v164, v225, v164
	s_waitcnt lgkmcnt(3)
	v_mfma_f32_32x32x16_bf16 v[34:49], v[194:197], v[130:133], v[34:49]
	ds_read_b128 v[190:193], v228 offset:35840
	v_exp_f32_e32 v222, v102
	v_exp_f32_e32 v223, v103
	v_add_f32_e32 v164, v222, v164
	v_cvt_pk_bf16_f32 v216, v222, v223
	v_add_f32_e32 v164, v223, v164
	s_waitcnt lgkmcnt(3)
	v_mfma_f32_32x32x16_bf16 v[50:65], v[198:201], v[130:133], v[50:65]
	ds_read_b128 v[194:197], v228 offset:40448
	v_exp_f32_e32 v224, v104
	v_exp_f32_e32 v225, v105
	v_add_f32_e32 v164, v224, v164
	v_cvt_pk_bf16_f32 v217, v224, v225
	v_add_f32_e32 v164, v225, v164
	s_waitcnt lgkmcnt(3)
	v_mfma_f32_32x32x16_bf16 v[34:49], v[182:185], v[134:137], v[34:49]
	ds_read_b128 v[198:201], v228 offset:35872
	v_exp_f32_e32 v222, v106
	v_exp_f32_e32 v223, v107
	v_add_f32_e32 v164, v222, v164
	v_cvt_pk_bf16_f32 v218, v222, v223
	v_add_f32_e32 v164, v223, v164
	s_waitcnt lgkmcnt(3)
	v_mfma_f32_32x32x16_bf16 v[50:65], v[186:189], v[134:137], v[50:65]
	ds_read_b128 v[182:185], v228 offset:40480
	v_exp_f32_e32 v224, v108
	v_exp_f32_e32 v225, v109
	v_add_f32_e32 v164, v224, v164
	v_cvt_pk_bf16_f32 v219, v224, v225
	v_add_f32_e32 v164, v225, v164
	s_waitcnt lgkmcnt(3)
	v_mfma_f32_32x32x16_bf16 v[2:17], v[190:193], v[206:209], v[2:17]
	ds_read_b128 v[186:189], v228 offset:35904
	v_exp_f32_e32 v222, v110
	v_exp_f32_e32 v223, v111
	v_add_f32_e32 v164, v222, v164
	v_cvt_pk_bf16_f32 v220, v222, v223
	v_add_f32_e32 v164, v223, v164
	s_waitcnt lgkmcnt(3)
	v_mfma_f32_32x32x16_bf16 v[18:33], v[194:197], v[206:209], v[18:33]
	ds_read_b128 v[190:193], v228 offset:40512
	v_exp_f32_e32 v224, v112
	v_exp_f32_e32 v225, v113
	v_add_f32_e32 v164, v224, v164
	v_cvt_pk_bf16_f32 v221, v224, v225
	v_add_f32_e32 v164, v225, v164
	s_mov_b32 s13, s20
	s_mov_b32 s20, s19
	s_add_i32 s19, s19, 1
	s_cmp_eq_u32 s19, s9
	s_cselect_b32 s19, 0, s19
	s_waitcnt lgkmcnt(3)
	v_mfma_f32_32x32x16_bf16 v[2:17], v[198:201], v[210:213], v[2:17]
	ds_read_b128 v[194:197], v228 offset:35936
	v_max3_f32 v224, v34, v35, v36
	v_max3_f32 v225, v50, v51, v52
	v_max3_f32 v224, v224, v37, v38
	v_max3_f32 v225, v225, v53, v54
	s_waitcnt vmcnt(2)
	ds_write_b128 v172, v[150:153] offset:45056
	v_lshl_add_u32 v222, s19, 17, v178
	global_load_dwordx4 v[150:153], v222, s[52:53]
	s_waitcnt lgkmcnt(4)
	v_mfma_f32_32x32x16_bf16 v[18:33], v[182:185], v[210:213], v[18:33]
	ds_read_b128 v[198:201], v228 offset:40544
	ds_read_b128 v[182:185], v174
	v_max3_f32 v224, v224, v39, v40
	v_max3_f32 v225, v225, v55, v56
	v_max3_f32 v224, v224, v41, v42
	v_max3_f32 v225, v225, v57, v58
	s_and_b64 vcc, exec, s[2:3]
	s_cbranch_vccz .Lmla_p13_nope
	ds_write_b128 v176, v[160:163] offset:45184
	v_lshl_add_u32 v222, s19, 12, v179
	global_load_dwordx4 v[160:163], v222, s[62:63]
.Lmla_p13_nope:
	s_waitcnt lgkmcnt(5)
	v_mfma_f32_32x32x16_bf16 v[2:17], v[186:189], v[214:217], v[2:17]
	ds_read_b128 v[186:189], v174 offset:6656
	v_max3_f32 v224, v224, v43, v44
	v_max3_f32 v225, v225, v59, v60
	v_max3_f32 v224, v224, v45, v46
	v_max3_f32 v225, v225, v61, v62
	v_add_u32_e32 v222, 0xb000, v173
	ds_write_b128 v222, v[202:205] offset:49152
	v_lshl_add_u32 v222, s13, 7, v168
	global_load_dwordx4 v[202:205], v222, s[56:57]
	s_waitcnt lgkmcnt(6)
	v_mfma_f32_32x32x16_bf16 v[18:33], v[190:193], v[214:217], v[18:33]
	ds_read_b128 v[190:193], v174 offset:32
	v_max3_f32 v224, v224, v47, v48
	v_max3_f32 v225, v225, v63, v64
	v_max3_f32 v224, v224, v49, v65
	v_max_f32_e32 v224, v224, v225
	s_waitcnt lgkmcnt(6)
	v_mfma_f32_32x32x16_bf16 v[2:17], v[194:197], v[218:221], v[2:17]
	ds_read_b128 v[194:197], v174 offset:6688
	v_mov_b32_e32 v225, v224
	v_add_f32_e32 v1, v1, v164
	s_add_i32 s11, s11, 1
	v_permlane32_swap_b32_e32 v224, v225
	s_cmp_eq_u32 s9, s11
	v_max_f32_e32 v167, v224, v225
	v_cmp_lt_f32_e32 vcc, s66, v167
	s_waitcnt lgkmcnt(5)
	v_mfma_f32_32x32x16_bf16 v[18:33], v[198:201], v[218:221], v[18:33]
	s_waitcnt lgkmcnt(2)
	s_barrier
	s_cbranch_scc1 .Lmla_exit_p13

; template <int VAR>
; __device__ __forceinline__ void attn_phase(LAS unsigned char* lds, const AttnP P, int vcu, int G, int wave_s) {
;     ...
;                 if (ND0 == 6) {
;                     KR1(0); KR1(1); KR1(2); KR1(3); SB();
;                     QK1(0, negm); EX2(pc0, 0, w0.x); KR1(4); SB();
;                     QK1(1, negm); EX2(pc0, 2, w0.y); KR1(5); SB();
;                     QK1(2, pn0); EX2(pc0, 4, w0.z); KR1(6); SB();
;                     QK1(3, pn1); EX2(pc0, 6, w0.w); KR1(7); SB();
;                     QK1(4, pn0); EX2(pc0, 8, w1.x); KR1(8); SB();
;                     QK1(5, pn1); EX2(pc0, 10, w1.y); KR1(9); SB();
;                     QK1(6, pn0); EX2(pc0, 12, w1.z); KR1(10); SB();
;                     QK1(7, pn1); EX2(pc0, 14, w1.w); KR1(11); SB();
;                     QK1(8, pn0); EX2(pc1, 0, w2.x); VR1(0); SB();
;                     QK1(9, pn1); EX2(pc1, 2, w2.y); VR1(1); SB();
;                     QK1(10, pn0); EX2(pc1, 4, w2.z); VR1(2); SB();
;                     QK1(11, pn1); EX2(pc1, 6, w2.w); VR1(3); SB();
;                 } else {
;                     KR1(0); KR1(1); KR1(2); KR1(3); SB();
;                     QK1(0, negm); EX2(pc0, 0, w0.x); EX2(pc0, 2, w0.y); KR1(4); SB();
;                     QK1(1, negm); EX2(pc0, 4, w0.z); EX2(pc0, 6, w0.w); KR1(5); SB();
;                     QK1(2, pn0); EX2(pc0, 8, w1.x); EX2(pc0, 10, w1.y); KR1(6); SB();
;                     QK1(3, pn1); EX2(pc0, 12, w1.z); EX2(pc0, 14, w1.w); KR1(7); SB();
;                     QK1(4, pn0); EX2(pc1, 0, w2.x); VR1(0); SB();
;                     QK1(5, pn1); EX2(pc1, 2, w2.y); VR1(1); SB();
;                     QK1(6, pn0); EX2(pc1, 4, w2.z); VR1(2); SB();
;                     QK1(7, pn1); EX2(pc1, 6, w2.w); VR1(3); SB();
;                 }
;                 PV1(0, w0); EX2(pc1, 8, w3.x); VR1(4); SB();
;                 PV1(1, w0); EX2(pc1, 10, w3.y); VR1(5); SB();
;                 PV1(2, w1); EX2(pc1, 12, w3.z); VR1(6); SB();
;                 PV1(3, w1); EX2(pc1, 14, w3.w); VR1(7); SB();
;                 lrun += sacc;
;                 PV1(4, w2); MASK_TILE(pn0, pn1, t + 1); SB();
;                 PV1(5, w2); SB();
;                 PV1(6, w3); SB();
;                 PV1(7, w3); rmn = rowmax32(pn0, pn1); if (!USE_NEGM) rmn -= mref; SB();
;     ...
;             if (hn) { STOREK(t & 1); STOREV((t + 1) & 1); }
;             __syncthreads();
.Lmla_p14_go:
	v_exp_f32_e32 v222, v34
	v_exp_f32_e32 v223, v35
	v_add_f32_e32 v164, 0, v222
	v_cvt_pk_bf16_f32 v206, v222, v223
	v_add_f32_e32 v164, v223, v164
	v_exp_f32_e32 v224, v36
	v_exp_f32_e32 v225, v37
	v_add_f32_e32 v164, v224, v164
	v_cvt_pk_bf16_f32 v207, v224, v225
	v_add_f32_e32 v164, v225, v164
	s_waitcnt lgkmcnt(3)
	v_mfma_f32_32x32x16_bf16 v[82:97], v[182:185], v[114:117], v[66:81]
	ds_read_b128 v[198:201], v174 offset:64
	v_exp_f32_e32 v222, v38
	v_exp_f32_e32 v223, v39
	v_add_f32_e32 v164, v222, v164
	v_cvt_pk_bf16_f32 v208, v222, v223
	v_add_f32_e32 v164, v223, v164
	s_waitcnt lgkmcnt(3)
	v_mfma_f32_32x32x16_bf16 v[98:113], v[186:189], v[114:117], v[66:81]
	ds_read_b128 v[182:185], v174 offset:6720
	v_exp_f32_e32 v224, v40
	v_exp_f32_e32 v225, v41
	v_add_f32_e32 v164, v224, v164
	v_cvt_pk_bf16_f32 v209, v224, v225
	v_add_f32_e32 v164, v225, v164
	s_waitcnt lgkmcnt(3)
	v_mfma_f32_32x32x16_bf16 v[82:97], v[190:193], v[118:121], v[82:97]
	ds_read_b128 v[186:189], v174 offset:96
	v_exp_f32_e32 v222, v42
	v_exp_f32_e32 v223, v43
	v_add_f32_e32 v164, v222, v164
	v_cvt_pk_bf16_f32 v210, v222, v223
	v_add_f32_e32 v164, v223, v164
	s_waitcnt lgkmcnt(3)
	v_mfma_f32_32x32x16_bf16 v[98:113], v[194:197], v[118:121], v[98:113]
	ds_read_b128 v[190:193], v174 offset:6752
	v_exp_f32_e32 v224, v44
	v_exp_f32_e32 v225, v45
	v_add_f32_e32 v164, v224, v164
	v_cvt_pk_bf16_f32 v211, v224, v225
	v_add_f32_e32 v164, v225, v164
	s_waitcnt lgkmcnt(3)
	v_mfma_f32_32x32x16_bf16 v[82:97], v[198:201], v[122:125], v[82:97]
	ds_read_b128 v[194:197], v174 offset:128
	v_exp_f32_e32 v222, v46
	v_exp_f32_e32 v223, v47
	v_add_f32_e32 v164, v222, v164
	v_cvt_pk_bf16_f32 v212, v222, v223
	v_add_f32_e32 v164, v223, v164
	s_waitcnt lgkmcnt(3)
	v_mfma_f32_32x32x16_bf16 v[98:113], v[182:185], v[122:125], v[98:113]
	ds_read_b128 v[198:201], v174 offset:6784
	v_exp_f32_e32 v224, v48
	v_exp_f32_e32 v225, v49
	v_add_f32_e32 v164, v224, v164
	v_cvt_pk_bf16_f32 v213, v224, v225
	v_add_f32_e32 v164, v225, v164
	s_waitcnt lgkmcnt(3)
	v_mfma_f32_32x32x16_bf16 v[82:97], v[186:189], v[126:129], v[82:97]
	ds_read_b128 v[182:185], v174 offset:160
	v_exp_f32_e32 v222, v50
	v_exp_f32_e32 v223, v51
	v_add_f32_e32 v164, v222, v164
	v_cvt_pk_bf16_f32 v214, v222, v223
	v_add_f32_e32 v164, v223, v164
	s_waitcnt lgkmcnt(3)
	v_mfma_f32_32x32x16_bf16 v[98:113], v[190:193], v[126:129], v[98:113]
	ds_read_b128 v[186:189], v174 offset:6816
	v_exp_f32_e32 v224, v52
	v_exp_f32_e32 v225, v53
	v_add_f32_e32 v164, v224, v164
	v_cvt_pk_bf16_f32 v215, v224, v225
	v_add_f32_e32 v164, v225, v164
	s_waitcnt lgkmcnt(3)
	v_mfma_f32_32x32x16_bf16 v[82:97], v[194:197], v[130:133], v[82:97]
	ds_read_b128 v[190:193], v181 offset:39936
	v_exp_f32_e32 v222, v54
	v_exp_f32_e32 v223, v55
	v_add_f32_e32 v164, v222, v164
	v_cvt_pk_bf16_f32 v216, v222, v223
	v_add_f32_e32 v164, v223, v164
	s_waitcnt lgkmcnt(3)
	v_mfma_f32_32x32x16_bf16 v[98:113], v[198:201], v[130:133], v[98:113]
	ds_read_b128 v[194:197], v181 offset:44544
	v_exp_f32_e32 v224, v56
	v_exp_f32_e32 v225, v57
	v_add_f32_e32 v164, v224, v164
	v_cvt_pk_bf16_f32 v217, v224, v225
	v_add_f32_e32 v164, v225, v164
	s_waitcnt lgkmcnt(3)
	v_mfma_f32_32x32x16_bf16 v[82:97], v[182:185], v[134:137], v[82:97]
	ds_read_b128 v[198:201], v181 offset:39968
	v_exp_f32_e32 v222, v58
	v_exp_f32_e32 v223, v59
	v_add_f32_e32 v164, v222, v164
	v_cvt_pk_bf16_f32 v218, v222, v223
	v_add_f32_e32 v164, v223, v164
	s_waitcnt lgkmcnt(3)
	v_mfma_f32_32x32x16_bf16 v[98:113], v[186:189], v[134:137], v[98:113]
	ds_read_b128 v[182:185], v181 offset:44576
	v_exp_f32_e32 v224, v60
	v_exp_f32_e32 v225, v61
	v_add_f32_e32 v164, v224, v164
	v_cvt_pk_bf16_f32 v219, v224, v225
	v_add_f32_e32 v164, v225, v164
	s_waitcnt lgkmcnt(3)
	v_mfma_f32_32x32x16_bf16 v[2:17], v[190:193], v[206:209], v[2:17]
	ds_read_b128 v[186:189], v181 offset:40000
	v_exp_f32_e32 v222, v62
	v_exp_f32_e32 v223, v63
	v_add_f32_e32 v164, v222, v164
	v_cvt_pk_bf16_f32 v220, v222, v223
	v_add_f32_e32 v164, v223, v164
	s_waitcnt lgkmcnt(3)
	v_mfma_f32_32x32x16_bf16 v[18:33], v[194:197], v[206:209], v[18:33]
	ds_read_b128 v[190:193], v181 offset:44608
	v_exp_f32_e32 v224, v64
	v_exp_f32_e32 v225, v65
	v_add_f32_e32 v164, v224, v164
	v_cvt_pk_bf16_f32 v221, v224, v225
	v_add_f32_e32 v164, v225, v164
	s_mov_b32 s13, s20
	s_mov_b32 s20, s19
	s_add_i32 s19, s19, 1
	s_cmp_eq_u32 s19, s9
	s_cselect_b32 s19, 0, s19
	s_waitcnt lgkmcnt(3)
	v_mfma_f32_32x32x16_bf16 v[2:17], v[198:201], v[210:213], v[2:17]
	ds_read_b128 v[194:197], v181 offset:40032
	v_max3_f32 v224, v82, v83, v84
	v_max3_f32 v225, v98, v99, v100
	v_max3_f32 v224, v224, v85, v86
	v_max3_f32 v225, v225, v101, v102
	s_waitcnt vmcnt(2)
	ds_write_b128 v172, v[146:149] offset:58368
	v_lshl_add_u32 v222, s19, 17, v178
	global_load_dwordx4 v[146:149], v222, s[52:53]
	s_waitcnt lgkmcnt(4)
	v_mfma_f32_32x32x16_bf16 v[18:33], v[182:185], v[210:213], v[18:33]
	ds_read_b128 v[198:201], v181 offset:44640
	ds_read_b128 v[182:185], v174 offset:22528
	v_max3_f32 v224, v224, v87, v88
	v_max3_f32 v225, v225, v103, v104
	v_max3_f32 v224, v224, v89, v90
	v_max3_f32 v225, v225, v105, v106
	s_and_b64 vcc, exec, s[2:3]
	s_cbranch_vccz .Lmla_p14_nope
	ds_write_b128 v176, v[138:141] offset:58496
	v_lshl_add_u32 v222, s19, 12, v179
	global_load_dwordx4 v[138:141], v222, s[62:63]
.Lmla_p14_nope:
	s_waitcnt lgkmcnt(5)
	v_mfma_f32_32x32x16_bf16 v[2:17], v[186:189], v[214:217], v[2:17]
	ds_read_b128 v[186:189], v174 offset:29184
	v_max3_f32 v224, v224, v91, v92
	v_max3_f32 v225, v225, v107, v108
	v_max3_f32 v224, v224, v93, v94
	v_max3_f32 v225, v225, v109, v110
	ds_write_b128 v173, v[142:145] offset:13312
	v_lshl_add_u32 v222, s13, 7, v168
	global_load_dwordx4 v[142:145], v222, s[56:57]
	s_waitcnt lgkmcnt(6)
	v_mfma_f32_32x32x16_bf16 v[18:33], v[190:193], v[214:217], v[18:33]
	ds_read_b128 v[190:193], v174 offset:22560
	v_max3_f32 v224, v224, v95, v96
	v_max3_f32 v225, v225, v111, v112
	v_max3_f32 v224, v224, v97, v113
	v_max_f32_e32 v224, v224, v225
	s_waitcnt lgkmcnt(6)
	v_mfma_f32_32x32x16_bf16 v[2:17], v[194:197], v[218:221], v[2:17]
	ds_read_b128 v[194:197], v174 offset:29216
	v_mov_b32_e32 v225, v224
	v_add_f32_e32 v1, v1, v164
	s_add_i32 s11, s11, 1
	v_permlane32_swap_b32_e32 v224, v225
	s_cmp_eq_u32 s9, s11
	v_max_f32_e32 v167, v224, v225
	v_cmp_lt_f32_e32 vcc, s66, v167
	s_waitcnt lgkmcnt(5)
	v_mfma_f32_32x32x16_bf16 v[18:33], v[198:201], v[218:221], v[18:33]
	s_cbranch_scc1 .Lmla_exit_p14

; template <int VAR>
; __device__ __forceinline__ void attn_phase(LAS unsigned char* lds, const AttnP P, int vcu, int G, int wave_s) {
;     ...
;                 if (ND0 == 6) {
;                     KR1(0); KR1(1); KR1(2); KR1(3); SB();
;                     QK1(0, negm); EX2(pc0, 0, w0.x); KR1(4); SB();
;                     QK1(1, negm); EX2(pc0, 2, w0.y); KR1(5); SB();
;                     QK1(2, pn0); EX2(pc0, 4, w0.z); KR1(6); SB();
;                     QK1(3, pn1); EX2(pc0, 6, w0.w); KR1(7); SB();
;                     QK1(4, pn0); EX2(pc0, 8, w1.x); KR1(8); SB();
;                     QK1(5, pn1); EX2(pc0, 10, w1.y); KR1(9); SB();
;                     QK1(6, pn0); EX2(pc0, 12, w1.z); KR1(10); SB();
;                     QK1(7, pn1); EX2(pc0, 14, w1.w); KR1(11); SB();
;                     QK1(8, pn0); EX2(pc1, 0, w2.x); VR1(0); SB();
;                     QK1(9, pn1); EX2(pc1, 2, w2.y); VR1(1); SB();
;                     QK1(10, pn0); EX2(pc1, 4, w2.z); VR1(2); SB();
;                     QK1(11, pn1); EX2(pc1, 6, w2.w); VR1(3); SB();
;                 } else {
;                     KR1(0); KR1(1); KR1(2); KR1(3); SB();
;                     QK1(0, negm); EX2(pc0, 0, w0.x); EX2(pc0, 2, w0.y); KR1(4); SB();
;                     QK1(1, negm); EX2(pc0, 4, w0.z); EX2(pc0, 6, w0.w); KR1(5); SB();
;                     QK1(2, pn0); EX2(pc0, 8, w1.x); EX2(pc0, 10, w1.y); KR1(6); SB();
;                     QK1(3, pn1); EX2(pc0, 12, w1.z); EX2(pc0, 14, w1.w); KR1(7); SB();
;                     QK1(4, pn0); EX2(pc1, 0, w2.x); VR1(0); SB();
;                     QK1(5, pn1); EX2(pc1, 2, w2.y); VR1(1); SB();
;                     QK1(6, pn0); EX2(pc1, 4, w2.z); VR1(2); SB();
;                     QK1(7, pn1); EX2(pc1, 6, w2.w); VR1(3); SB();
;                 }
;                 PV1(0, w0); EX2(pc1, 8, w3.x); VR1(4); SB();
;                 PV1(1, w0); EX2(pc1, 10, w3.y); VR1(5); SB();
;                 PV1(2, w1); EX2(pc1, 12, w3.z); VR1(6); SB();
;                 PV1(3, w1); EX2(pc1, 14, w3.w); VR1(7); SB();
;                 lrun += sacc;
;                 PV1(4, w2); MASK_TILE(pn0, pn1, t + 1); SB();
;                 PV1(5, w2); SB();
;                 PV1(6, w3); SB();
;                 PV1(7, w3); rmn = rowmax32(pn0, pn1); if (!USE_NEGM) rmn -= mref; SB();
;     ...
;             if (hn) { STOREK(t & 1); STOREV((t + 1) & 1); }
;             __syncthreads();
.Lmla_p15_go:
	v_exp_f32_e32 v222, v82
	v_exp_f32_e32 v223, v83
	v_add_f32_e32 v164, 0, v222
	v_cvt_pk_bf16_f32 v206, v222, v223
	v_add_f32_e32 v164, v223, v164
	v_exp_f32_e32 v224, v84
	v_exp_f32_e32 v225, v85
	v_add_f32_e32 v164, v224, v164
	v_cvt_pk_bf16_f32 v207, v224, v225
	v_add_f32_e32 v164, v225, v164
	s_waitcnt lgkmcnt(4)
	v_mfma_f32_32x32x16_bf16 v[34:49], v[182:185], v[114:117], v[66:81]
	ds_read_b128 v[198:201], v174 offset:22592
	v_exp_f32_e32 v222, v86
	v_exp_f32_e32 v223, v87
	v_add_f32_e32 v164, v222, v164
	v_cvt_pk_bf16_f32 v208, v222, v223
	v_add_f32_e32 v164, v223, v164
	s_waitcnt lgkmcnt(4)
	v_mfma_f32_32x32x16_bf16 v[50:65], v[186:189], v[114:117], v[66:81]
	ds_read_b128 v[182:185], v174 offset:29248
	v_exp_f32_e32 v224, v88
	v_exp_f32_e32 v225, v89
	v_add_f32_e32 v164, v224, v164
	v_cvt_pk_bf16_f32 v209, v224, v225
	v_add_f32_e32 v164, v225, v164
	s_waitcnt lgkmcnt(3)
	v_mfma_f32_32x32x16_bf16 v[34:49], v[190:193], v[118:121], v[34:49]
	ds_read_b128 v[186:189], v174 offset:22624
	v_exp_f32_e32 v222, v90
	v_exp_f32_e32 v223, v91
	v_add_f32_e32 v164, v222, v164
	v_cvt_pk_bf16_f32 v210, v222, v223
	v_add_f32_e32 v164, v223, v164
	s_waitcnt lgkmcnt(3)
	v_mfma_f32_32x32x16_bf16 v[50:65], v[194:197], v[118:121], v[50:65]
	ds_read_b128 v[190:193], v174 offset:29280
	v_exp_f32_e32 v224, v92
	v_exp_f32_e32 v225, v93
	v_add_f32_e32 v164, v224, v164
	v_cvt_pk_bf16_f32 v211, v224, v225
	v_add_f32_e32 v164, v225, v164
	s_waitcnt lgkmcnt(3)
	v_mfma_f32_32x32x16_bf16 v[34:49], v[198:201], v[122:125], v[34:49]
	ds_read_b128 v[194:197], v174 offset:22656
	v_exp_f32_e32 v222, v94
	v_exp_f32_e32 v223, v95
	v_add_f32_e32 v164, v222, v164
	v_cvt_pk_bf16_f32 v212, v222, v223
	v_add_f32_e32 v164, v223, v164
	s_waitcnt lgkmcnt(3)
	v_mfma_f32_32x32x16_bf16 v[50:65], v[182:185], v[122:125], v[50:65]
	ds_read_b128 v[198:201], v174 offset:29312
	v_exp_f32_e32 v224, v96
	v_exp_f32_e32 v225, v97
	v_add_f32_e32 v164, v224, v164
	v_cvt_pk_bf16_f32 v213, v224, v225
	v_add_f32_e32 v164, v225, v164
	s_waitcnt lgkmcnt(3)
	v_mfma_f32_32x32x16_bf16 v[34:49], v[186:189], v[126:129], v[34:49]
	ds_read_b128 v[182:185], v174 offset:22688
	v_exp_f32_e32 v222, v98
	v_exp_f32_e32 v223, v99
	v_add_f32_e32 v164, v222, v164
	v_cvt_pk_bf16_f32 v214, v222, v223
	v_add_f32_e32 v164, v223, v164
	s_waitcnt lgkmcnt(3)
	v_mfma_f32_32x32x16_bf16 v[50:65], v[190:193], v[126:129], v[50:65]
	ds_read_b128 v[186:189], v174 offset:29344
	v_exp_f32_e32 v224, v100
	v_exp_f32_e32 v225, v101
	v_add_f32_e32 v164, v224, v164
	v_cvt_pk_bf16_f32 v215, v224, v225
	v_add_f32_e32 v164, v225, v164
	s_waitcnt lgkmcnt(3)
	v_mfma_f32_32x32x16_bf16 v[34:49], v[194:197], v[130:133], v[34:49]
	ds_read_b128 v[190:193], v181 offset:49152
	v_exp_f32_e32 v222, v102
	v_exp_f32_e32 v223, v103
	v_add_f32_e32 v164, v222, v164
	v_cvt_pk_bf16_f32 v216, v222, v223
	v_add_f32_e32 v164, v223, v164
	s_waitcnt lgkmcnt(3)
	v_mfma_f32_32x32x16_bf16 v[50:65], v[198:201], v[130:133], v[50:65]
	ds_read_b128 v[194:197], v181 offset:53760
	v_exp_f32_e32 v224, v104
	v_exp_f32_e32 v225, v105
	v_add_f32_e32 v164, v224, v164
	v_cvt_pk_bf16_f32 v217, v224, v225
	v_add_f32_e32 v164, v225, v164
	s_waitcnt lgkmcnt(3)
	v_mfma_f32_32x32x16_bf16 v[34:49], v[182:185], v[134:137], v[34:49]
	ds_read_b128 v[198:201], v181 offset:49184
	v_exp_f32_e32 v222, v106
	v_exp_f32_e32 v223, v107
	v_add_f32_e32 v164, v222, v164
	v_cvt_pk_bf16_f32 v218, v222, v223
	v_add_f32_e32 v164, v223, v164
	s_waitcnt lgkmcnt(3)
	v_mfma_f32_32x32x16_bf16 v[50:65], v[186:189], v[134:137], v[50:65]
	ds_read_b128 v[182:185], v181 offset:53792
	v_exp_f32_e32 v224, v108
	v_exp_f32_e32 v225, v109
	v_add_f32_e32 v164, v224, v164
	v_cvt_pk_bf16_f32 v219, v224, v225
	v_add_f32_e32 v164, v225, v164
	s_waitcnt lgkmcnt(3)
	v_mfma_f32_32x32x16_bf16 v[2:17], v[190:193], v[206:209], v[2:17]
	ds_read_b128 v[186:189], v181 offset:49216
	v_exp_f32_e32 v222, v110
	v_exp_f32_e32 v223, v111
	v_add_f32_e32 v164, v222, v164
	v_cvt_pk_bf16_f32 v220, v222, v223
	v_add_f32_e32 v164, v223, v164
	s_waitcnt lgkmcnt(3)
	v_mfma_f32_32x32x16_bf16 v[18:33], v[194:197], v[206:209], v[18:33]
	ds_read_b128 v[190:193], v181 offset:53824
	v_exp_f32_e32 v224, v112
	v_exp_f32_e32 v225, v113
	v_add_f32_e32 v164, v224, v164
	v_cvt_pk_bf16_f32 v221, v224, v225
	v_add_f32_e32 v164, v225, v164
	s_mov_b32 s13, s20
	s_mov_b32 s20, s19
	s_add_i32 s19, s19, 1
	s_cmp_eq_u32 s19, s9
	s_cselect_b32 s19, 0, s19
	s_waitcnt lgkmcnt(3)
	v_mfma_f32_32x32x16_bf16 v[2:17], v[198:201], v[210:213], v[2:17]
	ds_read_b128 v[194:197], v181 offset:49248
	v_max3_f32 v224, v34, v35, v36
	v_max3_f32 v225, v50, v51, v52
	v_max3_f32 v224, v224, v37, v38
	v_max3_f32 v225, v225, v53, v54
	s_waitcnt vmcnt(2)
	v_add_u32_e32 v222, 0xb000, v172
	ds_write_b128 v222, v[150:153] offset:26624
	v_lshl_add_u32 v222, s19, 17, v178
	global_load_dwordx4 v[150:153], v222, s[52:53]
	s_waitcnt lgkmcnt(4)
	v_mfma_f32_32x32x16_bf16 v[18:33], v[182:185], v[210:213], v[18:33]
	ds_read_b128 v[198:201], v181 offset:53856
	ds_read_b128 v[182:185], v174 offset:45056
	v_max3_f32 v224, v224, v39, v40
	v_max3_f32 v225, v225, v55, v56
	v_max3_f32 v224, v224, v41, v42
	v_max3_f32 v225, v225, v57, v58
	s_and_b64 vcc, exec, s[2:3]
	s_cbranch_vccz .Lmla_p15_nope
	v_add_u32_e32 v222, 0xb000, v176
	ds_write_b128 v222, v[160:163] offset:26752
	v_lshl_add_u32 v222, s19, 12, v179
	global_load_dwordx4 v[160:163], v222, s[62:63]
.Lmla_p15_nope:
	s_waitcnt lgkmcnt(5)
	v_mfma_f32_32x32x16_bf16 v[2:17], v[186:189], v[214:217], v[2:17]
	ds_read_b128 v[186:189], v174 offset:51712
	v_max3_f32 v224, v224, v43, v44
	v_max3_f32 v225, v225, v59, v60
	v_max3_f32 v224, v224, v45, v46
	v_max3_f32 v225, v225, v61, v62
	ds_write_b128 v173, v[202:205] offset:35840
	v_lshl_add_u32 v222, s13, 7, v168
	global_load_dwordx4 v[202:205], v222, s[56:57]
	s_waitcnt lgkmcnt(6)
	v_mfma_f32_32x32x16_bf16 v[18:33], v[190:193], v[214:217], v[18:33]
	ds_read_b128 v[190:193], v174 offset:45088
	v_max3_f32 v224, v224, v47, v48
	v_max3_f32 v225, v225, v63, v64
	v_max3_f32 v224, v224, v49, v65
	v_max_f32_e32 v224, v224, v225
	s_waitcnt lgkmcnt(6)
	v_mfma_f32_32x32x16_bf16 v[2:17], v[194:197], v[218:221], v[2:17]
	ds_read_b128 v[194:197], v174 offset:51744
	v_mov_b32_e32 v225, v224
	v_add_f32_e32 v1, v1, v164
	s_add_i32 s11, s11, 1
	v_permlane32_swap_b32_e32 v224, v225
	s_cmp_eq_u32 s9, s11
	v_max_f32_e32 v167, v224, v225
	v_cmp_lt_f32_e32 vcc, s66, v167
	s_waitcnt lgkmcnt(5)
	v_mfma_f32_32x32x16_bf16 v[18:33], v[198:201], v[218:221], v[18:33]
	s_waitcnt lgkmcnt(2)
	s_barrier
	s_cbranch_scc1 .Lmla_exit_p15

; template <int VAR>
; __device__ __forceinline__ void attn_phase(LAS unsigned char* lds, const AttnP P, int vcu, int G, int wave_s) {
;     ...
;                 if (ND0 == 6) {
;                     KR1(0); KR1(1); KR1(2); KR1(3); SB();
;                     QK1(0, negm); EX2(pc0, 0, w0.x); KR1(4); SB();
;                     QK1(1, negm); EX2(pc0, 2, w0.y); KR1(5); SB();
;                     QK1(2, pn0); EX2(pc0, 4, w0.z); KR1(6); SB();
;                     QK1(3, pn1); EX2(pc0, 6, w0.w); KR1(7); SB();
;                     QK1(4, pn0); EX2(pc0, 8, w1.x); KR1(8); SB();
;                     QK1(5, pn1); EX2(pc0, 10, w1.y); KR1(9); SB();
;                     QK1(6, pn0); EX2(pc0, 12, w1.z); KR1(10); SB();
;                     QK1(7, pn1); EX2(pc0, 14, w1.w); KR1(11); SB();
;                     QK1(8, pn0); EX2(pc1, 0, w2.x); VR1(0); SB();
;                     QK1(9, pn1); EX2(pc1, 2, w2.y); VR1(1); SB();
;                     QK1(10, pn0); EX2(pc1, 4, w2.z); VR1(2); SB();
;                     QK1(11, pn1); EX2(pc1, 6, w2.w); VR1(3); SB();
;                 } else {
;                     KR1(0); KR1(1); KR1(2); KR1(3); SB();
;                     QK1(0, negm); EX2(pc0, 0, w0.x); EX2(pc0, 2, w0.y); KR1(4); SB();
;                     QK1(1, negm); EX2(pc0, 4, w0.z); EX2(pc0, 6, w0.w); KR1(5); SB();
;                     QK1(2, pn0); EX2(pc0, 8, w1.x); EX2(pc0, 10, w1.y); KR1(6); SB();
;                     QK1(3, pn1); EX2(pc0, 12, w1.z); EX2(pc0, 14, w1.w); KR1(7); SB();
;                     QK1(4, pn0); EX2(pc1, 0, w2.x); VR1(0); SB();
;                     QK1(5, pn1); EX2(pc1, 2, w2.y); VR1(1); SB();
;                     QK1(6, pn0); EX2(pc1, 4, w2.z); VR1(2); SB();
;                     QK1(7, pn1); EX2(pc1, 6, w2.w); VR1(3); SB();
;                 }
;                 PV1(0, w0); EX2(pc1, 8, w3.x); VR1(4); SB();
;                 PV1(1, w0); EX2(pc1, 10, w3.y); VR1(5); SB();
;                 PV1(2, w1); EX2(pc1, 12, w3.z); VR1(6); SB();
;                 PV1(3, w1); EX2(pc1, 14, w3.w); VR1(7); SB();
;                 lrun += sacc;
;                 PV1(4, w2); MASK_TILE(pn0, pn1, t + 1); SB();
;                 PV1(5, w2); SB();
;                 PV1(6, w3); SB();
;                 PV1(7, w3); rmn = rowmax32(pn0, pn1); if (!USE_NEGM) rmn -= mref; SB();
;     ...
;             if (hn) { STOREK(t & 1); STOREV((t + 1) & 1); }
;             __syncthreads();
.Lmla_p16_go:
	v_exp_f32_e32 v222, v34
	v_exp_f32_e32 v223, v35
	v_add_f32_e32 v164, 0, v222
	v_cvt_pk_bf16_f32 v206, v222, v223
	v_add_f32_e32 v164, v223, v164
	v_exp_f32_e32 v224, v36
	v_exp_f32_e32 v225, v37
	v_add_f32_e32 v164, v224, v164
	v_cvt_pk_bf16_f32 v207, v224, v225
	v_add_f32_e32 v164, v225, v164
	s_waitcnt lgkmcnt(3)
	v_mfma_f32_32x32x16_bf16 v[82:97], v[182:185], v[114:117], v[66:81]
	ds_read_b128 v[198:201], v174 offset:45120
	v_exp_f32_e32 v222, v38
	v_exp_f32_e32 v223, v39
	v_add_f32_e32 v164, v222, v164
	v_cvt_pk_bf16_f32 v208, v222, v223
	v_add_f32_e32 v164, v223, v164
	s_waitcnt lgkmcnt(3)
	v_mfma_f32_32x32x16_bf16 v[98:113], v[186:189], v[114:117], v[66:81]
	ds_read_b128 v[182:185], v174 offset:51776
	v_exp_f32_e32 v224, v40
	v_exp_f32_e32 v225, v41
	v_add_f32_e32 v164, v224, v164
	v_cvt_pk_bf16_f32 v209, v224, v225
	v_add_f32_e32 v164, v225, v164
	s_waitcnt lgkmcnt(3)
	v_mfma_f32_32x32x16_bf16 v[82:97], v[190:193], v[118:121], v[82:97]
	ds_read_b128 v[186:189], v174 offset:45152
	v_exp_f32_e32 v222, v42
	v_exp_f32_e32 v223, v43
	v_add_f32_e32 v164, v222, v164
	v_cvt_pk_bf16_f32 v210, v222, v223
	v_add_f32_e32 v164, v223, v164
	s_waitcnt lgkmcnt(3)
	v_mfma_f32_32x32x16_bf16 v[98:113], v[194:197], v[118:121], v[98:113]
	ds_read_b128 v[190:193], v174 offset:51808
	v_exp_f32_e32 v224, v44
	v_exp_f32_e32 v225, v45
	v_add_f32_e32 v164, v224, v164
	v_cvt_pk_bf16_f32 v211, v224, v225
	v_add_f32_e32 v164, v225, v164
	s_waitcnt lgkmcnt(3)
	v_mfma_f32_32x32x16_bf16 v[82:97], v[198:201], v[122:125], v[82:97]
	ds_read_b128 v[194:197], v174 offset:45184
	v_exp_f32_e32 v222, v46
	v_exp_f32_e32 v223, v47
	v_add_f32_e32 v164, v222, v164
	v_cvt_pk_bf16_f32 v212, v222, v223
	v_add_f32_e32 v164, v223, v164
	s_waitcnt lgkmcnt(3)
	v_mfma_f32_32x32x16_bf16 v[98:113], v[182:185], v[122:125], v[98:113]
	ds_read_b128 v[198:201], v174 offset:51840
	v_exp_f32_e32 v224, v48
	v_exp_f32_e32 v225, v49
	v_add_f32_e32 v164, v224, v164
	v_cvt_pk_bf16_f32 v213, v224, v225
	v_add_f32_e32 v164, v225, v164
	s_waitcnt lgkmcnt(3)
	v_mfma_f32_32x32x16_bf16 v[82:97], v[186:189], v[126:129], v[82:97]
	ds_read_b128 v[182:185], v174 offset:45216
	v_exp_f32_e32 v222, v50
	v_exp_f32_e32 v223, v51
	v_add_f32_e32 v164, v222, v164
	v_cvt_pk_bf16_f32 v214, v222, v223
	v_add_f32_e32 v164, v223, v164
	s_waitcnt lgkmcnt(3)
	v_mfma_f32_32x32x16_bf16 v[98:113], v[190:193], v[126:129], v[98:113]
	ds_read_b128 v[186:189], v174 offset:51872
	v_exp_f32_e32 v224, v52
	v_exp_f32_e32 v225, v53
	v_add_f32_e32 v164, v224, v164
	v_cvt_pk_bf16_f32 v215, v224, v225
	v_add_f32_e32 v164, v225, v164
	s_waitcnt lgkmcnt(3)
	v_mfma_f32_32x32x16_bf16 v[82:97], v[194:197], v[130:133], v[82:97]
	ds_read_b128 v[190:193], v228 offset:13312
	v_exp_f32_e32 v222, v54
	v_exp_f32_e32 v223, v55
	v_add_f32_e32 v164, v222, v164
	v_cvt_pk_bf16_f32 v216, v222, v223
	v_add_f32_e32 v164, v223, v164
	s_waitcnt lgkmcnt(3)
	v_mfma_f32_32x32x16_bf16 v[98:113], v[198:201], v[130:133], v[98:113]
	ds_read_b128 v[194:197], v228 offset:17920
	v_exp_f32_e32 v224, v56
	v_exp_f32_e32 v225, v57
	v_add_f32_e32 v164, v224, v164
	v_cvt_pk_bf16_f32 v217, v224, v225
	v_add_f32_e32 v164, v225, v164
	s_waitcnt lgkmcnt(3)
	v_mfma_f32_32x32x16_bf16 v[82:97], v[182:185], v[134:137], v[82:97]
	ds_read_b128 v[198:201], v228 offset:13344
	v_exp_f32_e32 v222, v58
	v_exp_f32_e32 v223, v59
	v_add_f32_e32 v164, v222, v164
	v_cvt_pk_bf16_f32 v218, v222, v223
	v_add_f32_e32 v164, v223, v164
	s_waitcnt lgkmcnt(3)
	v_mfma_f32_32x32x16_bf16 v[98:113], v[186:189], v[134:137], v[98:113]
	ds_read_b128 v[182:185], v228 offset:17952
	v_exp_f32_e32 v224, v60
	v_exp_f32_e32 v225, v61
	v_add_f32_e32 v164, v224, v164
	v_cvt_pk_bf16_f32 v219, v224, v225
	v_add_f32_e32 v164, v225, v164
	s_waitcnt lgkmcnt(3)
	v_mfma_f32_32x32x16_bf16 v[2:17], v[190:193], v[206:209], v[2:17]
	ds_read_b128 v[186:189], v228 offset:13376
	v_exp_f32_e32 v222, v62
	v_exp_f32_e32 v223, v63
	v_add_f32_e32 v164, v222, v164
	v_cvt_pk_bf16_f32 v220, v222, v223
	v_add_f32_e32 v164, v223, v164
	s_waitcnt lgkmcnt(3)
	v_mfma_f32_32x32x16_bf16 v[18:33], v[194:197], v[206:209], v[18:33]
	ds_read_b128 v[190:193], v228 offset:17984
	v_exp_f32_e32 v224, v64
	v_exp_f32_e32 v225, v65
	v_add_f32_e32 v164, v224, v164
	v_cvt_pk_bf16_f32 v221, v224, v225
	v_add_f32_e32 v164, v225, v164
	s_mov_b32 s13, s20
	s_mov_b32 s20, s19
	s_add_i32 s19, s19, 1
	s_cmp_eq_u32 s19, s9
	s_cselect_b32 s19, 0, s19
	s_waitcnt lgkmcnt(3)
	v_mfma_f32_32x32x16_bf16 v[2:17], v[198:201], v[210:213], v[2:17]
	ds_read_b128 v[194:197], v228 offset:13408
	v_max3_f32 v224, v82, v83, v84
	v_max3_f32 v225, v98, v99, v100
	v_max3_f32 v224, v224, v85, v86
	v_max3_f32 v225, v225, v101, v102
	s_waitcnt vmcnt(2)
	ds_write_b128 v172, v[146:149]
	v_lshl_add_u32 v222, s19, 17, v178
	global_load_dwordx4 v[146:149], v222, s[52:53]
	s_waitcnt lgkmcnt(4)
	v_mfma_f32_32x32x16_bf16 v[18:33], v[182:185], v[210:213], v[18:33]
	ds_read_b128 v[198:201], v228 offset:18016
	ds_read_b128 v[182:185], v229 offset:13312
	v_max3_f32 v224, v224, v87, v88
	v_max3_f32 v225, v225, v103, v104
	v_max3_f32 v224, v224, v89, v90
	v_max3_f32 v225, v225, v105, v106
	s_and_b64 vcc, exec, s[2:3]
	s_cbranch_vccz .Lmla_p16_nope
	ds_write_b128 v176, v[138:141] offset:128
	v_lshl_add_u32 v222, s19, 12, v179
	global_load_dwordx4 v[138:141], v222, s[62:63]
.Lmla_p16_nope:
	s_waitcnt lgkmcnt(5)
	v_mfma_f32_32x32x16_bf16 v[2:17], v[186:189], v[214:217], v[2:17]
	ds_read_b128 v[186:189], v229 offset:19968
	v_max3_f32 v224, v224, v91, v92
	v_max3_f32 v225, v225, v107, v108
	v_max3_f32 v224, v224, v93, v94
	v_max3_f32 v225, v225, v109, v110
	v_add_u32_e32 v222, 0xb000, v173
	ds_write_b128 v222, v[142:145] offset:39936
	v_lshl_add_u32 v222, s13, 7, v168
	global_load_dwordx4 v[142:145], v222, s[56:57]
	s_waitcnt lgkmcnt(6)
	v_mfma_f32_32x32x16_bf16 v[18:33], v[190:193], v[214:217], v[18:33]
	ds_read_b128 v[190:193], v229 offset:13344
	v_max3_f32 v224, v224, v95, v96
	v_max3_f32 v225, v225, v111, v112
	v_max3_f32 v224, v224, v97, v113
	v_max_f32_e32 v224, v224, v225
	s_waitcnt lgkmcnt(6)
	v_mfma_f32_32x32x16_bf16 v[2:17], v[194:197], v[218:221], v[2:17]
	ds_read_b128 v[194:197], v229 offset:20000
	v_mov_b32_e32 v225, v224
	v_add_f32_e32 v1, v1, v164
	s_add_i32 s11, s11, 1
	v_permlane32_swap_b32_e32 v224, v225
	s_cmp_eq_u32 s9, s11
	v_max_f32_e32 v167, v224, v225
	v_cmp_lt_f32_e32 vcc, s66, v167
	s_waitcnt lgkmcnt(5)
	v_mfma_f32_32x32x16_bf16 v[18:33], v[198:201], v[218:221], v[18:33]
	s_cbranch_scc1 .Lmla_exit_p16

; template <int VAR>
; __device__ __forceinline__ void attn_phase(LAS unsigned char* lds, const AttnP P, int vcu, int G, int wave_s) {
;     ...
;                 if (ND0 == 6) {
;                     KR1(0); KR1(1); KR1(2); KR1(3); SB();
;                     QK1(0, negm); EX2(pc0, 0, w0.x); KR1(4); SB();
;                     QK1(1, negm); EX2(pc0, 2, w0.y); KR1(5); SB();
;                     QK1(2, pn0); EX2(pc0, 4, w0.z); KR1(6); SB();
;                     QK1(3, pn1); EX2(pc0, 6, w0.w); KR1(7); SB();
;                     QK1(4, pn0); EX2(pc0, 8, w1.x); KR1(8); SB();
;                     QK1(5, pn1); EX2(pc0, 10, w1.y); KR1(9); SB();
;                     QK1(6, pn0); EX2(pc0, 12, w1.z); KR1(10); SB();
;                     QK1(7, pn1); EX2(pc0, 14, w1.w); KR1(11); SB();
;                     QK1(8, pn0); EX2(pc1, 0, w2.x); VR1(0); SB();
;                     QK1(9, pn1); EX2(pc1, 2, w2.y); VR1(1); SB();
;                     QK1(10, pn0); EX2(pc1, 4, w2.z); VR1(2); SB();
;                     QK1(11, pn1); EX2(pc1, 6, w2.w); VR1(3); SB();
;                 } else {
;                     KR1(0); KR1(1); KR1(2); KR1(3); SB();
;                     QK1(0, negm); EX2(pc0, 0, w0.x); EX2(pc0, 2, w0.y); KR1(4); SB();
;                     QK1(1, negm); EX2(pc0, 4, w0.z); EX2(pc0, 6, w0.w); KR1(5); SB();
;                     QK1(2, pn0); EX2(pc0, 8, w1.x); EX2(pc0, 10, w1.y); KR1(6); SB();
;                     QK1(3, pn1); EX2(pc0, 12, w1.z); EX2(pc0, 14, w1.w); KR1(7); SB();
;                     QK1(4, pn0); EX2(pc1, 0, w2.x); VR1(0); SB();
;                     QK1(5, pn1); EX2(pc1, 2, w2.y); VR1(1); SB();
;                     QK1(6, pn0); EX2(pc1, 4, w2.z); VR1(2); SB();
;                     QK1(7, pn1); EX2(pc1, 6, w2.w); VR1(3); SB();
;                 }
;                 PV1(0, w0); EX2(pc1, 8, w3.x); VR1(4); SB();
;                 PV1(1, w0); EX2(pc1, 10, w3.y); VR1(5); SB();
;                 PV1(2, w1); EX2(pc1, 12, w3.z); VR1(6); SB();
;                 PV1(3, w1); EX2(pc1, 14, w3.w); VR1(7); SB();
;                 lrun += sacc;
;                 PV1(4, w2); MASK_TILE(pn0, pn1, t + 1); SB();
;                 PV1(5, w2); SB();
;                 PV1(6, w3); SB();
;                 PV1(7, w3); rmn = rowmax32(pn0, pn1); if (!USE_NEGM) rmn -= mref; SB();
;     ...
;             if (hn) { STOREK(t & 1); STOREV((t + 1) & 1); }
;             __syncthreads();
.Lmla_p17_go:
	v_exp_f32_e32 v222, v82
	v_exp_f32_e32 v223, v83
	v_add_f32_e32 v164, 0, v222
	v_cvt_pk_bf16_f32 v206, v222, v223
	v_add_f32_e32 v164, v223, v164
	v_exp_f32_e32 v224, v84
	v_exp_f32_e32 v225, v85
	v_add_f32_e32 v164, v224, v164
	v_cvt_pk_bf16_f32 v207, v224, v225
	v_add_f32_e32 v164, v225, v164
	s_waitcnt lgkmcnt(4)
	v_mfma_f32_32x32x16_bf16 v[34:49], v[182:185], v[114:117], v[66:81]
	ds_read_b128 v[198:201], v229 offset:13376
	v_exp_f32_e32 v222, v86
	v_exp_f32_e32 v223, v87
	v_add_f32_e32 v164, v222, v164
	v_cvt_pk_bf16_f32 v208, v222, v223
	v_add_f32_e32 v164, v223, v164
	s_waitcnt lgkmcnt(4)
	v_mfma_f32_32x32x16_bf16 v[50:65], v[186:189], v[114:117], v[66:81]
	ds_read_b128 v[182:185], v229 offset:20032
	v_exp_f32_e32 v224, v88
	v_exp_f32_e32 v225, v89
	v_add_f32_e32 v164, v224, v164
	v_cvt_pk_bf16_f32 v209, v224, v225
	v_add_f32_e32 v164, v225, v164
	s_waitcnt lgkmcnt(3)
	v_mfma_f32_32x32x16_bf16 v[34:49], v[190:193], v[118:121], v[34:49]
	ds_read_b128 v[186:189], v229 offset:13408
	v_exp_f32_e32 v222, v90
	v_exp_f32_e32 v223, v91
	v_add_f32_e32 v164, v222, v164
	v_cvt_pk_bf16_f32 v210, v222, v223
	v_add_f32_e32 v164, v223, v164
	s_waitcnt lgkmcnt(3)
	v_mfma_f32_32x32x16_bf16 v[50:65], v[194:197], v[118:121], v[50:65]
	ds_read_b128 v[190:193], v229 offset:20064
	v_exp_f32_e32 v224, v92
	v_exp_f32_e32 v225, v93
	v_add_f32_e32 v164, v224, v164
	v_cvt_pk_bf16_f32 v211, v224, v225
	v_add_f32_e32 v164, v225, v164
	s_waitcnt lgkmcnt(3)
	v_mfma_f32_32x32x16_bf16 v[34:49], v[198:201], v[122:125], v[34:49]
	ds_read_b128 v[194:197], v229 offset:13440
	v_exp_f32_e32 v222, v94
	v_exp_f32_e32 v223, v95
	v_add_f32_e32 v164, v222, v164
	v_cvt_pk_bf16_f32 v212, v222, v223
	v_add_f32_e32 v164, v223, v164
	s_waitcnt lgkmcnt(3)
	v_mfma_f32_32x32x16_bf16 v[50:65], v[182:185], v[122:125], v[50:65]
	ds_read_b128 v[198:201], v229 offset:20096
	v_exp_f32_e32 v224, v96
	v_exp_f32_e32 v225, v97
	v_add_f32_e32 v164, v224, v164
	v_cvt_pk_bf16_f32 v213, v224, v225
	v_add_f32_e32 v164, v225, v164
	s_waitcnt lgkmcnt(3)
	v_mfma_f32_32x32x16_bf16 v[34:49], v[186:189], v[126:129], v[34:49]
	ds_read_b128 v[182:185], v229 offset:13472
	v_exp_f32_e32 v222, v98
	v_exp_f32_e32 v223, v99
	v_add_f32_e32 v164, v222, v164
	v_cvt_pk_bf16_f32 v214, v222, v223
	v_add_f32_e32 v164, v223, v164
	s_waitcnt lgkmcnt(3)
	v_mfma_f32_32x32x16_bf16 v[50:65], v[190:193], v[126:129], v[50:65]
	ds_read_b128 v[186:189], v229 offset:20128
	v_exp_f32_e32 v224, v100
	v_exp_f32_e32 v225, v101
	v_add_f32_e32 v164, v224, v164
	v_cvt_pk_bf16_f32 v215, v224, v225
	v_add_f32_e32 v164, v225, v164
	s_waitcnt lgkmcnt(3)
	v_mfma_f32_32x32x16_bf16 v[34:49], v[194:197], v[130:133], v[34:49]
	ds_read_b128 v[190:193], v228 offset:35840
	v_exp_f32_e32 v222, v102
	v_exp_f32_e32 v223, v103
	v_add_f32_e32 v164, v222, v164
	v_cvt_pk_bf16_f32 v216, v222, v223
	v_add_f32_e32 v164, v223, v164
	s_waitcnt lgkmcnt(3)
	v_mfma_f32_32x32x16_bf16 v[50:65], v[198:201], v[130:133], v[50:65]
	ds_read_b128 v[194:197], v228 offset:40448
	v_exp_f32_e32 v224, v104
	v_exp_f32_e32 v225, v105
	v_add_f32_e32 v164, v224, v164
	v_cvt_pk_bf16_f32 v217, v224, v225
	v_add_f32_e32 v164, v225, v164
	s_waitcnt lgkmcnt(3)
	v_mfma_f32_32x32x16_bf16 v[34:49], v[182:185], v[134:137], v[34:49]
	ds_read_b128 v[198:201], v228 offset:35872
	v_exp_f32_e32 v222, v106
	v_exp_f32_e32 v223, v107
	v_add_f32_e32 v164, v222, v164
	v_cvt_pk_bf16_f32 v218, v222, v223
	v_add_f32_e32 v164, v223, v164
	s_waitcnt lgkmcnt(3)
	v_mfma_f32_32x32x16_bf16 v[50:65], v[186:189], v[134:137], v[50:65]
	ds_read_b128 v[182:185], v228 offset:40480
	v_exp_f32_e32 v224, v108
	v_exp_f32_e32 v225, v109
	v_add_f32_e32 v164, v224, v164
	v_cvt_pk_bf16_f32 v219, v224, v225
	v_add_f32_e32 v164, v225, v164
	s_waitcnt lgkmcnt(3)
	v_mfma_f32_32x32x16_bf16 v[2:17], v[190:193], v[206:209], v[2:17]
	ds_read_b128 v[186:189], v228 offset:35904
	v_exp_f32_e32 v222, v110
	v_exp_f32_e32 v223, v111
	v_add_f32_e32 v164, v222, v164
	v_cvt_pk_bf16_f32 v220, v222, v223
	v_add_f32_e32 v164, v223, v164
	s_waitcnt lgkmcnt(3)
	v_mfma_f32_32x32x16_bf16 v[18:33], v[194:197], v[206:209], v[18:33]
	ds_read_b128 v[190:193], v228 offset:40512
	v_exp_f32_e32 v224, v112
	v_exp_f32_e32 v225, v113
	v_add_f32_e32 v164, v224, v164
	v_cvt_pk_bf16_f32 v221, v224, v225
	v_add_f32_e32 v164, v225, v164
	s_mov_b32 s13, s20
	s_mov_b32 s20, s19
	s_add_i32 s19, s19, 1
	s_cmp_eq_u32 s19, s9
	s_cselect_b32 s19, 0, s19
	s_waitcnt lgkmcnt(3)
	v_mfma_f32_32x32x16_bf16 v[2:17], v[198:201], v[210:213], v[2:17]
	ds_read_b128 v[194:197], v228 offset:35936
	v_max3_f32 v224, v34, v35, v36
	v_max3_f32 v225, v50, v51, v52
	v_max3_f32 v224, v224, v37, v38
	v_max3_f32 v225, v225, v53, v54
	s_waitcnt vmcnt(2)
	ds_write_b128 v172, v[150:153] offset:22528
	v_lshl_add_u32 v222, s19, 17, v178
	global_load_dwordx4 v[150:153], v222, s[52:53]
	s_waitcnt lgkmcnt(4)
	v_mfma_f32_32x32x16_bf16 v[18:33], v[182:185], v[210:213], v[18:33]
	ds_read_b128 v[198:201], v228 offset:40544
	ds_read_b128 v[182:185], v229 offset:26624
	v_max3_f32 v224, v224, v39, v40
	v_max3_f32 v225, v225, v55, v56
	v_max3_f32 v224, v224, v41, v42
	v_max3_f32 v225, v225, v57, v58
	s_and_b64 vcc, exec, s[2:3]
	s_cbranch_vccz .Lmla_p17_nope
	ds_write_b128 v176, v[160:163] offset:22656
	v_lshl_add_u32 v222, s19, 12, v179
	global_load_dwordx4 v[160:163], v222, s[62:63]
.Lmla_p17_nope:
	s_waitcnt lgkmcnt(5)
	v_mfma_f32_32x32x16_bf16 v[2:17], v[186:189], v[214:217], v[2:17]
	ds_read_b128 v[186:189], v229 offset:33280
	v_max3_f32 v224, v224, v43, v44
	v_max3_f32 v225, v225, v59, v60
	v_max3_f32 v224, v224, v45, v46
	v_max3_f32 v225, v225, v61, v62
	v_add_u32_e32 v222, 0xb000, v173
	ds_write_b128 v222, v[202:205] offset:49152
	v_lshl_add_u32 v222, s13, 7, v168
	global_load_dwordx4 v[202:205], v222, s[56:57]
	s_waitcnt lgkmcnt(6)
	v_mfma_f32_32x32x16_bf16 v[18:33], v[190:193], v[214:217], v[18:33]
	ds_read_b128 v[190:193], v229 offset:26656
	v_max3_f32 v224, v224, v47, v48
	v_max3_f32 v225, v225, v63, v64
	v_max3_f32 v224, v224, v49, v65
	v_max_f32_e32 v224, v224, v225
	s_waitcnt lgkmcnt(6)
	v_mfma_f32_32x32x16_bf16 v[2:17], v[194:197], v[218:221], v[2:17]
	ds_read_b128 v[194:197], v229 offset:33312
	v_mov_b32_e32 v225, v224
	v_add_f32_e32 v1, v1, v164
	s_add_i32 s11, s11, 1
	v_permlane32_swap_b32_e32 v224, v225
	s_cmp_eq_u32 s9, s11
	v_max_f32_e32 v167, v224, v225
	v_cmp_lt_f32_e32 vcc, s66, v167
	s_waitcnt lgkmcnt(5)
	v_mfma_f32_32x32x16_bf16 v[18:33], v[198:201], v[218:221], v[18:33]
	s_waitcnt lgkmcnt(2)
	s_barrier
	s_cbranch_scc1 .Lmla_exit_p17

; template <int VAR>
; __device__ __forceinline__ void attn_phase(LAS unsigned char* lds, const AttnP P, int vcu, int G, int wave_s) {
;     ...
;                 if (ND0 == 6) {
;                     KR1(0); KR1(1); KR1(2); KR1(3); SB();
;                     QK1(0, negm); EX2(pc0, 0, w0.x); KR1(4); SB();
;                     QK1(1, negm); EX2(pc0, 2, w0.y); KR1(5); SB();
;                     QK1(2, pn0); EX2(pc0, 4, w0.z); KR1(6); SB();
;                     QK1(3, pn1); EX2(pc0, 6, w0.w); KR1(7); SB();
;                     QK1(4, pn0); EX2(pc0, 8, w1.x); KR1(8); SB();
;                     QK1(5, pn1); EX2(pc0, 10, w1.y); KR1(9); SB();
;                     QK1(6, pn0); EX2(pc0, 12, w1.z); KR1(10); SB();
;                     QK1(7, pn1); EX2(pc0, 14, w1.w); KR1(11); SB();
;                     QK1(8, pn0); EX2(pc1, 0, w2.x); VR1(0); SB();
;                     QK1(9, pn1); EX2(pc1, 2, w2.y); VR1(1); SB();
;                     QK1(10, pn0); EX2(pc1, 4, w2.z); VR1(2); SB();
;                     QK1(11, pn1); EX2(pc1, 6, w2.w); VR1(3); SB();
;                 } else {
;                     KR1(0); KR1(1); KR1(2); KR1(3); SB();
;                     QK1(0, negm); EX2(pc0, 0, w0.x); EX2(pc0, 2, w0.y); KR1(4); SB();
;                     QK1(1, negm); EX2(pc0, 4, w0.z); EX2(pc0, 6, w0.w); KR1(5); SB();
;                     QK1(2, pn0); EX2(pc0, 8, w1.x); EX2(pc0, 10, w1.y); KR1(6); SB();
;                     QK1(3, pn1); EX2(pc0, 12, w1.z); EX2(pc0, 14, w1.w); KR1(7); SB();
;                     QK1(4, pn0); EX2(pc1, 0, w2.x); VR1(0); SB();
;                     QK1(5, pn1); EX2(pc1, 2, w2.y); VR1(1); SB();
;                     QK1(6, pn0); EX2(pc1, 4, w2.z); VR1(2); SB();
;                     QK1(7, pn1); EX2(pc1, 6, w2.w); VR1(3); SB();
;                 }
;                 PV1(0, w0); EX2(pc1, 8, w3.x); VR1(4); SB();
;                 PV1(1, w0); EX2(pc1, 10, w3.y); VR1(5); SB();
;                 PV1(2, w1); EX2(pc1, 12, w3.z); VR1(6); SB();
;                 PV1(3, w1); EX2(pc1, 14, w3.w); VR1(7); SB();
;                 lrun += sacc;
;                 PV1(4, w2); MASK_TILE(pn0, pn1, t + 1); SB();
;                 PV1(5, w2); SB();
;                 PV1(6, w3); SB();
;                 PV1(7, w3); rmn = rowmax32(pn0, pn1); if (!USE_NEGM) rmn -= mref; SB();
;     ...
;             if (hn) { STOREK(t & 1); STOREV((t + 1) & 1); }
;             __syncthreads();
.Lmla_p18_go:
	v_exp_f32_e32 v222, v34
	v_exp_f32_e32 v223, v35
	v_add_f32_e32 v164, 0, v222
	v_cvt_pk_bf16_f32 v206, v222, v223
	v_add_f32_e32 v164, v223, v164
	v_exp_f32_e32 v224, v36
	v_exp_f32_e32 v225, v37
	v_add_f32_e32 v164, v224, v164
	v_cvt_pk_bf16_f32 v207, v224, v225
	v_add_f32_e32 v164, v225, v164
	s_waitcnt lgkmcnt(3)
	v_mfma_f32_32x32x16_bf16 v[82:97], v[182:185], v[114:117], v[66:81]
	ds_read_b128 v[198:201], v229 offset:26688
	v_exp_f32_e32 v222, v38
	v_exp_f32_e32 v223, v39
	v_add_f32_e32 v164, v222, v164
	v_cvt_pk_bf16_f32 v208, v222, v223
	v_add_f32_e32 v164, v223, v164
	s_waitcnt lgkmcnt(3)
	v_mfma_f32_32x32x16_bf16 v[98:113], v[186:189], v[114:117], v[66:81]
	ds_read_b128 v[182:185], v229 offset:33344
	v_exp_f32_e32 v224, v40
	v_exp_f32_e32 v225, v41
	v_add_f32_e32 v164, v224, v164
	v_cvt_pk_bf16_f32 v209, v224, v225
	v_add_f32_e32 v164, v225, v164
	s_waitcnt lgkmcnt(3)
	v_mfma_f32_32x32x16_bf16 v[82:97], v[190:193], v[118:121], v[82:97]
	ds_read_b128 v[186:189], v229 offset:26720
	v_exp_f32_e32 v222, v42
	v_exp_f32_e32 v223, v43
	v_add_f32_e32 v164, v222, v164
	v_cvt_pk_bf16_f32 v210, v222, v223
	v_add_f32_e32 v164, v223, v164
	s_waitcnt lgkmcnt(3)
	v_mfma_f32_32x32x16_bf16 v[98:113], v[194:197], v[118:121], v[98:113]
	ds_read_b128 v[190:193], v229 offset:33376
	v_exp_f32_e32 v224, v44
	v_exp_f32_e32 v225, v45
	v_add_f32_e32 v164, v224, v164
	v_cvt_pk_bf16_f32 v211, v224, v225
	v_add_f32_e32 v164, v225, v164
	s_waitcnt lgkmcnt(3)
	v_mfma_f32_32x32x16_bf16 v[82:97], v[198:201], v[122:125], v[82:97]
	ds_read_b128 v[194:197], v229 offset:26752
	v_exp_f32_e32 v222, v46
	v_exp_f32_e32 v223, v47
	v_add_f32_e32 v164, v222, v164
	v_cvt_pk_bf16_f32 v212, v222, v223
	v_add_f32_e32 v164, v223, v164
	s_waitcnt lgkmcnt(3)
	v_mfma_f32_32x32x16_bf16 v[98:113], v[182:185], v[122:125], v[98:113]
	ds_read_b128 v[198:201], v229 offset:33408
	v_exp_f32_e32 v224, v48
	v_exp_f32_e32 v225, v49
	v_add_f32_e32 v164, v224, v164
	v_cvt_pk_bf16_f32 v213, v224, v225
	v_add_f32_e32 v164, v225, v164
	s_waitcnt lgkmcnt(3)
	v_mfma_f32_32x32x16_bf16 v[82:97], v[186:189], v[126:129], v[82:97]
	ds_read_b128 v[182:185], v229 offset:26784
	v_exp_f32_e32 v222, v50
	v_exp_f32_e32 v223, v51
	v_add_f32_e32 v164, v222, v164
	v_cvt_pk_bf16_f32 v214, v222, v223
	v_add_f32_e32 v164, v223, v164
	s_waitcnt lgkmcnt(3)
	v_mfma_f32_32x32x16_bf16 v[98:113], v[190:193], v[126:129], v[98:113]
	ds_read_b128 v[186:189], v229 offset:33440
	v_exp_f32_e32 v224, v52
	v_exp_f32_e32 v225, v53
	v_add_f32_e32 v164, v224, v164
	v_cvt_pk_bf16_f32 v215, v224, v225
	v_add_f32_e32 v164, v225, v164
	s_waitcnt lgkmcnt(3)
	v_mfma_f32_32x32x16_bf16 v[82:97], v[194:197], v[130:133], v[82:97]
	ds_read_b128 v[190:193], v181 offset:39936
	v_exp_f32_e32 v222, v54
	v_exp_f32_e32 v223, v55
	v_add_f32_e32 v164, v222, v164
	v_cvt_pk_bf16_f32 v216, v222, v223
	v_add_f32_e32 v164, v223, v164
	s_waitcnt lgkmcnt(3)
	v_mfma_f32_32x32x16_bf16 v[98:113], v[198:201], v[130:133], v[98:113]
	ds_read_b128 v[194:197], v181 offset:44544
	v_exp_f32_e32 v224, v56
	v_exp_f32_e32 v225, v57
	v_add_f32_e32 v164, v224, v164
	v_cvt_pk_bf16_f32 v217, v224, v225
	v_add_f32_e32 v164, v225, v164
	s_waitcnt lgkmcnt(3)
	v_mfma_f32_32x32x16_bf16 v[82:97], v[182:185], v[134:137], v[82:97]
	ds_read_b128 v[198:201], v181 offset:39968
	v_exp_f32_e32 v222, v58
	v_exp_f32_e32 v223, v59
	v_add_f32_e32 v164, v222, v164
	v_cvt_pk_bf16_f32 v218, v222, v223
	v_add_f32_e32 v164, v223, v164
	s_waitcnt lgkmcnt(3)
	v_mfma_f32_32x32x16_bf16 v[98:113], v[186:189], v[134:137], v[98:113]
	ds_read_b128 v[182:185], v181 offset:44576
	v_exp_f32_e32 v224, v60
	v_exp_f32_e32 v225, v61
	v_add_f32_e32 v164, v224, v164
	v_cvt_pk_bf16_f32 v219, v224, v225
	v_add_f32_e32 v164, v225, v164
	s_waitcnt lgkmcnt(3)
	v_mfma_f32_32x32x16_bf16 v[2:17], v[190:193], v[206:209], v[2:17]
	ds_read_b128 v[186:189], v181 offset:40000
	v_exp_f32_e32 v222, v62
	v_exp_f32_e32 v223, v63
	v_add_f32_e32 v164, v222, v164
	v_cvt_pk_bf16_f32 v220, v222, v223
	v_add_f32_e32 v164, v223, v164
	s_waitcnt lgkmcnt(3)
	v_mfma_f32_32x32x16_bf16 v[18:33], v[194:197], v[206:209], v[18:33]
	ds_read_b128 v[190:193], v181 offset:44608
	v_exp_f32_e32 v224, v64
	v_exp_f32_e32 v225, v65
	v_add_f32_e32 v164, v224, v164
	v_cvt_pk_bf16_f32 v221, v224, v225
	v_add_f32_e32 v164, v225, v164
	s_mov_b32 s13, s20
	s_mov_b32 s20, s19
	s_add_i32 s19, s19, 1
	s_cmp_eq_u32 s19, s9
	s_cselect_b32 s19, 0, s19
	s_waitcnt lgkmcnt(3)
	v_mfma_f32_32x32x16_bf16 v[2:17], v[198:201], v[210:213], v[2:17]
	ds_read_b128 v[194:197], v181 offset:40032
	v_max3_f32 v224, v82, v83, v84
	v_max3_f32 v225, v98, v99, v100
	v_max3_f32 v224, v224, v85, v86
	v_max3_f32 v225, v225, v101, v102
	s_waitcnt vmcnt(2)
	ds_write_b128 v172, v[146:149] offset:45056
	v_lshl_add_u32 v222, s19, 17, v178
	global_load_dwordx4 v[146:149], v222, s[52:53]
	s_waitcnt lgkmcnt(4)
	v_mfma_f32_32x32x16_bf16 v[18:33], v[182:185], v[210:213], v[18:33]
	ds_read_b128 v[198:201], v181 offset:44640
	ds_read_b128 v[182:185], v174
	v_max3_f32 v224, v224, v87, v88
	v_max3_f32 v225, v225, v103, v104
	v_max3_f32 v224, v224, v89, v90
	v_max3_f32 v225, v225, v105, v106
	s_and_b64 vcc, exec, s[2:3]
	s_cbranch_vccz .Lmla_p18_nope
	ds_write_b128 v176, v[138:141] offset:45184
	v_lshl_add_u32 v222, s19, 12, v179
	global_load_dwordx4 v[138:141], v222, s[62:63]
.Lmla_p18_nope:
	s_waitcnt lgkmcnt(5)
	v_mfma_f32_32x32x16_bf16 v[2:17], v[186:189], v[214:217], v[2:17]
	ds_read_b128 v[186:189], v174 offset:6656
	v_max3_f32 v224, v224, v91, v92
	v_max3_f32 v225, v225, v107, v108
	v_max3_f32 v224, v224, v93, v94
	v_max3_f32 v225, v225, v109, v110
	ds_write_b128 v173, v[142:145] offset:13312
	v_lshl_add_u32 v222, s13, 7, v168
	global_load_dwordx4 v[142:145], v222, s[56:57]
	s_waitcnt lgkmcnt(6)
	v_mfma_f32_32x32x16_bf16 v[18:33], v[190:193], v[214:217], v[18:33]
	ds_read_b128 v[190:193], v174 offset:32
	v_max3_f32 v224, v224, v95, v96
	v_max3_f32 v225, v225, v111, v112
	v_max3_f32 v224, v224, v97, v113
	v_max_f32_e32 v224, v224, v225
	s_waitcnt lgkmcnt(6)
	v_mfma_f32_32x32x16_bf16 v[2:17], v[194:197], v[218:221], v[2:17]
	ds_read_b128 v[194:197], v174 offset:6688
	v_mov_b32_e32 v225, v224
	v_add_f32_e32 v1, v1, v164
	s_add_i32 s11, s11, 1
	v_permlane32_swap_b32_e32 v224, v225
	s_cmp_eq_u32 s9, s11
	v_max_f32_e32 v167, v224, v225
	v_cmp_lt_f32_e32 vcc, s66, v167
	s_waitcnt lgkmcnt(5)
	v_mfma_f32_32x32x16_bf16 v[18:33], v[198:201], v[218:221], v[18:33]
	s_cbranch_scc1 .Lmla_exit_p18

; template <int VAR>
; __device__ __forceinline__ void attn_phase(LAS unsigned char* lds, const AttnP P, int vcu, int G, int wave_s) {
;     ...
;                 if (ND0 == 6) {
;                     KR1(0); KR1(1); KR1(2); KR1(3); SB();
;                     QK1(0, negm); EX2(pc0, 0, w0.x); KR1(4); SB();
;                     QK1(1, negm); EX2(pc0, 2, w0.y); KR1(5); SB();
;                     QK1(2, pn0); EX2(pc0, 4, w0.z); KR1(6); SB();
;                     QK1(3, pn1); EX2(pc0, 6, w0.w); KR1(7); SB();
;                     QK1(4, pn0); EX2(pc0, 8, w1.x); KR1(8); SB();
;                     QK1(5, pn1); EX2(pc0, 10, w1.y); KR1(9); SB();
;                     QK1(6, pn0); EX2(pc0, 12, w1.z); KR1(10); SB();
;                     QK1(7, pn1); EX2(pc0, 14, w1.w); KR1(11); SB();
;                     QK1(8, pn0); EX2(pc1, 0, w2.x); VR1(0); SB();
;                     QK1(9, pn1); EX2(pc1, 2, w2.y); VR1(1); SB();
;                     QK1(10, pn0); EX2(pc1, 4, w2.z); VR1(2); SB();
;                     QK1(11, pn1); EX2(pc1, 6, w2.w); VR1(3); SB();
;                 } else {
;                     KR1(0); KR1(1); KR1(2); KR1(3); SB();
;                     QK1(0, negm); EX2(pc0, 0, w0.x); EX2(pc0, 2, w0.y); KR1(4); SB();
;                     QK1(1, negm); EX2(pc0, 4, w0.z); EX2(pc0, 6, w0.w); KR1(5); SB();
;                     QK1(2, pn0); EX2(pc0, 8, w1.x); EX2(pc0, 10, w1.y); KR1(6); SB();
;                     QK1(3, pn1); EX2(pc0, 12, w1.z); EX2(pc0, 14, w1.w); KR1(7); SB();
;                     QK1(4, pn0); EX2(pc1, 0, w2.x); VR1(0); SB();
;                     QK1(5, pn1); EX2(pc1, 2, w2.y); VR1(1); SB();
;                     QK1(6, pn0); EX2(pc1, 4, w2.z); VR1(2); SB();
;                     QK1(7, pn1); EX2(pc1, 6, w2.w); VR1(3); SB();
;                 }
;                 PV1(0, w0); EX2(pc1, 8, w3.x); VR1(4); SB();
;                 PV1(1, w0); EX2(pc1, 10, w3.y); VR1(5); SB();
;                 PV1(2, w1); EX2(pc1, 12, w3.z); VR1(6); SB();
;                 PV1(3, w1); EX2(pc1, 14, w3.w); VR1(7); SB();
;                 lrun += sacc;
;                 PV1(4, w2); MASK_TILE(pn0, pn1, t + 1); SB();
;                 PV1(5, w2); SB();
;                 PV1(6, w3); SB();
;                 PV1(7, w3); rmn = rowmax32(pn0, pn1); if (!USE_NEGM) rmn -= mref; SB();
;     ...
;             if (hn) { STOREK(t & 1); STOREV((t + 1) & 1); }
;             __syncthreads();
.Lmla_p19_go:
	v_exp_f32_e32 v222, v82
	v_exp_f32_e32 v223, v83
	v_add_f32_e32 v164, 0, v222
	v_cvt_pk_bf16_f32 v206, v222, v223
	v_add_f32_e32 v164, v223, v164
	v_exp_f32_e32 v224, v84
	v_exp_f32_e32 v225, v85
	v_add_f32_e32 v164, v224, v164
	v_cvt_pk_bf16_f32 v207, v224, v225
	v_add_f32_e32 v164, v225, v164
	s_waitcnt lgkmcnt(4)
	v_mfma_f32_32x32x16_bf16 v[34:49], v[182:185], v[114:117], v[66:81]
	ds_read_b128 v[198:201], v174 offset:64
	v_exp_f32_e32 v222, v86
	v_exp_f32_e32 v223, v87
	v_add_f32_e32 v164, v222, v164
	v_cvt_pk_bf16_f32 v208, v222, v223
	v_add_f32_e32 v164, v223, v164
	s_waitcnt lgkmcnt(4)
	v_mfma_f32_32x32x16_bf16 v[50:65], v[186:189], v[114:117], v[66:81]
	ds_read_b128 v[182:185], v174 offset:6720
	v_exp_f32_e32 v224, v88
	v_exp_f32_e32 v225, v89
	v_add_f32_e32 v164, v224, v164
	v_cvt_pk_bf16_f32 v209, v224, v225
	v_add_f32_e32 v164, v225, v164
	s_waitcnt lgkmcnt(3)
	v_mfma_f32_32x32x16_bf16 v[34:49], v[190:193], v[118:121], v[34:49]
	ds_read_b128 v[186:189], v174 offset:96
	v_exp_f32_e32 v222, v90
	v_exp_f32_e32 v223, v91
	v_add_f32_e32 v164, v222, v164
	v_cvt_pk_bf16_f32 v210, v222, v223
	v_add_f32_e32 v164, v223, v164
	s_waitcnt lgkmcnt(3)
	v_mfma_f32_32x32x16_bf16 v[50:65], v[194:197], v[118:121], v[50:65]
	ds_read_b128 v[190:193], v174 offset:6752
	v_exp_f32_e32 v224, v92
	v_exp_f32_e32 v225, v93
	v_add_f32_e32 v164, v224, v164
	v_cvt_pk_bf16_f32 v211, v224, v225
	v_add_f32_e32 v164, v225, v164
	s_waitcnt lgkmcnt(3)
	v_mfma_f32_32x32x16_bf16 v[34:49], v[198:201], v[122:125], v[34:49]
	ds_read_b128 v[194:197], v174 offset:128
	v_exp_f32_e32 v222, v94
	v_exp_f32_e32 v223, v95
	v_add_f32_e32 v164, v222, v164
	v_cvt_pk_bf16_f32 v212, v222, v223
	v_add_f32_e32 v164, v223, v164
	s_waitcnt lgkmcnt(3)
	v_mfma_f32_32x32x16_bf16 v[50:65], v[182:185], v[122:125], v[50:65]
	ds_read_b128 v[198:201], v174 offset:6784
	v_exp_f32_e32 v224, v96
	v_exp_f32_e32 v225, v97
	v_add_f32_e32 v164, v224, v164
	v_cvt_pk_bf16_f32 v213, v224, v225
	v_add_f32_e32 v164, v225, v164
	s_waitcnt lgkmcnt(3)
	v_mfma_f32_32x32x16_bf16 v[34:49], v[186:189], v[126:129], v[34:49]
	ds_read_b128 v[182:185], v174 offset:160
	v_exp_f32_e32 v222, v98
	v_exp_f32_e32 v223, v99
	v_add_f32_e32 v164, v222, v164
	v_cvt_pk_bf16_f32 v214, v222, v223
	v_add_f32_e32 v164, v223, v164
	s_waitcnt lgkmcnt(3)
	v_mfma_f32_32x32x16_bf16 v[50:65], v[190:193], v[126:129], v[50:65]
	ds_read_b128 v[186:189], v174 offset:6816
	v_exp_f32_e32 v224, v100
	v_exp_f32_e32 v225, v101
	v_add_f32_e32 v164, v224, v164
	v_cvt_pk_bf16_f32 v215, v224, v225
	v_add_f32_e32 v164, v225, v164
	s_waitcnt lgkmcnt(3)
	v_mfma_f32_32x32x16_bf16 v[34:49], v[194:197], v[130:133], v[34:49]
	ds_read_b128 v[190:193], v181 offset:49152
	v_exp_f32_e32 v222, v102
	v_exp_f32_e32 v223, v103
	v_add_f32_e32 v164, v222, v164
	v_cvt_pk_bf16_f32 v216, v222, v223
	v_add_f32_e32 v164, v223, v164
	s_waitcnt lgkmcnt(3)
	v_mfma_f32_32x32x16_bf16 v[50:65], v[198:201], v[130:133], v[50:65]
	ds_read_b128 v[194:197], v181 offset:53760
	v_exp_f32_e32 v224, v104
	v_exp_f32_e32 v225, v105
	v_add_f32_e32 v164, v224, v164
	v_cvt_pk_bf16_f32 v217, v224, v225
	v_add_f32_e32 v164, v225, v164
	s_waitcnt lgkmcnt(3)
	v_mfma_f32_32x32x16_bf16 v[34:49], v[182:185], v[134:137], v[34:49]
	ds_read_b128 v[198:201], v181 offset:49184
	v_exp_f32_e32 v222, v106
	v_exp_f32_e32 v223, v107
	v_add_f32_e32 v164, v222, v164
	v_cvt_pk_bf16_f32 v218, v222, v223
	v_add_f32_e32 v164, v223, v164
	s_waitcnt lgkmcnt(3)
	v_mfma_f32_32x32x16_bf16 v[50:65], v[186:189], v[134:137], v[50:65]
	ds_read_b128 v[182:185], v181 offset:53792
	v_exp_f32_e32 v224, v108
	v_exp_f32_e32 v225, v109
	v_add_f32_e32 v164, v224, v164
	v_cvt_pk_bf16_f32 v219, v224, v225
	v_add_f32_e32 v164, v225, v164
	s_waitcnt lgkmcnt(3)
	v_mfma_f32_32x32x16_bf16 v[2:17], v[190:193], v[206:209], v[2:17]
	ds_read_b128 v[186:189], v181 offset:49216
	v_exp_f32_e32 v222, v110
	v_exp_f32_e32 v223, v111
	v_add_f32_e32 v164, v222, v164
	v_cvt_pk_bf16_f32 v220, v222, v223
	v_add_f32_e32 v164, v223, v164
	s_waitcnt lgkmcnt(3)
	v_mfma_f32_32x32x16_bf16 v[18:33], v[194:197], v[206:209], v[18:33]
	ds_read_b128 v[190:193], v181 offset:53824
	v_exp_f32_e32 v224, v112
	v_exp_f32_e32 v225, v113
	v_add_f32_e32 v164, v224, v164
	v_cvt_pk_bf16_f32 v221, v224, v225
	v_add_f32_e32 v164, v225, v164
	s_mov_b32 s13, s20
	s_mov_b32 s20, s19
	s_add_i32 s19, s19, 1
	s_cmp_eq_u32 s19, s9
	s_cselect_b32 s19, 0, s19
	s_waitcnt lgkmcnt(3)
	v_mfma_f32_32x32x16_bf16 v[2:17], v[198:201], v[210:213], v[2:17]
	ds_read_b128 v[194:197], v181 offset:49248
	v_max3_f32 v224, v34, v35, v36
	v_max3_f32 v225, v50, v51, v52
	v_max3_f32 v224, v224, v37, v38
	v_max3_f32 v225, v225, v53, v54
	s_waitcnt vmcnt(2)
	ds_write_b128 v172, v[150:153] offset:58368
	v_lshl_add_u32 v222, s19, 17, v178
	global_load_dwordx4 v[150:153], v222, s[52:53]
	s_waitcnt lgkmcnt(4)
	v_mfma_f32_32x32x16_bf16 v[18:33], v[182:185], v[210:213], v[18:33]
	ds_read_b128 v[198:201], v181 offset:53856
	ds_read_b128 v[182:185], v174 offset:22528
	v_max3_f32 v224, v224, v39, v40
	v_max3_f32 v225, v225, v55, v56
	v_max3_f32 v224, v224, v41, v42
	v_max3_f32 v225, v225, v57, v58
	s_and_b64 vcc, exec, s[2:3]
	s_cbranch_vccz .Lmla_p19_nope
	ds_write_b128 v176, v[160:163] offset:58496
	v_lshl_add_u32 v222, s19, 12, v179
	global_load_dwordx4 v[160:163], v222, s[62:63]
.Lmla_p19_nope:
	s_waitcnt lgkmcnt(5)
	v_mfma_f32_32x32x16_bf16 v[2:17], v[186:189], v[214:217], v[2:17]
	ds_read_b128 v[186:189], v174 offset:29184
	v_max3_f32 v224, v224, v43, v44
	v_max3_f32 v225, v225, v59, v60
	v_max3_f32 v224, v224, v45, v46
	v_max3_f32 v225, v225, v61, v62
	ds_write_b128 v173, v[202:205] offset:35840
	v_lshl_add_u32 v222, s13, 7, v168
	global_load_dwordx4 v[202:205], v222, s[56:57]
	s_waitcnt lgkmcnt(6)
	v_mfma_f32_32x32x16_bf16 v[18:33], v[190:193], v[214:217], v[18:33]
	ds_read_b128 v[190:193], v174 offset:22560
	v_max3_f32 v224, v224, v47, v48
	v_max3_f32 v225, v225, v63, v64
	v_max3_f32 v224, v224, v49, v65
	v_max_f32_e32 v224, v224, v225
	s_waitcnt lgkmcnt(6)
	v_mfma_f32_32x32x16_bf16 v[2:17], v[194:197], v[218:221], v[2:17]
	ds_read_b128 v[194:197], v174 offset:29216
	v_mov_b32_e32 v225, v224
	v_add_f32_e32 v1, v1, v164
	s_add_i32 s11, s11, 1
	v_permlane32_swap_b32_e32 v224, v225
	s_cmp_eq_u32 s9, s11
	v_max_f32_e32 v167, v224, v225
	v_cmp_lt_f32_e32 vcc, s66, v167
	s_waitcnt lgkmcnt(5)
	v_mfma_f32_32x32x16_bf16 v[18:33], v[198:201], v[218:221], v[18:33]
	s_waitcnt lgkmcnt(2)
	s_barrier
	s_cbranch_scc1 .Lmla_exit_p19
	s_branch .Lmla_p0
